# attention unit epilogue: the 8 gate loads issued together (were one exposed round trip per row group), on top of v34
# baseline (speedup 1.0000x reference)
; __device__ __forceinline__ int crow(int r, int hi) { return (r & 3) + 8 * (r >> 2) + 4 * hi; }
; __device__ __forceinline__ unsigned short f2bf(float f) { unsigned u = __float_as_uint(f); return (unsigned short)((u + 0x7fffu + ((u >> 16) & 1u)) >> 16); }
; __device__ __forceinline__ unsigned f2bf(float f) { return pk2(f, 0.f) & 0xffffu; }
; __device__ __forceinline__ void attn_unit(const bf16* __restrict__ P, unsigned short* __restrict__ Ob, int b, int h, int kvh, int qb, bool meta, int jt0, int ntl, float* part, unsigned* cnt, const float* __restrict__ qnw, const float2* __restrict__ rtab, char* lds) {
;     ...
;     if (hi == 0) li_l[r32] = l_reg; asm volatile("s_waitcnt lgkmcnt(0)" ::: "memory");
;     float rli[16];
; #pragma unroll
;     for (int r = 0; r < 16; ++r) rli[r] = __builtin_amdgcn_rcpf(li_l[crow(r, hi)]);
;     char* stg = lds + 2 * SHM_V + 2 * SHM_K + NW * 64 * 4 + wid * (32 * 272);
; #pragma unroll
;     for (int r = 0; r < 16; ++r) { const int orow = crow(r, hi);
; #pragma unroll
;       for (int d0 = 0; d0 < 4; ++d0) *(unsigned short*)(stg + orow * 272 + (d0 * 32 + r32) * 2) = f2bf(o[d0][r] * rli[r]); }
.LBB0_270:
	s_or_b64 exec, exec, s[0:1]
	s_waitcnt lgkmcnt(0)
	v_add_u32_e32 v72, v195, v180
	ds_read_b128 v[64:67], v72
	ds_read_b128 v[68:71], v72 offset:32
	s_movk_i32 s0, 0x2200
	v_lshlrev_b32_e32 v81, 1, v193
	v_mul_u32_u24_e32 v82, 0x440, v194
	s_waitcnt lgkmcnt(1)
	v_rcp_f32_e32 v73, v64
	v_rcp_f32_e32 v74, v65
	v_rcp_f32_e32 v75, v66
	v_rcp_f32_e32 v76, v67
	s_waitcnt lgkmcnt(0)
	v_rcp_f32_e32 v77, v68
	ds_read_b128 v[64:67], v72 offset:64
	v_rcp_f32_e32 v78, v69
	v_rcp_f32_e32 v79, v70
	v_rcp_f32_e32 v80, v71
	ds_read_b128 v[68:71], v72 offset:96
	v_mul_lo_u32 v72, v192, s0
	v_add_u32_e32 v72, s82, v72
	v_mul_f32_e32 v0, v0, v73
	v_add3_u32 v81, v72, v81, v82
	v_bfe_u32 v82, v0, 16, 1
	v_add3_u32 v0, v0, v82, s80
	ds_write_b16_d16_hi v81, v0
	v_mul_f32_e32 v0, v48, v73
	v_bfe_u32 v48, v0, 16, 1
	v_add3_u32 v0, v0, v48, s80
	ds_write_b16_d16_hi v81, v0 offset:64
	v_mul_f32_e32 v0, v32, v73
	v_bfe_u32 v32, v0, 16, 1
	v_add3_u32 v0, v0, v32, s80
	ds_write_b16_d16_hi v81, v0 offset:128
	v_mul_f32_e32 v0, v16, v73
	v_bfe_u32 v16, v0, 16, 1
	v_add3_u32 v0, v0, v16, s80
	ds_write_b16_d16_hi v81, v0 offset:192
	v_mul_f32_e32 v0, v1, v74
	v_bfe_u32 v1, v0, 16, 1
	v_add3_u32 v0, v0, v1, s80
	ds_write_b16_d16_hi v81, v0 offset:272
	v_mul_f32_e32 v0, v49, v74
	v_bfe_u32 v1, v0, 16, 1
	v_add3_u32 v0, v0, v1, s80
	ds_write_b16_d16_hi v81, v0 offset:336
	v_mul_f32_e32 v0, v33, v74
	v_bfe_u32 v1, v0, 16, 1
	v_add3_u32 v0, v0, v1, s80
	ds_write_b16_d16_hi v81, v0 offset:400
	v_mul_f32_e32 v0, v17, v74
	v_bfe_u32 v1, v0, 16, 1
	v_add3_u32 v0, v0, v1, s80
	ds_write_b16_d16_hi v81, v0 offset:464
	v_mul_f32_e32 v0, v2, v75
	v_bfe_u32 v1, v0, 16, 1
	v_add3_u32 v0, v0, v1, s80
	ds_write_b16_d16_hi v81, v0 offset:544
	v_mul_f32_e32 v0, v50, v75
	v_bfe_u32 v1, v0, 16, 1
	v_add3_u32 v0, v0, v1, s80
	ds_write_b16_d16_hi v81, v0 offset:608
	v_mul_f32_e32 v0, v34, v75
	v_bfe_u32 v1, v0, 16, 1
	v_add3_u32 v0, v0, v1, s80
	ds_write_b16_d16_hi v81, v0 offset:672
	v_mul_f32_e32 v0, v18, v75
	v_bfe_u32 v1, v0, 16, 1
	v_add3_u32 v0, v0, v1, s80
	ds_write_b16_d16_hi v81, v0 offset:736
	v_mul_f32_e32 v0, v3, v76
	v_bfe_u32 v1, v0, 16, 1
	v_add3_u32 v0, v0, v1, s80
	ds_write_b16_d16_hi v81, v0 offset:816
	v_mul_f32_e32 v0, v51, v76
	v_bfe_u32 v1, v0, 16, 1
	v_add3_u32 v0, v0, v1, s80
	ds_write_b16_d16_hi v81, v0 offset:880
	v_mul_f32_e32 v0, v35, v76
	v_bfe_u32 v1, v0, 16, 1
	v_add3_u32 v0, v0, v1, s80
	ds_write_b16_d16_hi v81, v0 offset:944
	v_mul_f32_e32 v0, v19, v76
	v_bfe_u32 v1, v0, 16, 1
	v_add3_u32 v0, v0, v1, s80
	ds_write_b16_d16_hi v81, v0 offset:1008
	v_mul_f32_e32 v0, v4, v77
	v_bfe_u32 v1, v0, 16, 1
	v_add3_u32 v0, v0, v1, s80
	ds_write_b16_d16_hi v81, v0 offset:2176
	v_mul_f32_e32 v0, v52, v77
	v_bfe_u32 v1, v0, 16, 1
	v_add3_u32 v0, v0, v1, s80
	ds_write_b16_d16_hi v81, v0 offset:2240
	v_mul_f32_e32 v0, v36, v77
	v_bfe_u32 v1, v0, 16, 1
	v_add3_u32 v0, v0, v1, s80
	ds_write_b16_d16_hi v81, v0 offset:2304
	v_mul_f32_e32 v0, v20, v77
	v_bfe_u32 v1, v0, 16, 1
	v_add3_u32 v0, v0, v1, s80
	ds_write_b16_d16_hi v81, v0 offset:2368
	v_mul_f32_e32 v0, v5, v78
	v_bfe_u32 v1, v0, 16, 1
	v_add3_u32 v0, v0, v1, s80
	ds_write_b16_d16_hi v81, v0 offset:2448
	v_mul_f32_e32 v0, v53, v78
	v_bfe_u32 v1, v0, 16, 1
	v_add3_u32 v0, v0, v1, s80
	ds_write_b16_d16_hi v81, v0 offset:2512
	v_mul_f32_e32 v0, v37, v78
	v_bfe_u32 v1, v0, 16, 1
	v_add3_u32 v0, v0, v1, s80
	ds_write_b16_d16_hi v81, v0 offset:2576
	v_mul_f32_e32 v0, v21, v78
	v_bfe_u32 v1, v0, 16, 1
	v_add3_u32 v0, v0, v1, s80
	ds_write_b16_d16_hi v81, v0 offset:2640
	v_mul_f32_e32 v0, v6, v79
	v_bfe_u32 v1, v0, 16, 1
	v_add3_u32 v0, v0, v1, s80
	ds_write_b16_d16_hi v81, v0 offset:2720
	v_mul_f32_e32 v0, v54, v79
	v_bfe_u32 v1, v0, 16, 1
	v_add3_u32 v0, v0, v1, s80
	ds_write_b16_d16_hi v81, v0 offset:2784
	v_mul_f32_e32 v0, v38, v79
	v_bfe_u32 v1, v0, 16, 1
	v_add3_u32 v0, v0, v1, s80
	ds_write_b16_d16_hi v81, v0 offset:2848
	v_mul_f32_e32 v0, v22, v79
	v_bfe_u32 v1, v0, 16, 1
	v_add3_u32 v0, v0, v1, s80
	ds_write_b16_d16_hi v81, v0 offset:2912
	v_mul_f32_e32 v0, v7, v80
	v_bfe_u32 v1, v0, 16, 1
	v_add3_u32 v0, v0, v1, s80
	ds_write_b16_d16_hi v81, v0 offset:2992
	v_mul_f32_e32 v0, v55, v80
	v_bfe_u32 v1, v0, 16, 1
	v_add3_u32 v0, v0, v1, s80
	ds_write_b16_d16_hi v81, v0 offset:3056
	v_mul_f32_e32 v0, v39, v80
	v_bfe_u32 v1, v0, 16, 1
	s_waitcnt lgkmcnt(14)
; __device__ __forceinline__ int crow(int r, int hi) { return (r & 3) + 8 * (r >> 2) + 4 * hi; }
; __device__ __forceinline__ unsigned short f2bf(float f) { unsigned u = __float_as_uint(f); return (unsigned short)((u + 0x7fffu + ((u >> 16) & 1u)) >> 16); }
; __device__ __forceinline__ unsigned f2bf(float f) { return pk2(f, 0.f) & 0xffffu; }
; __device__ __forceinline__ void attn_unit(const bf16* __restrict__ P, unsigned short* __restrict__ Ob, int b, int h, int kvh, int qb, bool meta, int jt0, int ntl, float* part, unsigned* cnt, const float* __restrict__ qnw, const float2* __restrict__ rtab, char* lds) {
;     ...
;     for (int r = 0; r < 16; ++r) { const int orow = crow(r, hi);
; #pragma unroll
;       for (int d0 = 0; d0 < 4; ++d0) *(unsigned short*)(stg + orow * 272 + (d0 * 32 + r32) * 2) = f2bf(o[d0][r] * rli[r]); }
;     asm volatile("s_waitcnt lgkmcnt(0)" ::: "memory");
;     const long grow0 = (long)b * 4096 + qb * 256 + wid * QBLK;
; #pragma unroll
;     for (int i = 0; i < 8; ++i) { const int cidx = lane + 64 * i, orow = cidx >> 4, c8 = (cidx & 15) * 8;
;       const u32x4 ov = *(const u32x4*)(stg + orow * 272 + c8 * 2);
;       const u32x4 gv = *(const u32x4*)(Pg + (grow0 + orow) * LD + 4096 + h * D + c8);
	v_rcp_f32_e32 v64, v64
	v_add3_u32 v0, v0, v1, s80
	ds_write_b16_d16_hi v81, v0 offset:3120
	v_mul_f32_e32 v0, v23, v80
	v_bfe_u32 v1, v0, 16, 1
	v_add3_u32 v0, v0, v1, s80
	ds_write_b16_d16_hi v81, v0 offset:3184
	v_mul_f32_e32 v0, v8, v64
	v_bfe_u32 v1, v0, 16, 1
	v_add3_u32 v0, v0, v1, s80
	ds_write_b16_d16_hi v81, v0 offset:4352
	v_mul_f32_e32 v0, v56, v64
	v_bfe_u32 v1, v0, 16, 1
	v_add3_u32 v0, v0, v1, s80
	ds_write_b16_d16_hi v81, v0 offset:4416
	v_mul_f32_e32 v0, v40, v64
	v_bfe_u32 v1, v0, 16, 1
	v_rcp_f32_e32 v65, v65
	v_add3_u32 v0, v0, v1, s80
	ds_write_b16_d16_hi v81, v0 offset:4480
	v_mul_f32_e32 v0, v24, v64
	v_bfe_u32 v1, v0, 16, 1
	v_add3_u32 v0, v0, v1, s80
	ds_write_b16_d16_hi v81, v0 offset:4544
	v_mul_f32_e32 v0, v9, v65
	v_bfe_u32 v1, v0, 16, 1
	v_add3_u32 v0, v0, v1, s80
	ds_write_b16_d16_hi v81, v0 offset:4624
	v_mul_f32_e32 v0, v57, v65
	v_bfe_u32 v1, v0, 16, 1
	v_add3_u32 v0, v0, v1, s80
	ds_write_b16_d16_hi v81, v0 offset:4688
	v_mul_f32_e32 v0, v41, v65
	v_bfe_u32 v1, v0, 16, 1
	v_rcp_f32_e32 v66, v66
	v_add3_u32 v0, v0, v1, s80
	ds_write_b16_d16_hi v81, v0 offset:4752
	v_mul_f32_e32 v0, v25, v65
	v_bfe_u32 v1, v0, 16, 1
	v_add3_u32 v0, v0, v1, s80
	ds_write_b16_d16_hi v81, v0 offset:4816
	v_mul_f32_e32 v0, v10, v66
	v_bfe_u32 v1, v0, 16, 1
	v_add3_u32 v0, v0, v1, s80
	ds_write_b16_d16_hi v81, v0 offset:4896
	v_mul_f32_e32 v0, v58, v66
	v_bfe_u32 v1, v0, 16, 1
	v_add3_u32 v0, v0, v1, s80
	ds_write_b16_d16_hi v81, v0 offset:4960
	v_mul_f32_e32 v0, v42, v66
	v_bfe_u32 v1, v0, 16, 1
	v_rcp_f32_e32 v67, v67
	v_add3_u32 v0, v0, v1, s80
	ds_write_b16_d16_hi v81, v0 offset:5024
	v_mul_f32_e32 v0, v26, v66
	v_bfe_u32 v1, v0, 16, 1
	v_add3_u32 v0, v0, v1, s80
	ds_write_b16_d16_hi v81, v0 offset:5088
	v_mul_f32_e32 v0, v11, v67
	v_bfe_u32 v1, v0, 16, 1
	v_add3_u32 v0, v0, v1, s80
	ds_write_b16_d16_hi v81, v0 offset:5168
	v_mul_f32_e32 v0, v59, v67
	v_bfe_u32 v1, v0, 16, 1
	v_add3_u32 v0, v0, v1, s80
	ds_write_b16_d16_hi v81, v0 offset:5232
	v_mul_f32_e32 v0, v43, v67
	v_bfe_u32 v1, v0, 16, 1
	v_rcp_f32_e32 v68, v68
	v_add3_u32 v0, v0, v1, s80
	ds_write_b16_d16_hi v81, v0 offset:5296
	v_mul_f32_e32 v0, v27, v67
	v_bfe_u32 v1, v0, 16, 1
	v_add3_u32 v0, v0, v1, s80
	ds_write_b16_d16_hi v81, v0 offset:5360
	v_mul_f32_e32 v0, v12, v68
	v_bfe_u32 v1, v0, 16, 1
	v_add3_u32 v0, v0, v1, s80
	ds_write_b16_d16_hi v81, v0 offset:6528
	v_mul_f32_e32 v0, v60, v68
	v_bfe_u32 v1, v0, 16, 1
	v_add3_u32 v0, v0, v1, s80
	ds_write_b16_d16_hi v81, v0 offset:6592
	v_mul_f32_e32 v0, v44, v68
	v_bfe_u32 v1, v0, 16, 1
	v_rcp_f32_e32 v69, v69
	v_add3_u32 v0, v0, v1, s80
	ds_write_b16_d16_hi v81, v0 offset:6656
	v_mul_f32_e32 v0, v28, v68
	v_bfe_u32 v1, v0, 16, 1
	v_add3_u32 v0, v0, v1, s80
	ds_write_b16_d16_hi v81, v0 offset:6720
	v_mul_f32_e32 v0, v13, v69
	v_bfe_u32 v1, v0, 16, 1
	v_add3_u32 v0, v0, v1, s80
	ds_write_b16_d16_hi v81, v0 offset:6800
	v_mul_f32_e32 v0, v61, v69
	v_bfe_u32 v1, v0, 16, 1
	v_add3_u32 v0, v0, v1, s80
	ds_write_b16_d16_hi v81, v0 offset:6864
	v_mul_f32_e32 v0, v45, v69
	v_bfe_u32 v1, v0, 16, 1
	v_rcp_f32_e32 v70, v70
	v_add3_u32 v0, v0, v1, s80
	ds_write_b16_d16_hi v81, v0 offset:6928
	v_mul_f32_e32 v0, v29, v69
	v_bfe_u32 v1, v0, 16, 1
	v_add3_u32 v0, v0, v1, s80
	ds_write_b16_d16_hi v81, v0 offset:6992
	v_mul_f32_e32 v0, v14, v70
	v_bfe_u32 v1, v0, 16, 1
	v_add3_u32 v0, v0, v1, s80
	ds_write_b16_d16_hi v81, v0 offset:7072
	v_mul_f32_e32 v0, v62, v70
	v_bfe_u32 v1, v0, 16, 1
	v_add3_u32 v0, v0, v1, s80
	ds_write_b16_d16_hi v81, v0 offset:7136
	v_mul_f32_e32 v0, v46, v70
	v_bfe_u32 v1, v0, 16, 1
	v_rcp_f32_e32 v71, v71
	v_add3_u32 v0, v0, v1, s80
	ds_write_b16_d16_hi v81, v0 offset:7200
	v_mul_f32_e32 v0, v30, v70
	v_bfe_u32 v1, v0, 16, 1
	v_add3_u32 v0, v0, v1, s80
	ds_write_b16_d16_hi v81, v0 offset:7264
	v_mul_f32_e32 v0, v15, v71
	v_bfe_u32 v1, v0, 16, 1
	v_add3_u32 v0, v0, v1, s80
	ds_write_b16_d16_hi v81, v0 offset:7344
	v_mul_f32_e32 v0, v63, v71
	v_bfe_u32 v1, v0, 16, 1
	v_add3_u32 v0, v0, v1, s80
	ds_write_b16_d16_hi v81, v0 offset:7408
	v_mul_f32_e32 v0, v47, v71
	v_bfe_u32 v1, v0, 16, 1
	v_add3_u32 v0, v0, v1, s80
	ds_write_b16_d16_hi v81, v0 offset:7472
	v_mul_f32_e32 v0, v31, v71
	v_bfe_u32 v1, v0, 16, 1
	v_add3_u32 v0, v0, v1, s80
	ds_write_b16_d16_hi v81, v0 offset:7536
	v_lshl_add_u64 v[0:1], s[34:35], 0, v[178:179]
	v_lshrrev_b32_e32 v8, 4, v181
	v_or_b32_e32 v0, v8, v0
	v_mov_b64_e32 v[2:3], s[6:7]
	v_mad_u64_u32 v[4:5], s[0:1], v0, s44, v[2:3]
	v_mul_lo_u32 v13, v1, s44
	s_lshl_b32 s8, s36, 1
	v_add_u32_e32 v5, v13, v5
	v_lshl_add_u64 v[4:5], v[4:5], 0, s[8:9]
	v_lshl_add_u64 v[4:5], v[4:5], 0, v[176:177]
	v_add_co_u32_e32 v4, vcc, s50, v4
	s_waitcnt lgkmcnt(0)
	v_mul_u32_u24_e32 v8, 0x110, v8
	s_nop 0
	v_addc_co_u32_e32 v5, vcc, 0, v5, vcc
	s_mov_b32 s99, 0
	s_mov_b32 s98, 0xc000
	v_lshl_add_u64 v[128:129], v[4:5], 0, s[98:99]
	global_load_dwordx4 v[100:103], v[128:129], off
	s_mov_b32 s98, 0x18000
	v_lshl_add_u64 v[128:129], v[4:5], 0, s[98:99]
	global_load_dwordx4 v[104:107], v[128:129], off
	s_mov_b32 s98, 0x24000
	v_lshl_add_u64 v[128:129], v[4:5], 0, s[98:99]
	global_load_dwordx4 v[108:111], v[128:129], off
	s_mov_b32 s98, 0x30000
	v_lshl_add_u64 v[128:129], v[4:5], 0, s[98:99]
	global_load_dwordx4 v[112:115], v[128:129], off
	s_mov_b32 s98, 0x3c000
	v_lshl_add_u64 v[128:129], v[4:5], 0, s[98:99]
	global_load_dwordx4 v[116:119], v[128:129], off
	s_mov_b32 s98, 0x48000
	v_lshl_add_u64 v[128:129], v[4:5], 0, s[98:99]
	global_load_dwordx4 v[120:123], v[128:129], off
	s_mov_b32 s98, 0x54000
	v_lshl_add_u64 v[128:129], v[4:5], 0, s[98:99]
	global_load_dwordx4 v[124:127], v[128:129], off
	global_load_dwordx4 v[4:7], v[4:5], off
	v_add3_u32 v12, v72, v176, v8
	s_waitcnt vmcnt(0)
; __device__ __forceinline__ void attn_unit(const bf16* __restrict__ P, unsigned short* __restrict__ Ob, int b, int h, int kvh, int qb, bool meta, int jt0, int ntl, float* part, unsigned* cnt, const float* __restrict__ qnw, const float2* __restrict__ rtab, char* lds) {
;     ...
;     for (int i = 0; i < 8; ++i) { const int cidx = lane + 64 * i, orow = cidx >> 4, c8 = (cidx & 15) * 8;
;       const u32x4 ov = *(const u32x4*)(stg + orow * 272 + c8 * 2);
;       const u32x4 gv = *(const u32x4*)(Pg + (grow0 + orow) * LD + 4096 + h * D + c8);
;       const unsigned ow[4] = {ov.x, ov.y, ov.z, ov.w}, gw[4] = {gv.x, gv.y, gv.z, gv.w}; unsigned res[4];
; #pragma unroll
;       for (int e = 0; e < 4; ++e) { const float o0 = __uint_as_float(ow[e] << 16), o1 = __uint_as_float(ow[e] & 0xffff0000u), g0 = __uint_as_float(gw[e] << 16), g1 = __uint_as_float(gw[e] & 0xffff0000u);
;         res[e] = cvtpk(o0 * (g0 / (1.f + __expf(-g0))), o1 * (g1 / (1.f + __expf(-g1)))); }
;       *(u32x4*)(Ob + (grow0 + orow) * 2048 + h * D + c8) = (u32x4){res[0], res[1], res[2], res[3]}; }
	v_lshlrev_b32_e32 v14, 16, v4
	v_mul_f32_e32 v9, 0xbfb8aa3b, v14
	v_exp_f32_e32 v15, v9
	v_and_b32_e32 v4, 0xffff0000, v4
	v_mul_f32_e32 v21, 0xbfb8aa3b, v4
	v_exp_f32_e32 v21, v21
	v_add_f32_e32 v15, 1.0, v15
	v_div_scale_f32 v16, s[0:1], v15, v15, v14
	v_rcp_f32_e32 v17, v16
	ds_read_b128 v[8:11], v12
	v_fma_f32 v19, -v16, v17, 1.0
	v_fmac_f32_e32 v17, v19, v17
	v_div_scale_f32 v19, vcc, v14, v15, v14
	v_mul_f32_e32 v20, v19, v17
	v_fma_f32 v22, -v16, v20, v19
	v_fmac_f32_e32 v20, v22, v17
	v_fma_f32 v16, -v16, v20, v19
	v_add_f32_e32 v19, 1.0, v21
	v_div_scale_f32 v21, s[0:1], v19, v19, v4
	v_rcp_f32_e32 v22, v21
	v_div_fmas_f32 v16, v16, v17, v20
	v_div_fixup_f32 v14, v16, v15, v14
	s_waitcnt lgkmcnt(0)
	v_lshlrev_b32_e32 v18, 16, v8
	v_fma_f32 v15, -v21, v22, 1.0
	v_fmac_f32_e32 v22, v15, v22
	v_div_scale_f32 v15, vcc, v4, v19, v4
	v_mul_f32_e32 v16, v15, v22
	v_fma_f32 v17, -v21, v16, v15
	v_fmac_f32_e32 v16, v17, v22
	v_fma_f32 v15, -v21, v16, v15
	v_div_fmas_f32 v15, v15, v22, v16
	v_lshlrev_b32_e32 v16, 16, v5
	v_mul_f32_e32 v17, 0xbfb8aa3b, v16
	v_exp_f32_e32 v17, v17
	v_and_b32_e32 v8, 0xffff0000, v8
	v_div_fixup_f32 v4, v15, v19, v4
	v_mul_f32_e32 v4, v4, v8
	v_mul_f32_e32 v14, v14, v18
	v_cvt_pk_bf16_f32 v8, v14, v4
	v_add_f32_e32 v4, 1.0, v17
	v_div_scale_f32 v14, s[0:1], v4, v4, v16
	v_rcp_f32_e32 v15, v14
	v_and_b32_e32 v5, 0xffff0000, v5
	v_mul_f32_e32 v20, 0xbfb8aa3b, v5
	v_exp_f32_e32 v20, v20
	v_fma_f32 v18, -v14, v15, 1.0
	v_fmac_f32_e32 v15, v18, v15
	v_div_scale_f32 v18, vcc, v16, v4, v16
	v_mul_f32_e32 v19, v18, v15
	v_fma_f32 v21, -v14, v19, v18
	v_fmac_f32_e32 v19, v21, v15
	v_fma_f32 v14, -v14, v19, v18
	v_add_f32_e32 v18, 1.0, v20
	v_div_scale_f32 v20, s[0:1], v18, v18, v5
	v_rcp_f32_e32 v21, v20
	v_div_fmas_f32 v14, v14, v15, v19
	v_div_fixup_f32 v4, v14, v4, v16
	v_lshlrev_b32_e32 v17, 16, v9
	v_fma_f32 v14, -v20, v21, 1.0
	v_fmac_f32_e32 v21, v14, v21
	v_div_scale_f32 v14, vcc, v5, v18, v5
	v_mul_f32_e32 v15, v14, v21
	v_fma_f32 v16, -v20, v15, v14
	v_fmac_f32_e32 v15, v16, v21
	v_fma_f32 v14, -v20, v15, v14
	v_div_fmas_f32 v14, v14, v21, v15
	v_lshlrev_b32_e32 v15, 16, v6
	v_mul_f32_e32 v16, 0xbfb8aa3b, v15
	v_exp_f32_e32 v16, v16
	v_and_b32_e32 v9, 0xffff0000, v9
	v_mul_f32_e32 v4, v4, v17
	v_div_fixup_f32 v5, v14, v18, v5
	v_mul_f32_e32 v5, v5, v9
	v_cvt_pk_bf16_f32 v9, v4, v5
	v_add_f32_e32 v4, 1.0, v16
	v_div_scale_f32 v5, s[0:1], v4, v4, v15
	v_rcp_f32_e32 v14, v5
	v_and_b32_e32 v6, 0xffff0000, v6
	v_mul_f32_e32 v19, 0xbfb8aa3b, v6
	v_exp_f32_e32 v19, v19
	v_fma_f32 v17, -v5, v14, 1.0
	v_fmac_f32_e32 v14, v17, v14
	v_div_scale_f32 v17, vcc, v15, v4, v15
	v_mul_f32_e32 v18, v17, v14
	v_fma_f32 v20, -v5, v18, v17
	v_fmac_f32_e32 v18, v20, v14
	v_fma_f32 v5, -v5, v18, v17
	v_add_f32_e32 v17, 1.0, v19
	v_div_scale_f32 v19, s[0:1], v17, v17, v6
	v_rcp_f32_e32 v20, v19
	v_div_fmas_f32 v5, v5, v14, v18
	v_div_fixup_f32 v4, v5, v4, v15
	v_lshlrev_b32_e32 v16, 16, v10
	v_fma_f32 v5, -v19, v20, 1.0
	v_fmac_f32_e32 v20, v5, v20
	v_div_scale_f32 v5, vcc, v6, v17, v6
	v_mul_f32_e32 v14, v5, v20
	v_fma_f32 v15, -v19, v14, v5
	v_fmac_f32_e32 v14, v15, v20
	v_fma_f32 v5, -v19, v14, v5
	v_div_fmas_f32 v5, v5, v20, v14
	v_lshlrev_b32_e32 v14, 16, v7
	v_mul_f32_e32 v15, 0xbfb8aa3b, v14
	v_exp_f32_e32 v15, v15
	v_and_b32_e32 v10, 0xffff0000, v10
	v_mul_f32_e32 v4, v4, v16
	v_div_fixup_f32 v5, v5, v17, v6
	v_mul_f32_e32 v5, v5, v10
	v_cvt_pk_bf16_f32 v10, v4, v5
	v_add_f32_e32 v4, 1.0, v15
	v_div_scale_f32 v5, s[0:1], v4, v4, v14
	v_rcp_f32_e32 v6, v5
	v_and_b32_e32 v7, 0xffff0000, v7
	v_mul_f32_e32 v18, 0xbfb8aa3b, v7
	v_exp_f32_e32 v18, v18
	v_fma_f32 v16, -v5, v6, 1.0
	v_fmac_f32_e32 v6, v16, v6
	v_div_scale_f32 v16, vcc, v14, v4, v14
	v_mul_f32_e32 v17, v16, v6
	v_fma_f32 v19, -v5, v17, v16
	v_fmac_f32_e32 v17, v19, v6
	v_fma_f32 v5, -v5, v17, v16
	v_add_f32_e32 v16, 1.0, v18
	v_div_scale_f32 v18, s[0:1], v16, v16, v7
	v_rcp_f32_e32 v19, v18
	v_div_fmas_f32 v5, v5, v6, v17
	v_div_fixup_f32 v4, v5, v4, v14
	v_lshlrev_b32_e32 v15, 16, v11
	v_fma_f32 v5, -v18, v19, 1.0
	v_fmac_f32_e32 v19, v5, v19
	v_div_scale_f32 v5, vcc, v7, v16, v7
	v_mul_f32_e32 v6, v5, v19
	v_fma_f32 v14, -v18, v6, v5
	v_fmac_f32_e32 v6, v14, v19
	v_fma_f32 v5, -v18, v6, v5
	v_div_fmas_f32 v5, v5, v19, v6
	v_and_b32_e32 v11, 0xffff0000, v11
	v_div_fixup_f32 v5, v5, v16, v7
	v_mul_f32_e32 v4, v4, v15
	v_mul_f32_e32 v5, v5, v11
	v_or_b32_e32 v6, 4, v0
	v_cvt_pk_bf16_f32 v11, v4, v5
	v_mad_u64_u32 v[4:5], s[0:1], v6, s44, v[2:3]
	v_add_u32_e32 v5, v13, v5
	v_lshl_add_u64 v[4:5], v[4:5], 0, s[8:9]
	v_lshl_add_u64 v[4:5], v[4:5], 0, v[176:177]
	v_add_co_u32_e32 v4, vcc, s50, v4
	s_add_u32 s0, s24, s8
	s_nop 0
	v_addc_co_u32_e32 v5, vcc, 0, v5, vcc
	s_nop 1
	v_mov_b64_e32 v[14:15], v[100:101]
	v_mov_b64_e32 v[16:17], v[102:103]
	s_addc_u32 s1, s25, 0
	v_lshl_add_u64 v[4:5], s[0:1], 0, v[176:177]
	v_lshlrev_b64 v[18:19], 12, v[0:1]
	v_lshl_add_u64 v[18:19], v[4:5], 0, v[18:19]
	global_store_dwordx4 v[18:19], v[8:11], off
	ds_read_b128 v[8:11], v12 offset:1088
	s_waitcnt lgkmcnt(0)
	v_lshlrev_b32_e32 v21, 16, v8
	v_and_b32_e32 v8, 0xffff0000, v8
	s_waitcnt vmcnt(1)
; __device__ __forceinline__ void attn_unit(const bf16* __restrict__ P, unsigned short* __restrict__ Ob, int b, int h, int kvh, int qb, bool meta, int jt0, int ntl, float* part, unsigned* cnt, const float* __restrict__ qnw, const float2* __restrict__ rtab, char* lds) {
;     ...
;     for (int i = 0; i < 8; ++i) { const int cidx = lane + 64 * i, orow = cidx >> 4, c8 = (cidx & 15) * 8;
;       const u32x4 ov = *(const u32x4*)(stg + orow * 272 + c8 * 2);
;       const u32x4 gv = *(const u32x4*)(Pg + (grow0 + orow) * LD + 4096 + h * D + c8);
;       const unsigned ow[4] = {ov.x, ov.y, ov.z, ov.w}, gw[4] = {gv.x, gv.y, gv.z, gv.w}; unsigned res[4];
; #pragma unroll
;       for (int e = 0; e < 4; ++e) { const float o0 = __uint_as_float(ow[e] << 16), o1 = __uint_as_float(ow[e] & 0xffff0000u), g0 = __uint_as_float(gw[e] << 16), g1 = __uint_as_float(gw[e] & 0xffff0000u);
;         res[e] = cvtpk(o0 * (g0 / (1.f + __expf(-g0))), o1 * (g1 / (1.f + __expf(-g1)))); }
;       *(u32x4*)(Ob + (grow0 + orow) * 2048 + h * D + c8) = (u32x4){res[0], res[1], res[2], res[3]}; }
	v_lshlrev_b32_e32 v7, 16, v14
	v_mul_f32_e32 v20, 0xbfb8aa3b, v7
	v_exp_f32_e32 v20, v20
	v_and_b32_e32 v14, 0xffff0000, v14
	v_mul_f32_e32 v24, 0xbfb8aa3b, v14
	v_exp_f32_e32 v24, v24
	v_add_f32_e32 v18, 1.0, v20
	v_div_scale_f32 v19, s[0:1], v18, v18, v7
	v_rcp_f32_e32 v20, v19
	s_nop 0
	v_fma_f32 v22, -v19, v20, 1.0
	v_fmac_f32_e32 v20, v22, v20
	v_div_scale_f32 v22, vcc, v7, v18, v7
	v_mul_f32_e32 v23, v22, v20
	v_fma_f32 v25, -v19, v23, v22
	v_fmac_f32_e32 v23, v25, v20
	v_fma_f32 v19, -v19, v23, v22
	v_add_f32_e32 v22, 1.0, v24
	v_div_scale_f32 v24, s[0:1], v22, v22, v14
	v_rcp_f32_e32 v25, v24
	v_div_fmas_f32 v19, v19, v20, v23
	v_div_fixup_f32 v7, v19, v18, v7
	v_mul_f32_e32 v7, v7, v21
	v_fma_f32 v18, -v24, v25, 1.0
	v_fmac_f32_e32 v25, v18, v25
	v_div_scale_f32 v18, vcc, v14, v22, v14
	v_mul_f32_e32 v19, v18, v25
	v_fma_f32 v20, -v24, v19, v18
	v_fmac_f32_e32 v19, v20, v25
	v_fma_f32 v18, -v24, v19, v18
	v_div_fmas_f32 v18, v18, v25, v19
	v_lshlrev_b32_e32 v19, 16, v15
	v_mul_f32_e32 v20, 0xbfb8aa3b, v19
	v_exp_f32_e32 v20, v20
	v_div_fixup_f32 v14, v18, v22, v14
	v_mul_f32_e32 v8, v14, v8
	v_cvt_pk_bf16_f32 v14, v7, v8
	v_add_f32_e32 v7, 1.0, v20
	v_div_scale_f32 v8, s[0:1], v7, v7, v19
	v_rcp_f32_e32 v18, v8
	v_and_b32_e32 v15, 0xffff0000, v15
	v_mul_f32_e32 v23, 0xbfb8aa3b, v15
	v_exp_f32_e32 v23, v23
	v_fma_f32 v21, -v8, v18, 1.0
	v_fmac_f32_e32 v18, v21, v18
	v_div_scale_f32 v21, vcc, v19, v7, v19
	v_mul_f32_e32 v22, v21, v18
	v_fma_f32 v24, -v8, v22, v21
	v_fmac_f32_e32 v22, v24, v18
	v_fma_f32 v8, -v8, v22, v21
	v_add_f32_e32 v21, 1.0, v23
	v_div_scale_f32 v23, s[0:1], v21, v21, v15
	v_rcp_f32_e32 v24, v23
	v_div_fmas_f32 v8, v8, v18, v22
	v_div_fixup_f32 v7, v8, v7, v19
	v_lshlrev_b32_e32 v20, 16, v9
	v_fma_f32 v8, -v23, v24, 1.0
	v_fmac_f32_e32 v24, v8, v24
	v_div_scale_f32 v8, vcc, v15, v21, v15
	v_mul_f32_e32 v18, v8, v24
	v_fma_f32 v19, -v23, v18, v8
	v_fmac_f32_e32 v18, v19, v24
	v_fma_f32 v8, -v23, v18, v8
	v_div_fmas_f32 v8, v8, v24, v18
	v_lshlrev_b32_e32 v18, 16, v16
	v_mul_f32_e32 v19, 0xbfb8aa3b, v18
	v_exp_f32_e32 v19, v19
	v_and_b32_e32 v9, 0xffff0000, v9
	v_mul_f32_e32 v7, v7, v20
	v_div_fixup_f32 v8, v8, v21, v15
	v_mul_f32_e32 v8, v8, v9
	v_cvt_pk_bf16_f32 v15, v7, v8
	v_add_f32_e32 v7, 1.0, v19
	v_div_scale_f32 v8, s[0:1], v7, v7, v18
	v_rcp_f32_e32 v9, v8
	v_and_b32_e32 v16, 0xffff0000, v16
	v_mul_f32_e32 v22, 0xbfb8aa3b, v16
	v_exp_f32_e32 v22, v22
	v_fma_f32 v20, -v8, v9, 1.0
	v_fmac_f32_e32 v9, v20, v9
	v_div_scale_f32 v20, vcc, v18, v7, v18
	v_mul_f32_e32 v21, v20, v9
	v_fma_f32 v23, -v8, v21, v20
	v_fmac_f32_e32 v21, v23, v9
	v_fma_f32 v8, -v8, v21, v20
	v_add_f32_e32 v20, 1.0, v22
	v_div_scale_f32 v22, s[0:1], v20, v20, v16
	v_rcp_f32_e32 v23, v22
	v_div_fmas_f32 v8, v8, v9, v21
	v_div_fixup_f32 v7, v8, v7, v18
	v_lshlrev_b32_e32 v19, 16, v10
	v_fma_f32 v8, -v22, v23, 1.0
	v_fmac_f32_e32 v23, v8, v23
	v_div_scale_f32 v8, vcc, v16, v20, v16
	v_mul_f32_e32 v9, v8, v23
	v_fma_f32 v18, -v22, v9, v8
	v_fmac_f32_e32 v9, v18, v23
	v_fma_f32 v8, -v22, v9, v8
	v_div_fmas_f32 v8, v8, v23, v9
	v_lshlrev_b32_e32 v9, 16, v17
	v_mul_f32_e32 v18, 0xbfb8aa3b, v9
	v_exp_f32_e32 v18, v18
	v_and_b32_e32 v10, 0xffff0000, v10
	v_mul_f32_e32 v7, v7, v19
	v_div_fixup_f32 v8, v8, v20, v16
	v_mul_f32_e32 v8, v8, v10
	v_cvt_pk_bf16_f32 v16, v7, v8
	v_add_f32_e32 v7, 1.0, v18
	v_div_scale_f32 v8, s[0:1], v7, v7, v9
	v_rcp_f32_e32 v10, v8
	v_and_b32_e32 v17, 0xffff0000, v17
	v_mul_f32_e32 v21, 0xbfb8aa3b, v17
	v_exp_f32_e32 v21, v21
	v_fma_f32 v19, -v8, v10, 1.0
	v_fmac_f32_e32 v10, v19, v10
	v_div_scale_f32 v19, vcc, v9, v7, v9
	v_mul_f32_e32 v20, v19, v10
	v_fma_f32 v22, -v8, v20, v19
	v_fmac_f32_e32 v20, v22, v10
	v_fma_f32 v8, -v8, v20, v19
	v_add_f32_e32 v19, 1.0, v21
	v_div_scale_f32 v21, s[0:1], v19, v19, v17
	v_rcp_f32_e32 v22, v21
	v_div_fmas_f32 v8, v8, v10, v20
	v_div_fixup_f32 v7, v8, v7, v9
	v_lshlrev_b32_e32 v18, 16, v11
	v_fma_f32 v8, -v21, v22, 1.0
	v_fmac_f32_e32 v22, v8, v22
	v_div_scale_f32 v8, vcc, v17, v19, v17
	v_mul_f32_e32 v9, v8, v22
	v_fma_f32 v10, -v21, v9, v8
	v_fmac_f32_e32 v9, v10, v22
	v_fma_f32 v8, -v21, v9, v8
	v_div_fmas_f32 v8, v8, v22, v9
	v_and_b32_e32 v11, 0xffff0000, v11
	v_div_fixup_f32 v8, v8, v19, v17
	v_mul_f32_e32 v8, v8, v11
	v_or_b32_e32 v10, 8, v0
	v_mul_f32_e32 v7, v7, v18
	v_cvt_pk_bf16_f32 v17, v7, v8
	v_mad_u64_u32 v[8:9], s[0:1], v10, s44, v[2:3]
	v_add_u32_e32 v9, v13, v9
	v_lshl_add_u64 v[8:9], v[8:9], 0, s[8:9]
	v_lshl_add_u64 v[8:9], v[8:9], 0, v[176:177]
	v_add_co_u32_e32 v8, vcc, s50, v8
	v_mov_b32_e32 v7, v1
	s_nop 0
	v_addc_co_u32_e32 v9, vcc, 0, v9, vcc
	s_nop 1
	v_mov_b64_e32 v[18:19], v[104:105]
	v_mov_b64_e32 v[20:21], v[106:107]
	v_lshlrev_b64 v[6:7], 12, v[6:7]
	v_lshl_add_u64 v[6:7], v[4:5], 0, v[6:7]
	global_store_dwordx4 v[6:7], v[14:17], off
	s_waitcnt vmcnt(1)
	v_lshlrev_b32_e32 v11, 16, v18
	v_mul_f32_e32 v8, 0xbfb8aa3b, v11
	v_exp_f32_e32 v22, v8
	v_and_b32_e32 v18, 0xffff0000, v18
	v_mul_f32_e32 v24, 0xbfb8aa3b, v18
	v_exp_f32_e32 v24, v24
	v_add_f32_e32 v14, 1.0, v22
	v_div_scale_f32 v15, s[0:1], v14, v14, v11
	v_rcp_f32_e32 v16, v15
	ds_read_b128 v[6:9], v12 offset:2176
	v_fma_f32 v22, -v15, v16, 1.0
	v_fmac_f32_e32 v16, v22, v16
	v_div_scale_f32 v22, vcc, v11, v14, v11
	v_mul_f32_e32 v23, v22, v16
	v_fma_f32 v25, -v15, v23, v22
	v_fmac_f32_e32 v23, v25, v16
	v_fma_f32 v15, -v15, v23, v22
	v_add_f32_e32 v22, 1.0, v24
	v_div_scale_f32 v24, s[0:1], v22, v22, v18
	v_rcp_f32_e32 v25, v24
	v_div_fmas_f32 v15, v15, v16, v23
	v_div_fixup_f32 v11, v15, v14, v11
	s_waitcnt lgkmcnt(0)
; __device__ __forceinline__ void attn_unit(const bf16* __restrict__ P, unsigned short* __restrict__ Ob, int b, int h, int kvh, int qb, bool meta, int jt0, int ntl, float* part, unsigned* cnt, const float* __restrict__ qnw, const float2* __restrict__ rtab, char* lds) {
;     ...
;     for (int i = 0; i < 8; ++i) { const int cidx = lane + 64 * i, orow = cidx >> 4, c8 = (cidx & 15) * 8;
;       const u32x4 ov = *(const u32x4*)(stg + orow * 272 + c8 * 2);
;       const u32x4 gv = *(const u32x4*)(Pg + (grow0 + orow) * LD + 4096 + h * D + c8);
;       const unsigned ow[4] = {ov.x, ov.y, ov.z, ov.w}, gw[4] = {gv.x, gv.y, gv.z, gv.w}; unsigned res[4];
; #pragma unroll
;       for (int e = 0; e < 4; ++e) { const float o0 = __uint_as_float(ow[e] << 16), o1 = __uint_as_float(ow[e] & 0xffff0000u), g0 = __uint_as_float(gw[e] << 16), g1 = __uint_as_float(gw[e] & 0xffff0000u);
;         res[e] = cvtpk(o0 * (g0 / (1.f + __expf(-g0))), o1 * (g1 / (1.f + __expf(-g1)))); }
;       *(u32x4*)(Ob + (grow0 + orow) * 2048 + h * D + c8) = (u32x4){res[0], res[1], res[2], res[3]}; }
	v_lshlrev_b32_e32 v17, 16, v6
	v_fma_f32 v14, -v24, v25, 1.0
	v_fmac_f32_e32 v25, v14, v25
	v_div_scale_f32 v14, vcc, v18, v22, v18
	v_mul_f32_e32 v15, v14, v25
	v_fma_f32 v16, -v24, v15, v14
	v_fmac_f32_e32 v15, v16, v25
	v_fma_f32 v14, -v24, v15, v14
	v_div_fmas_f32 v14, v14, v25, v15
	v_lshlrev_b32_e32 v15, 16, v19
	v_mul_f32_e32 v16, 0xbfb8aa3b, v15
	v_exp_f32_e32 v16, v16
	v_and_b32_e32 v6, 0xffff0000, v6
	v_div_fixup_f32 v14, v14, v22, v18
	v_mul_f32_e32 v6, v14, v6
	v_mul_f32_e32 v11, v11, v17
	v_cvt_pk_bf16_f32 v14, v11, v6
	v_add_f32_e32 v6, 1.0, v16
	v_div_scale_f32 v11, s[0:1], v6, v6, v15
	v_rcp_f32_e32 v16, v11
	v_and_b32_e32 v18, 0xffff0000, v19
	v_mul_f32_e32 v23, 0xbfb8aa3b, v18
	v_exp_f32_e32 v23, v23
	v_fma_f32 v19, -v11, v16, 1.0
	v_fmac_f32_e32 v16, v19, v16
	v_div_scale_f32 v19, vcc, v15, v6, v15
	v_mul_f32_e32 v22, v19, v16
	v_fma_f32 v24, -v11, v22, v19
	v_fmac_f32_e32 v22, v24, v16
	v_fma_f32 v11, -v11, v22, v19
	v_add_f32_e32 v19, 1.0, v23
	v_div_scale_f32 v23, s[0:1], v19, v19, v18
	v_rcp_f32_e32 v24, v23
	v_div_fmas_f32 v11, v11, v16, v22
	v_div_fixup_f32 v6, v11, v6, v15
	v_lshlrev_b32_e32 v17, 16, v7
	v_fma_f32 v11, -v23, v24, 1.0
	v_fmac_f32_e32 v24, v11, v24
	v_div_scale_f32 v11, vcc, v18, v19, v18
	v_mul_f32_e32 v15, v11, v24
	v_fma_f32 v16, -v23, v15, v11
	v_fmac_f32_e32 v15, v16, v24
	v_fma_f32 v11, -v23, v15, v11
	v_lshlrev_b32_e32 v16, 16, v20
	v_div_fmas_f32 v11, v11, v24, v15
	v_mul_f32_e32 v15, 0xbfb8aa3b, v16
	v_mul_f32_e32 v6, v6, v17
	v_exp_f32_e32 v17, v15
	v_and_b32_e32 v7, 0xffff0000, v7
	v_div_fixup_f32 v11, v11, v19, v18
	v_mul_f32_e32 v7, v11, v7
	v_cvt_pk_bf16_f32 v15, v6, v7
	v_add_f32_e32 v6, 1.0, v17
	v_div_scale_f32 v7, s[0:1], v6, v6, v16
	v_rcp_f32_e32 v11, v7
	v_and_b32_e32 v18, 0xffff0000, v20
	v_mul_f32_e32 v22, 0xbfb8aa3b, v18
	v_exp_f32_e32 v22, v22
	v_fma_f32 v19, -v7, v11, 1.0
	v_fmac_f32_e32 v11, v19, v11
	v_div_scale_f32 v19, vcc, v16, v6, v16
	v_mul_f32_e32 v20, v19, v11
	v_fma_f32 v23, -v7, v20, v19
	v_fmac_f32_e32 v20, v23, v11
	v_fma_f32 v7, -v7, v20, v19
	v_add_f32_e32 v19, 1.0, v22
	v_div_scale_f32 v22, s[0:1], v19, v19, v18
	v_rcp_f32_e32 v23, v22
	v_div_fmas_f32 v7, v7, v11, v20
	v_div_fixup_f32 v6, v7, v6, v16
	v_lshlrev_b32_e32 v17, 16, v8
	v_fma_f32 v7, -v22, v23, 1.0
	v_fmac_f32_e32 v23, v7, v23
	v_div_scale_f32 v7, vcc, v18, v19, v18
	v_mul_f32_e32 v11, v7, v23
	v_fma_f32 v16, -v22, v11, v7
	v_fmac_f32_e32 v11, v16, v23
	v_fma_f32 v7, -v22, v11, v7
	v_div_fmas_f32 v7, v7, v23, v11
	v_lshlrev_b32_e32 v11, 16, v21
	v_mul_f32_e32 v16, 0xbfb8aa3b, v11
	v_mul_f32_e32 v6, v6, v17
	v_exp_f32_e32 v17, v16
	v_and_b32_e32 v8, 0xffff0000, v8
	v_div_fixup_f32 v7, v7, v19, v18
	v_mul_f32_e32 v7, v7, v8
	v_cvt_pk_bf16_f32 v16, v6, v7
	v_add_f32_e32 v6, 1.0, v17
	v_div_scale_f32 v7, s[0:1], v6, v6, v11
	v_rcp_f32_e32 v8, v7
	v_and_b32_e32 v18, 0xffff0000, v21
	v_mul_f32_e32 v21, 0xbfb8aa3b, v18
	v_exp_f32_e32 v21, v21
	v_fma_f32 v19, -v7, v8, 1.0
	v_fmac_f32_e32 v8, v19, v8
	v_div_scale_f32 v19, vcc, v11, v6, v11
	v_mul_f32_e32 v20, v19, v8
	v_fma_f32 v22, -v7, v20, v19
	v_fmac_f32_e32 v20, v22, v8
	v_fma_f32 v7, -v7, v20, v19
	v_add_f32_e32 v19, 1.0, v21
	v_div_scale_f32 v21, s[0:1], v19, v19, v18
	v_rcp_f32_e32 v22, v21
	v_div_fmas_f32 v7, v7, v8, v20
	v_div_fixup_f32 v6, v7, v6, v11
	v_lshlrev_b32_e32 v17, 16, v9
	v_fma_f32 v7, -v21, v22, 1.0
	v_fmac_f32_e32 v22, v7, v22
	v_div_scale_f32 v7, vcc, v18, v19, v18
	v_mul_f32_e32 v8, v7, v22
	v_fma_f32 v11, -v21, v8, v7
	v_fmac_f32_e32 v8, v11, v22
	v_fma_f32 v7, -v21, v8, v7
	v_div_fmas_f32 v7, v7, v22, v8
	v_and_b32_e32 v9, 0xffff0000, v9
	v_div_fixup_f32 v7, v7, v19, v18
	v_mul_f32_e32 v6, v6, v17
	v_mul_f32_e32 v7, v7, v9
	v_or_b32_e32 v8, 12, v0
	v_cvt_pk_bf16_f32 v17, v6, v7
	v_mad_u64_u32 v[6:7], s[0:1], v8, s44, v[2:3]
	v_add_u32_e32 v7, v13, v7
	v_lshl_add_u64 v[6:7], v[6:7], 0, s[8:9]
	v_lshl_add_u64 v[6:7], v[6:7], 0, v[176:177]
	v_add_co_u32_e32 v6, vcc, s50, v6
	v_mov_b32_e32 v11, v1
	s_nop 0
	v_addc_co_u32_e32 v7, vcc, 0, v7, vcc
	s_nop 1
	v_mov_b64_e32 v[18:19], v[108:109]
	v_mov_b64_e32 v[20:21], v[110:111]
	v_lshlrev_b64 v[6:7], 12, v[10:11]
	v_lshl_add_u64 v[6:7], v[4:5], 0, v[6:7]
	global_store_dwordx4 v[6:7], v[14:17], off
	ds_read_b128 v[14:17], v12 offset:3264
	s_waitcnt lgkmcnt(0)
	v_lshlrev_b32_e32 v11, 16, v14
	v_and_b32_e32 v14, 0xffff0000, v14
	s_waitcnt vmcnt(1)
; __device__ __forceinline__ void attn_unit(const bf16* __restrict__ P, unsigned short* __restrict__ Ob, int b, int h, int kvh, int qb, bool meta, int jt0, int ntl, float* part, unsigned* cnt, const float* __restrict__ qnw, const float2* __restrict__ rtab, char* lds) {
;     ...
;     for (int i = 0; i < 8; ++i) { const int cidx = lane + 64 * i, orow = cidx >> 4, c8 = (cidx & 15) * 8;
;       const u32x4 ov = *(const u32x4*)(stg + orow * 272 + c8 * 2);
;       const u32x4 gv = *(const u32x4*)(Pg + (grow0 + orow) * LD + 4096 + h * D + c8);
;       const unsigned ow[4] = {ov.x, ov.y, ov.z, ov.w}, gw[4] = {gv.x, gv.y, gv.z, gv.w}; unsigned res[4];
; #pragma unroll
;       for (int e = 0; e < 4; ++e) { const float o0 = __uint_as_float(ow[e] << 16), o1 = __uint_as_float(ow[e] & 0xffff0000u), g0 = __uint_as_float(gw[e] << 16), g1 = __uint_as_float(gw[e] & 0xffff0000u);
;         res[e] = cvtpk(o0 * (g0 / (1.f + __expf(-g0))), o1 * (g1 / (1.f + __expf(-g1)))); }
;       *(u32x4*)(Ob + (grow0 + orow) * 2048 + h * D + c8) = (u32x4){res[0], res[1], res[2], res[3]}; }
	v_lshlrev_b32_e32 v9, 16, v18
	v_mul_f32_e32 v10, 0xbfb8aa3b, v9
	v_exp_f32_e32 v10, v10
	v_and_b32_e32 v18, 0xffff0000, v18
	v_mul_f32_e32 v24, 0xbfb8aa3b, v18
	v_exp_f32_e32 v24, v24
	v_add_f32_e32 v6, 1.0, v10
	v_div_scale_f32 v7, s[0:1], v6, v6, v9
	v_rcp_f32_e32 v10, v7
	s_nop 0
	v_fma_f32 v22, -v7, v10, 1.0
	v_fmac_f32_e32 v10, v22, v10
	v_div_scale_f32 v22, vcc, v9, v6, v9
	v_mul_f32_e32 v23, v22, v10
	v_fma_f32 v25, -v7, v23, v22
	v_fmac_f32_e32 v23, v25, v10
	v_fma_f32 v7, -v7, v23, v22
	v_add_f32_e32 v22, 1.0, v24
	v_div_scale_f32 v24, s[0:1], v22, v22, v18
	v_rcp_f32_e32 v25, v24
	v_div_fmas_f32 v7, v7, v10, v23
	v_div_fixup_f32 v6, v7, v6, v9
	v_mul_f32_e32 v6, v6, v11
	v_fma_f32 v7, -v24, v25, 1.0
	v_fmac_f32_e32 v25, v7, v25
	v_div_scale_f32 v7, vcc, v18, v22, v18
	v_mul_f32_e32 v9, v7, v25
	v_fma_f32 v10, -v24, v9, v7
	v_fmac_f32_e32 v9, v10, v25
	v_fma_f32 v7, -v24, v9, v7
	v_div_fmas_f32 v7, v7, v25, v9
	v_lshlrev_b32_e32 v9, 16, v19
	v_mul_f32_e32 v10, 0xbfb8aa3b, v9
	v_exp_f32_e32 v10, v10
	v_div_fixup_f32 v7, v7, v22, v18
	v_mul_f32_e32 v7, v7, v14
	v_cvt_pk_bf16_f32 v14, v6, v7
	v_add_f32_e32 v6, 1.0, v10
	v_div_scale_f32 v7, s[0:1], v6, v6, v9
	v_rcp_f32_e32 v10, v7
	v_and_b32_e32 v18, 0xffff0000, v19
	v_mul_f32_e32 v23, 0xbfb8aa3b, v18
	v_exp_f32_e32 v23, v23
	v_fma_f32 v19, -v7, v10, 1.0
	v_fmac_f32_e32 v10, v19, v10
	v_div_scale_f32 v19, vcc, v9, v6, v9
	v_mul_f32_e32 v22, v19, v10
	v_fma_f32 v24, -v7, v22, v19
	v_fmac_f32_e32 v22, v24, v10
	v_fma_f32 v7, -v7, v22, v19
	v_add_f32_e32 v19, 1.0, v23
	v_div_scale_f32 v23, s[0:1], v19, v19, v18
	v_rcp_f32_e32 v24, v23
	v_div_fmas_f32 v7, v7, v10, v22
	v_div_fixup_f32 v6, v7, v6, v9
	v_lshlrev_b32_e32 v11, 16, v15
	v_fma_f32 v7, -v23, v24, 1.0
	v_fmac_f32_e32 v24, v7, v24
	v_div_scale_f32 v7, vcc, v18, v19, v18
	v_mul_f32_e32 v9, v7, v24
	v_fma_f32 v10, -v23, v9, v7
	v_fmac_f32_e32 v9, v10, v24
	v_fma_f32 v7, -v23, v9, v7
	v_div_fmas_f32 v7, v7, v24, v9
	v_lshlrev_b32_e32 v9, 16, v20
	v_mul_f32_e32 v10, 0xbfb8aa3b, v9
	v_exp_f32_e32 v10, v10
	v_and_b32_e32 v15, 0xffff0000, v15
	v_mul_f32_e32 v6, v6, v11
	v_div_fixup_f32 v7, v7, v19, v18
	v_mul_f32_e32 v7, v7, v15
	v_cvt_pk_bf16_f32 v15, v6, v7
	v_add_f32_e32 v6, 1.0, v10
	v_div_scale_f32 v7, s[0:1], v6, v6, v9
	v_rcp_f32_e32 v10, v7
	v_and_b32_e32 v18, 0xffff0000, v20
	v_mul_f32_e32 v22, 0xbfb8aa3b, v18
	v_exp_f32_e32 v22, v22
	v_fma_f32 v19, -v7, v10, 1.0
	v_fmac_f32_e32 v10, v19, v10
	v_div_scale_f32 v19, vcc, v9, v6, v9
	v_mul_f32_e32 v20, v19, v10
	v_fma_f32 v23, -v7, v20, v19
	v_fmac_f32_e32 v20, v23, v10
	v_fma_f32 v7, -v7, v20, v19
	v_add_f32_e32 v19, 1.0, v22
	v_div_scale_f32 v22, s[0:1], v19, v19, v18
	v_rcp_f32_e32 v23, v22
	v_div_fmas_f32 v7, v7, v10, v20
	v_div_fixup_f32 v6, v7, v6, v9
	v_lshlrev_b32_e32 v11, 16, v16
	v_fma_f32 v7, -v22, v23, 1.0
	v_fmac_f32_e32 v23, v7, v23
	v_div_scale_f32 v7, vcc, v18, v19, v18
	v_mul_f32_e32 v9, v7, v23
	v_fma_f32 v10, -v22, v9, v7
	v_fmac_f32_e32 v9, v10, v23
	v_fma_f32 v7, -v22, v9, v7
	v_div_fmas_f32 v7, v7, v23, v9
	v_lshlrev_b32_e32 v9, 16, v21
	v_mul_f32_e32 v10, 0xbfb8aa3b, v9
	v_exp_f32_e32 v10, v10
	v_and_b32_e32 v16, 0xffff0000, v16
	v_mul_f32_e32 v6, v6, v11
	v_div_fixup_f32 v7, v7, v19, v18
	v_mul_f32_e32 v7, v7, v16
	v_cvt_pk_bf16_f32 v16, v6, v7
	v_add_f32_e32 v6, 1.0, v10
	v_div_scale_f32 v7, s[0:1], v6, v6, v9
	v_rcp_f32_e32 v10, v7
	v_and_b32_e32 v18, 0xffff0000, v21
	v_mul_f32_e32 v21, 0xbfb8aa3b, v18
	v_exp_f32_e32 v21, v21
	v_fma_f32 v19, -v7, v10, 1.0
	v_fmac_f32_e32 v10, v19, v10
	v_div_scale_f32 v19, vcc, v9, v6, v9
	v_mul_f32_e32 v20, v19, v10
	v_fma_f32 v22, -v7, v20, v19
	v_fmac_f32_e32 v20, v22, v10
	v_fma_f32 v7, -v7, v20, v19
	v_add_f32_e32 v19, 1.0, v21
	v_div_scale_f32 v21, s[0:1], v19, v19, v18
	v_rcp_f32_e32 v22, v21
	v_div_fmas_f32 v7, v7, v10, v20
	v_div_fixup_f32 v6, v7, v6, v9
	v_lshlrev_b32_e32 v11, 16, v17
	v_fma_f32 v7, -v21, v22, 1.0
	v_fmac_f32_e32 v22, v7, v22
	v_div_scale_f32 v7, vcc, v18, v19, v18
	v_mul_f32_e32 v9, v7, v22
	v_fma_f32 v10, -v21, v9, v7
	v_fmac_f32_e32 v9, v10, v22
	v_fma_f32 v7, -v21, v9, v7
	v_div_fmas_f32 v7, v7, v22, v9
	v_and_b32_e32 v17, 0xffff0000, v17
	v_mul_f32_e32 v6, v6, v11
	v_div_fixup_f32 v7, v7, v19, v18
	v_mul_f32_e32 v7, v7, v17
	v_cvt_pk_bf16_f32 v17, v6, v7
	v_or_b32_e32 v6, 16, v0
	v_mad_u64_u32 v[10:11], s[0:1], v6, s44, v[2:3]
	v_add_u32_e32 v11, v13, v11
	v_lshl_add_u64 v[10:11], v[10:11], 0, s[8:9]
	v_lshl_add_u64 v[10:11], v[10:11], 0, v[176:177]
	v_add_co_u32_e32 v10, vcc, s50, v10
	v_mov_b32_e32 v9, v1
	s_nop 0
	v_addc_co_u32_e32 v11, vcc, 0, v11, vcc
	s_nop 1
	v_mov_b64_e32 v[18:19], v[112:113]
	v_mov_b64_e32 v[20:21], v[114:115]
	v_lshlrev_b64 v[8:9], 12, v[8:9]
	v_lshl_add_u64 v[8:9], v[4:5], 0, v[8:9]
	global_store_dwordx4 v[8:9], v[14:17], off
	s_waitcnt vmcnt(1)
	v_lshlrev_b32_e32 v7, 16, v18
	v_mul_f32_e32 v10, 0xbfb8aa3b, v7
	v_exp_f32_e32 v22, v10
	v_and_b32_e32 v18, 0xffff0000, v18
	v_mul_f32_e32 v24, 0xbfb8aa3b, v18
	v_exp_f32_e32 v24, v24
	v_add_f32_e32 v14, 1.0, v22
	v_div_scale_f32 v15, s[0:1], v14, v14, v7
	v_rcp_f32_e32 v16, v15
	ds_read_b128 v[8:11], v12 offset:4352
	v_fma_f32 v22, -v15, v16, 1.0
	v_fmac_f32_e32 v16, v22, v16
	v_div_scale_f32 v22, vcc, v7, v14, v7
	v_mul_f32_e32 v23, v22, v16
	v_fma_f32 v25, -v15, v23, v22
	v_fmac_f32_e32 v23, v25, v16
	v_fma_f32 v15, -v15, v23, v22
	v_add_f32_e32 v22, 1.0, v24
	v_div_scale_f32 v24, s[0:1], v22, v22, v18
	v_rcp_f32_e32 v25, v24
	v_div_fmas_f32 v15, v15, v16, v23
	v_div_fixup_f32 v7, v15, v14, v7
	s_waitcnt lgkmcnt(0)
; __device__ __forceinline__ void attn_unit(const bf16* __restrict__ P, unsigned short* __restrict__ Ob, int b, int h, int kvh, int qb, bool meta, int jt0, int ntl, float* part, unsigned* cnt, const float* __restrict__ qnw, const float2* __restrict__ rtab, char* lds) {
;     ...
;     for (int i = 0; i < 8; ++i) { const int cidx = lane + 64 * i, orow = cidx >> 4, c8 = (cidx & 15) * 8;
;       const u32x4 ov = *(const u32x4*)(stg + orow * 272 + c8 * 2);
;       const u32x4 gv = *(const u32x4*)(Pg + (grow0 + orow) * LD + 4096 + h * D + c8);
;       const unsigned ow[4] = {ov.x, ov.y, ov.z, ov.w}, gw[4] = {gv.x, gv.y, gv.z, gv.w}; unsigned res[4];
; #pragma unroll
;       for (int e = 0; e < 4; ++e) { const float o0 = __uint_as_float(ow[e] << 16), o1 = __uint_as_float(ow[e] & 0xffff0000u), g0 = __uint_as_float(gw[e] << 16), g1 = __uint_as_float(gw[e] & 0xffff0000u);
;         res[e] = cvtpk(o0 * (g0 / (1.f + __expf(-g0))), o1 * (g1 / (1.f + __expf(-g1)))); }
;       *(u32x4*)(Ob + (grow0 + orow) * 2048 + h * D + c8) = (u32x4){res[0], res[1], res[2], res[3]}; }
	v_lshlrev_b32_e32 v17, 16, v8
	v_fma_f32 v14, -v24, v25, 1.0
	v_fmac_f32_e32 v25, v14, v25
	v_div_scale_f32 v14, vcc, v18, v22, v18
	v_mul_f32_e32 v15, v14, v25
	v_fma_f32 v16, -v24, v15, v14
	v_fmac_f32_e32 v15, v16, v25
	v_fma_f32 v14, -v24, v15, v14
	v_div_fmas_f32 v14, v14, v25, v15
	v_lshlrev_b32_e32 v15, 16, v19
	v_mul_f32_e32 v16, 0xbfb8aa3b, v15
	v_exp_f32_e32 v16, v16
	v_and_b32_e32 v8, 0xffff0000, v8
	v_mul_f32_e32 v7, v7, v17
	v_div_fixup_f32 v14, v14, v22, v18
	v_mul_f32_e32 v8, v14, v8
	v_cvt_pk_bf16_f32 v14, v7, v8
	v_add_f32_e32 v7, 1.0, v16
	v_div_scale_f32 v8, s[0:1], v7, v7, v15
	v_rcp_f32_e32 v16, v8
	v_and_b32_e32 v18, 0xffff0000, v19
	v_mul_f32_e32 v23, 0xbfb8aa3b, v18
	v_exp_f32_e32 v23, v23
	v_fma_f32 v19, -v8, v16, 1.0
	v_fmac_f32_e32 v16, v19, v16
	v_div_scale_f32 v19, vcc, v15, v7, v15
	v_mul_f32_e32 v22, v19, v16
	v_fma_f32 v24, -v8, v22, v19
	v_fmac_f32_e32 v22, v24, v16
	v_fma_f32 v8, -v8, v22, v19
	v_add_f32_e32 v19, 1.0, v23
	v_div_scale_f32 v23, s[0:1], v19, v19, v18
	v_rcp_f32_e32 v24, v23
	v_div_fmas_f32 v8, v8, v16, v22
	v_div_fixup_f32 v7, v8, v7, v15
	v_lshlrev_b32_e32 v17, 16, v9
	v_fma_f32 v8, -v23, v24, 1.0
	v_fmac_f32_e32 v24, v8, v24
	v_div_scale_f32 v8, vcc, v18, v19, v18
	v_mul_f32_e32 v15, v8, v24
	v_fma_f32 v16, -v23, v15, v8
	v_fmac_f32_e32 v15, v16, v24
	v_fma_f32 v8, -v23, v15, v8
	v_lshlrev_b32_e32 v16, 16, v20
	v_div_fmas_f32 v8, v8, v24, v15
	v_mul_f32_e32 v15, 0xbfb8aa3b, v16
	v_mul_f32_e32 v7, v7, v17
	v_exp_f32_e32 v17, v15
	v_and_b32_e32 v9, 0xffff0000, v9
	v_div_fixup_f32 v8, v8, v19, v18
	v_mul_f32_e32 v8, v8, v9
	v_cvt_pk_bf16_f32 v15, v7, v8
	v_add_f32_e32 v7, 1.0, v17
	v_div_scale_f32 v8, s[0:1], v7, v7, v16
	v_rcp_f32_e32 v9, v8
	v_and_b32_e32 v18, 0xffff0000, v20
	v_mul_f32_e32 v22, 0xbfb8aa3b, v18
	v_exp_f32_e32 v22, v22
	v_fma_f32 v19, -v8, v9, 1.0
	v_fmac_f32_e32 v9, v19, v9
	v_div_scale_f32 v19, vcc, v16, v7, v16
	v_mul_f32_e32 v20, v19, v9
	v_fma_f32 v23, -v8, v20, v19
	v_fmac_f32_e32 v20, v23, v9
	v_fma_f32 v8, -v8, v20, v19
	v_add_f32_e32 v19, 1.0, v22
	v_div_scale_f32 v22, s[0:1], v19, v19, v18
	v_rcp_f32_e32 v23, v22
	v_div_fmas_f32 v8, v8, v9, v20
	v_div_fixup_f32 v7, v8, v7, v16
	v_lshlrev_b32_e32 v17, 16, v10
	v_fma_f32 v8, -v22, v23, 1.0
	v_fmac_f32_e32 v23, v8, v23
	v_div_scale_f32 v8, vcc, v18, v19, v18
	v_mul_f32_e32 v9, v8, v23
	v_fma_f32 v16, -v22, v9, v8
	v_fmac_f32_e32 v9, v16, v23
	v_fma_f32 v8, -v22, v9, v8
	v_div_fmas_f32 v8, v8, v23, v9
	v_lshlrev_b32_e32 v9, 16, v21
	v_mul_f32_e32 v16, 0xbfb8aa3b, v9
	v_mul_f32_e32 v7, v7, v17
	v_exp_f32_e32 v17, v16
	v_and_b32_e32 v10, 0xffff0000, v10
	v_div_fixup_f32 v8, v8, v19, v18
	v_mul_f32_e32 v8, v8, v10
	v_cvt_pk_bf16_f32 v16, v7, v8
	v_add_f32_e32 v7, 1.0, v17
	v_div_scale_f32 v8, s[0:1], v7, v7, v9
	v_rcp_f32_e32 v10, v8
	v_and_b32_e32 v18, 0xffff0000, v21
	v_mul_f32_e32 v21, 0xbfb8aa3b, v18
	v_exp_f32_e32 v21, v21
	v_fma_f32 v19, -v8, v10, 1.0
	v_fmac_f32_e32 v10, v19, v10
	v_div_scale_f32 v19, vcc, v9, v7, v9
	v_mul_f32_e32 v20, v19, v10
	v_fma_f32 v22, -v8, v20, v19
	v_fmac_f32_e32 v20, v22, v10
	v_fma_f32 v8, -v8, v20, v19
	v_add_f32_e32 v19, 1.0, v21
	v_div_scale_f32 v21, s[0:1], v19, v19, v18
	v_rcp_f32_e32 v22, v21
	v_div_fmas_f32 v8, v8, v10, v20
	v_div_fixup_f32 v7, v8, v7, v9
	v_lshlrev_b32_e32 v17, 16, v11
	v_fma_f32 v8, -v21, v22, 1.0
	v_fmac_f32_e32 v22, v8, v22
	v_div_scale_f32 v8, vcc, v18, v19, v18
	v_mul_f32_e32 v9, v8, v22
	v_fma_f32 v10, -v21, v9, v8
	v_fmac_f32_e32 v9, v10, v22
	v_fma_f32 v8, -v21, v9, v8
	v_div_fmas_f32 v8, v8, v22, v9
	v_and_b32_e32 v11, 0xffff0000, v11
	v_div_fixup_f32 v8, v8, v19, v18
	v_mul_f32_e32 v8, v8, v11
	v_mul_f32_e32 v7, v7, v17
	v_cvt_pk_bf16_f32 v17, v7, v8
	v_or_b32_e32 v8, 20, v0
	v_mad_u64_u32 v[10:11], s[0:1], v8, s44, v[2:3]
	v_add_u32_e32 v11, v13, v11
	v_lshl_add_u64 v[10:11], v[10:11], 0, s[8:9]
	v_lshl_add_u64 v[10:11], v[10:11], 0, v[176:177]
	v_add_co_u32_e32 v10, vcc, s50, v10
	v_mov_b32_e32 v7, v1
	s_nop 0
	v_addc_co_u32_e32 v11, vcc, 0, v11, vcc
	s_nop 1
	v_mov_b64_e32 v[18:19], v[116:117]
	v_mov_b64_e32 v[20:21], v[118:119]
	v_lshlrev_b64 v[6:7], 12, v[6:7]
	v_lshl_add_u64 v[6:7], v[4:5], 0, v[6:7]
	global_store_dwordx4 v[6:7], v[14:17], off
	ds_read_b128 v[14:17], v12 offset:5440
	s_waitcnt lgkmcnt(0)
	v_lshlrev_b32_e32 v11, 16, v14
	v_and_b32_e32 v14, 0xffff0000, v14
	s_waitcnt vmcnt(1)
; __device__ __forceinline__ void attn_unit(const bf16* __restrict__ P, unsigned short* __restrict__ Ob, int b, int h, int kvh, int qb, bool meta, int jt0, int ntl, float* part, unsigned* cnt, const float* __restrict__ qnw, const float2* __restrict__ rtab, char* lds) {
;     ...
;     for (int i = 0; i < 8; ++i) { const int cidx = lane + 64 * i, orow = cidx >> 4, c8 = (cidx & 15) * 8;
;       const u32x4 ov = *(const u32x4*)(stg + orow * 272 + c8 * 2);
;       const u32x4 gv = *(const u32x4*)(Pg + (grow0 + orow) * LD + 4096 + h * D + c8);
;       const unsigned ow[4] = {ov.x, ov.y, ov.z, ov.w}, gw[4] = {gv.x, gv.y, gv.z, gv.w}; unsigned res[4];
; #pragma unroll
;       for (int e = 0; e < 4; ++e) { const float o0 = __uint_as_float(ow[e] << 16), o1 = __uint_as_float(ow[e] & 0xffff0000u), g0 = __uint_as_float(gw[e] << 16), g1 = __uint_as_float(gw[e] & 0xffff0000u);
;         res[e] = cvtpk(o0 * (g0 / (1.f + __expf(-g0))), o1 * (g1 / (1.f + __expf(-g1)))); }
;       *(u32x4*)(Ob + (grow0 + orow) * 2048 + h * D + c8) = (u32x4){res[0], res[1], res[2], res[3]}; }
	v_lshlrev_b32_e32 v9, 16, v18
	v_mul_f32_e32 v10, 0xbfb8aa3b, v9
	v_exp_f32_e32 v10, v10
	v_and_b32_e32 v18, 0xffff0000, v18
	v_mul_f32_e32 v24, 0xbfb8aa3b, v18
	v_exp_f32_e32 v24, v24
	v_add_f32_e32 v6, 1.0, v10
	v_div_scale_f32 v7, s[0:1], v6, v6, v9
	v_rcp_f32_e32 v10, v7
	s_nop 0
	v_fma_f32 v22, -v7, v10, 1.0
	v_fmac_f32_e32 v10, v22, v10
	v_div_scale_f32 v22, vcc, v9, v6, v9
	v_mul_f32_e32 v23, v22, v10
	v_fma_f32 v25, -v7, v23, v22
	v_fmac_f32_e32 v23, v25, v10
	v_fma_f32 v7, -v7, v23, v22
	v_add_f32_e32 v22, 1.0, v24
	v_div_scale_f32 v24, s[0:1], v22, v22, v18
	v_rcp_f32_e32 v25, v24
	v_div_fmas_f32 v7, v7, v10, v23
	v_div_fixup_f32 v6, v7, v6, v9
	v_mul_f32_e32 v6, v6, v11
	v_fma_f32 v7, -v24, v25, 1.0
	v_fmac_f32_e32 v25, v7, v25
	v_div_scale_f32 v7, vcc, v18, v22, v18
	v_mul_f32_e32 v9, v7, v25
	v_fma_f32 v10, -v24, v9, v7
	v_fmac_f32_e32 v9, v10, v25
	v_fma_f32 v7, -v24, v9, v7
	v_div_fmas_f32 v7, v7, v25, v9
	v_lshlrev_b32_e32 v9, 16, v19
	v_mul_f32_e32 v10, 0xbfb8aa3b, v9
	v_exp_f32_e32 v10, v10
	v_div_fixup_f32 v7, v7, v22, v18
	v_mul_f32_e32 v7, v7, v14
	v_cvt_pk_bf16_f32 v14, v6, v7
	v_add_f32_e32 v6, 1.0, v10
	v_div_scale_f32 v7, s[0:1], v6, v6, v9
	v_rcp_f32_e32 v10, v7
	v_and_b32_e32 v18, 0xffff0000, v19
	v_mul_f32_e32 v23, 0xbfb8aa3b, v18
	v_exp_f32_e32 v23, v23
	v_fma_f32 v19, -v7, v10, 1.0
	v_fmac_f32_e32 v10, v19, v10
	v_div_scale_f32 v19, vcc, v9, v6, v9
	v_mul_f32_e32 v22, v19, v10
	v_fma_f32 v24, -v7, v22, v19
	v_fmac_f32_e32 v22, v24, v10
	v_fma_f32 v7, -v7, v22, v19
	v_add_f32_e32 v19, 1.0, v23
	v_div_scale_f32 v23, s[0:1], v19, v19, v18
	v_rcp_f32_e32 v24, v23
	v_div_fmas_f32 v7, v7, v10, v22
	v_div_fixup_f32 v6, v7, v6, v9
	v_lshlrev_b32_e32 v11, 16, v15
	v_fma_f32 v7, -v23, v24, 1.0
	v_fmac_f32_e32 v24, v7, v24
	v_div_scale_f32 v7, vcc, v18, v19, v18
	v_mul_f32_e32 v9, v7, v24
	v_fma_f32 v10, -v23, v9, v7
	v_fmac_f32_e32 v9, v10, v24
	v_fma_f32 v7, -v23, v9, v7
	v_div_fmas_f32 v7, v7, v24, v9
	v_lshlrev_b32_e32 v9, 16, v20
	v_mul_f32_e32 v10, 0xbfb8aa3b, v9
	v_exp_f32_e32 v10, v10
	v_and_b32_e32 v15, 0xffff0000, v15
	v_mul_f32_e32 v6, v6, v11
	v_div_fixup_f32 v7, v7, v19, v18
	v_mul_f32_e32 v7, v7, v15
	v_cvt_pk_bf16_f32 v15, v6, v7
	v_add_f32_e32 v6, 1.0, v10
	v_div_scale_f32 v7, s[0:1], v6, v6, v9
	v_rcp_f32_e32 v10, v7
	v_and_b32_e32 v18, 0xffff0000, v20
	v_mul_f32_e32 v22, 0xbfb8aa3b, v18
	v_exp_f32_e32 v22, v22
	v_fma_f32 v19, -v7, v10, 1.0
	v_fmac_f32_e32 v10, v19, v10
	v_div_scale_f32 v19, vcc, v9, v6, v9
	v_mul_f32_e32 v20, v19, v10
	v_fma_f32 v23, -v7, v20, v19
	v_fmac_f32_e32 v20, v23, v10
	v_fma_f32 v7, -v7, v20, v19
	v_add_f32_e32 v19, 1.0, v22
	v_div_scale_f32 v22, s[0:1], v19, v19, v18
	v_rcp_f32_e32 v23, v22
	v_div_fmas_f32 v7, v7, v10, v20
	v_div_fixup_f32 v6, v7, v6, v9
	v_lshlrev_b32_e32 v11, 16, v16
	v_fma_f32 v7, -v22, v23, 1.0
	v_fmac_f32_e32 v23, v7, v23
	v_div_scale_f32 v7, vcc, v18, v19, v18
	v_mul_f32_e32 v9, v7, v23
	v_fma_f32 v10, -v22, v9, v7
	v_fmac_f32_e32 v9, v10, v23
	v_fma_f32 v7, -v22, v9, v7
	v_div_fmas_f32 v7, v7, v23, v9
	v_lshlrev_b32_e32 v9, 16, v21
	v_mul_f32_e32 v10, 0xbfb8aa3b, v9
	v_exp_f32_e32 v10, v10
	v_and_b32_e32 v16, 0xffff0000, v16
	v_mul_f32_e32 v6, v6, v11
	v_div_fixup_f32 v7, v7, v19, v18
	v_mul_f32_e32 v7, v7, v16
	v_cvt_pk_bf16_f32 v16, v6, v7
	v_add_f32_e32 v6, 1.0, v10
	v_div_scale_f32 v7, s[0:1], v6, v6, v9
	v_rcp_f32_e32 v10, v7
	v_and_b32_e32 v18, 0xffff0000, v21
	v_mul_f32_e32 v21, 0xbfb8aa3b, v18
	v_exp_f32_e32 v21, v21
	v_fma_f32 v19, -v7, v10, 1.0
	v_fmac_f32_e32 v10, v19, v10
	v_div_scale_f32 v19, vcc, v9, v6, v9
	v_mul_f32_e32 v20, v19, v10
	v_fma_f32 v22, -v7, v20, v19
	v_fmac_f32_e32 v20, v22, v10
	v_fma_f32 v7, -v7, v20, v19
	v_add_f32_e32 v19, 1.0, v21
	v_div_scale_f32 v21, s[0:1], v19, v19, v18
	v_rcp_f32_e32 v22, v21
	v_div_fmas_f32 v7, v7, v10, v20
	v_div_fixup_f32 v6, v7, v6, v9
	v_lshlrev_b32_e32 v11, 16, v17
	v_fma_f32 v7, -v21, v22, 1.0
	v_fmac_f32_e32 v22, v7, v22
	v_div_scale_f32 v7, vcc, v18, v19, v18
	v_mul_f32_e32 v9, v7, v22
	v_fma_f32 v10, -v21, v9, v7
	v_fmac_f32_e32 v9, v10, v22
	v_fma_f32 v7, -v21, v9, v7
	v_div_fmas_f32 v7, v7, v22, v9
	v_and_b32_e32 v17, 0xffff0000, v17
	v_mul_f32_e32 v6, v6, v11
	v_div_fixup_f32 v7, v7, v19, v18
	v_mul_f32_e32 v7, v7, v17
	v_cvt_pk_bf16_f32 v17, v6, v7
	v_or_b32_e32 v6, 24, v0
	v_mad_u64_u32 v[10:11], s[0:1], v6, s44, v[2:3]
	v_add_u32_e32 v11, v13, v11
	v_lshl_add_u64 v[10:11], v[10:11], 0, s[8:9]
	v_lshl_add_u64 v[10:11], v[10:11], 0, v[176:177]
	v_add_co_u32_e32 v10, vcc, s50, v10
	v_mov_b32_e32 v9, v1
	s_nop 0
	v_addc_co_u32_e32 v11, vcc, 0, v11, vcc
	s_nop 1
	v_mov_b64_e32 v[18:19], v[120:121]
	v_mov_b64_e32 v[20:21], v[122:123]
	v_lshlrev_b64 v[8:9], 12, v[8:9]
	v_lshl_add_u64 v[8:9], v[4:5], 0, v[8:9]
	global_store_dwordx4 v[8:9], v[14:17], off
	v_or_b32_e32 v0, 28, v0
	v_mad_u64_u32 v[2:3], s[0:1], v0, s44, v[2:3]
	v_add_u32_e32 v3, v13, v3
	v_lshl_add_u64 v[2:3], v[2:3], 0, s[8:9]
	v_lshl_add_u64 v[2:3], v[2:3], 0, v[176:177]
	s_waitcnt vmcnt(1)
	v_lshlrev_b32_e32 v7, 16, v18
	v_mul_f32_e32 v10, 0xbfb8aa3b, v7
	v_exp_f32_e32 v22, v10
	v_and_b32_e32 v18, 0xffff0000, v18
	v_mul_f32_e32 v24, 0xbfb8aa3b, v18
	v_exp_f32_e32 v24, v24
	v_add_f32_e32 v14, 1.0, v22
	v_div_scale_f32 v15, s[0:1], v14, v14, v7
	v_rcp_f32_e32 v16, v15
	ds_read_b128 v[8:11], v12 offset:6528
	v_fma_f32 v22, -v15, v16, 1.0
	v_fmac_f32_e32 v16, v22, v16
	v_div_scale_f32 v22, vcc, v7, v14, v7
	v_mul_f32_e32 v23, v22, v16
	v_fma_f32 v25, -v15, v23, v22
	v_fmac_f32_e32 v23, v25, v16
	v_fma_f32 v15, -v15, v23, v22
	v_add_f32_e32 v22, 1.0, v24
	v_div_scale_f32 v24, s[0:1], v22, v22, v18
	v_rcp_f32_e32 v25, v24
	v_div_fmas_f32 v15, v15, v16, v23
	v_div_fixup_f32 v7, v15, v14, v7
	s_waitcnt lgkmcnt(0)
; __device__ __forceinline__ void attn_unit(const bf16* __restrict__ P, unsigned short* __restrict__ Ob, int b, int h, int kvh, int qb, bool meta, int jt0, int ntl, float* part, unsigned* cnt, const float* __restrict__ qnw, const float2* __restrict__ rtab, char* lds) {
;     ...
;     for (int i = 0; i < 8; ++i) { const int cidx = lane + 64 * i, orow = cidx >> 4, c8 = (cidx & 15) * 8;
;       const u32x4 ov = *(const u32x4*)(stg + orow * 272 + c8 * 2);
;       const u32x4 gv = *(const u32x4*)(Pg + (grow0 + orow) * LD + 4096 + h * D + c8);
;       const unsigned ow[4] = {ov.x, ov.y, ov.z, ov.w}, gw[4] = {gv.x, gv.y, gv.z, gv.w}; unsigned res[4];
; #pragma unroll
;       for (int e = 0; e < 4; ++e) { const float o0 = __uint_as_float(ow[e] << 16), o1 = __uint_as_float(ow[e] & 0xffff0000u), g0 = __uint_as_float(gw[e] << 16), g1 = __uint_as_float(gw[e] & 0xffff0000u);
;         res[e] = cvtpk(o0 * (g0 / (1.f + __expf(-g0))), o1 * (g1 / (1.f + __expf(-g1)))); }
;       *(u32x4*)(Ob + (grow0 + orow) * 2048 + h * D + c8) = (u32x4){res[0], res[1], res[2], res[3]}; }
	v_lshlrev_b32_e32 v17, 16, v8
	v_fma_f32 v14, -v24, v25, 1.0
	v_fmac_f32_e32 v25, v14, v25
	v_div_scale_f32 v14, vcc, v18, v22, v18
	v_mul_f32_e32 v15, v14, v25
	v_fma_f32 v16, -v24, v15, v14
	v_fmac_f32_e32 v15, v16, v25
	v_fma_f32 v14, -v24, v15, v14
	v_div_fmas_f32 v14, v14, v25, v15
	v_lshlrev_b32_e32 v15, 16, v19
	v_mul_f32_e32 v16, 0xbfb8aa3b, v15
	v_exp_f32_e32 v16, v16
	v_and_b32_e32 v8, 0xffff0000, v8
	v_div_fixup_f32 v14, v14, v22, v18
	v_mul_f32_e32 v7, v7, v17
	v_mul_f32_e32 v8, v14, v8
	v_cvt_pk_bf16_f32 v8, v7, v8
	v_add_f32_e32 v7, 1.0, v16
	v_div_scale_f32 v14, s[0:1], v7, v7, v15
	v_rcp_f32_e32 v16, v14
	v_and_b32_e32 v18, 0xffff0000, v19
	v_mul_f32_e32 v23, 0xbfb8aa3b, v18
	v_exp_f32_e32 v23, v23
	v_fma_f32 v19, -v14, v16, 1.0
	v_fmac_f32_e32 v16, v19, v16
	v_div_scale_f32 v19, vcc, v15, v7, v15
	v_mul_f32_e32 v22, v19, v16
	v_fma_f32 v24, -v14, v22, v19
	v_fmac_f32_e32 v22, v24, v16
	v_fma_f32 v14, -v14, v22, v19
	v_add_f32_e32 v19, 1.0, v23
	v_div_scale_f32 v23, s[0:1], v19, v19, v18
	v_rcp_f32_e32 v24, v23
	v_div_fmas_f32 v14, v14, v16, v22
	v_div_fixup_f32 v7, v14, v7, v15
	v_lshlrev_b32_e32 v17, 16, v9
	v_fma_f32 v14, -v23, v24, 1.0
	v_fmac_f32_e32 v24, v14, v24
	v_div_scale_f32 v14, vcc, v18, v19, v18
	v_mul_f32_e32 v15, v14, v24
	v_fma_f32 v16, -v23, v15, v14
	v_fmac_f32_e32 v15, v16, v24
	v_fma_f32 v14, -v23, v15, v14
	v_div_fmas_f32 v14, v14, v24, v15
	v_lshlrev_b32_e32 v15, 16, v20
	v_mul_f32_e32 v16, 0xbfb8aa3b, v15
	v_exp_f32_e32 v16, v16
	v_and_b32_e32 v9, 0xffff0000, v9
	v_div_fixup_f32 v14, v14, v19, v18
	v_mul_f32_e32 v7, v7, v17
	v_mul_f32_e32 v9, v14, v9
	v_cvt_pk_bf16_f32 v9, v7, v9
	v_add_f32_e32 v7, 1.0, v16
	v_div_scale_f32 v14, s[0:1], v7, v7, v15
	v_rcp_f32_e32 v16, v14
	v_and_b32_e32 v18, 0xffff0000, v20
	v_mul_f32_e32 v22, 0xbfb8aa3b, v18
	v_exp_f32_e32 v22, v22
	v_fma_f32 v19, -v14, v16, 1.0
	v_fmac_f32_e32 v16, v19, v16
	v_div_scale_f32 v19, vcc, v15, v7, v15
	v_mul_f32_e32 v20, v19, v16
	v_fma_f32 v23, -v14, v20, v19
	v_fmac_f32_e32 v20, v23, v16
	v_fma_f32 v14, -v14, v20, v19
	v_add_f32_e32 v19, 1.0, v22
	v_div_scale_f32 v22, s[0:1], v19, v19, v18
	v_rcp_f32_e32 v23, v22
	v_div_fmas_f32 v14, v14, v16, v20
	v_div_fixup_f32 v7, v14, v7, v15
	v_lshlrev_b32_e32 v17, 16, v10
	v_fma_f32 v14, -v22, v23, 1.0
	v_fmac_f32_e32 v23, v14, v23
	v_div_scale_f32 v14, vcc, v18, v19, v18
	v_mul_f32_e32 v15, v14, v23
	v_fma_f32 v16, -v22, v15, v14
	v_fmac_f32_e32 v15, v16, v23
	v_fma_f32 v14, -v22, v15, v14
	v_div_fmas_f32 v14, v14, v23, v15
	v_lshlrev_b32_e32 v15, 16, v21
	v_mul_f32_e32 v16, 0xbfb8aa3b, v15
	v_exp_f32_e32 v16, v16
	v_and_b32_e32 v10, 0xffff0000, v10
	v_div_fixup_f32 v14, v14, v19, v18
	v_mul_f32_e32 v7, v7, v17
	v_mul_f32_e32 v10, v14, v10
	v_cvt_pk_bf16_f32 v10, v7, v10
	v_add_f32_e32 v7, 1.0, v16
	v_div_scale_f32 v14, s[0:1], v7, v7, v15
	v_rcp_f32_e32 v16, v14
	v_and_b32_e32 v18, 0xffff0000, v21
	v_mul_f32_e32 v21, 0xbfb8aa3b, v18
	v_exp_f32_e32 v21, v21
	v_fma_f32 v19, -v14, v16, 1.0
	v_fmac_f32_e32 v16, v19, v16
	v_div_scale_f32 v19, vcc, v15, v7, v15
	v_mul_f32_e32 v20, v19, v16
	v_fma_f32 v22, -v14, v20, v19
	v_fmac_f32_e32 v20, v22, v16
	v_fma_f32 v14, -v14, v20, v19
	v_add_f32_e32 v19, 1.0, v21
	v_div_scale_f32 v21, s[0:1], v19, v19, v18
	v_rcp_f32_e32 v22, v21
	v_div_fmas_f32 v14, v14, v16, v20
	v_div_fixup_f32 v7, v14, v7, v15
	v_lshlrev_b32_e32 v17, 16, v11
	v_fma_f32 v14, -v21, v22, 1.0
	v_fmac_f32_e32 v22, v14, v22
	v_div_scale_f32 v14, vcc, v18, v19, v18
	v_mul_f32_e32 v15, v14, v22
	v_fma_f32 v16, -v21, v15, v14
	v_fmac_f32_e32 v15, v16, v22
	v_fma_f32 v14, -v21, v15, v14
	v_div_fmas_f32 v14, v14, v22, v15
	v_and_b32_e32 v11, 0xffff0000, v11
	v_div_fixup_f32 v14, v14, v19, v18
	v_add_co_u32_e32 v2, vcc, s50, v2
	v_mul_f32_e32 v11, v14, v11
	s_nop 0
	v_addc_co_u32_e32 v3, vcc, 0, v3, vcc
	v_mul_f32_e32 v7, v7, v17
	v_cvt_pk_bf16_f32 v11, v7, v11
	s_nop 1
	v_mov_b64_e32 v[14:15], v[124:125]
	v_mov_b64_e32 v[16:17], v[126:127]
	v_mov_b32_e32 v7, v1
	v_lshlrev_b64 v[2:3], 12, v[6:7]
	v_lshl_add_u64 v[2:3], v[4:5], 0, v[2:3]
	global_store_dwordx4 v[2:3], v[8:11], off
	v_lshlrev_b64 v[0:1], 12, v[0:1]
	v_lshl_add_u64 v[0:1], v[4:5], 0, v[0:1]
	s_waitcnt vmcnt(1)
; __device__ __forceinline__ void attn_unit(const bf16* __restrict__ P, unsigned short* __restrict__ Ob, int b, int h, int kvh, int qb, bool meta, int jt0, int ntl, float* part, unsigned* cnt, const float* __restrict__ qnw, const float2* __restrict__ rtab, char* lds) {
;     ...
;     for (int i = 0; i < 8; ++i) { const int cidx = lane + 64 * i, orow = cidx >> 4, c8 = (cidx & 15) * 8;
;       const u32x4 ov = *(const u32x4*)(stg + orow * 272 + c8 * 2);
;       const u32x4 gv = *(const u32x4*)(Pg + (grow0 + orow) * LD + 4096 + h * D + c8);
;       const unsigned ow[4] = {ov.x, ov.y, ov.z, ov.w}, gw[4] = {gv.x, gv.y, gv.z, gv.w}; unsigned res[4];
; #pragma unroll
;       for (int e = 0; e < 4; ++e) { const float o0 = __uint_as_float(ow[e] << 16), o1 = __uint_as_float(ow[e] & 0xffff0000u), g0 = __uint_as_float(gw[e] << 16), g1 = __uint_as_float(gw[e] & 0xffff0000u);
;         res[e] = cvtpk(o0 * (g0 / (1.f + __expf(-g0))), o1 * (g1 / (1.f + __expf(-g1)))); }
;       *(u32x4*)(Ob + (grow0 + orow) * 2048 + h * D + c8) = (u32x4){res[0], res[1], res[2], res[3]}; }
;     ...
;   __syncthreads();
	v_lshlrev_b32_e32 v13, 16, v14
	v_mul_f32_e32 v6, 0xbfb8aa3b, v13
	v_exp_f32_e32 v18, v6
	ds_read_b128 v[6:9], v12 offset:7616
	v_and_b32_e32 v12, 0xffff0000, v14
	v_mul_f32_e32 v19, 0xbfb8aa3b, v12
	v_add_f32_e32 v2, 1.0, v18
	v_div_scale_f32 v3, s[0:1], v2, v2, v13
	v_rcp_f32_e32 v10, v3
	v_exp_f32_e32 v19, v19
	s_waitcnt lgkmcnt(0)
	v_lshlrev_b32_e32 v11, 16, v6
	v_and_b32_e32 v6, 0xffff0000, v6
	v_fma_f32 v14, -v3, v10, 1.0
	v_fmac_f32_e32 v10, v14, v10
	v_div_scale_f32 v14, vcc, v13, v2, v13
	v_mul_f32_e32 v18, v14, v10
	v_fma_f32 v20, -v3, v18, v14
	v_fmac_f32_e32 v18, v20, v10
	v_fma_f32 v3, -v3, v18, v14
	v_add_f32_e32 v14, 1.0, v19
	v_div_scale_f32 v19, s[0:1], v14, v14, v12
	v_rcp_f32_e32 v20, v19
	v_div_fmas_f32 v3, v3, v10, v18
	v_div_fixup_f32 v2, v3, v2, v13
	v_mul_f32_e32 v2, v2, v11
	v_fma_f32 v3, -v19, v20, 1.0
	v_fmac_f32_e32 v20, v3, v20
	v_div_scale_f32 v3, vcc, v12, v14, v12
	v_mul_f32_e32 v10, v3, v20
	v_fma_f32 v11, -v19, v10, v3
	v_fmac_f32_e32 v10, v11, v20
	v_fma_f32 v3, -v19, v10, v3
	v_div_fmas_f32 v3, v3, v20, v10
	v_lshlrev_b32_e32 v10, 16, v15
	v_mul_f32_e32 v11, 0xbfb8aa3b, v10
	v_exp_f32_e32 v11, v11
	v_div_fixup_f32 v3, v3, v14, v12
	v_mul_f32_e32 v3, v3, v6
	v_cvt_pk_bf16_f32 v6, v2, v3
	v_add_f32_e32 v2, 1.0, v11
	v_div_scale_f32 v3, s[0:1], v2, v2, v10
	v_rcp_f32_e32 v11, v3
	v_and_b32_e32 v13, 0xffff0000, v15
	v_mul_f32_e32 v18, 0xbfb8aa3b, v13
	v_exp_f32_e32 v18, v18
	v_fma_f32 v14, -v3, v11, 1.0
	v_fmac_f32_e32 v11, v14, v11
	v_div_scale_f32 v14, vcc, v10, v2, v10
	v_mul_f32_e32 v15, v14, v11
	v_fma_f32 v19, -v3, v15, v14
	v_fmac_f32_e32 v15, v19, v11
	v_fma_f32 v3, -v3, v15, v14
	v_add_f32_e32 v14, 1.0, v18
	v_div_scale_f32 v18, s[0:1], v14, v14, v13
	v_rcp_f32_e32 v19, v18
	v_div_fmas_f32 v3, v3, v11, v15
	v_div_fixup_f32 v2, v3, v2, v10
	v_lshlrev_b32_e32 v12, 16, v7
	v_fma_f32 v3, -v18, v19, 1.0
	v_fmac_f32_e32 v19, v3, v19
	v_div_scale_f32 v3, vcc, v13, v14, v13
	v_mul_f32_e32 v10, v3, v19
	v_fma_f32 v11, -v18, v10, v3
	v_fmac_f32_e32 v10, v11, v19
	v_fma_f32 v3, -v18, v10, v3
	v_div_fmas_f32 v3, v3, v19, v10
	v_lshlrev_b32_e32 v10, 16, v16
	v_mul_f32_e32 v11, 0xbfb8aa3b, v10
	v_exp_f32_e32 v11, v11
	v_and_b32_e32 v7, 0xffff0000, v7
	v_mul_f32_e32 v2, v2, v12
	v_div_fixup_f32 v3, v3, v14, v13
	v_mul_f32_e32 v3, v3, v7
	v_cvt_pk_bf16_f32 v7, v2, v3
	v_add_f32_e32 v2, 1.0, v11
	v_div_scale_f32 v3, s[0:1], v2, v2, v10
	v_rcp_f32_e32 v11, v3
	v_and_b32_e32 v13, 0xffff0000, v16
	v_mul_f32_e32 v16, 0xbfb8aa3b, v13
	v_exp_f32_e32 v16, v16
	v_fma_f32 v14, -v3, v11, 1.0
	v_fmac_f32_e32 v11, v14, v11
	v_div_scale_f32 v14, vcc, v10, v2, v10
	v_mul_f32_e32 v15, v14, v11
	v_fma_f32 v18, -v3, v15, v14
	v_fmac_f32_e32 v15, v18, v11
	v_fma_f32 v3, -v3, v15, v14
	v_add_f32_e32 v14, 1.0, v16
	v_div_scale_f32 v16, s[0:1], v14, v14, v13
	v_rcp_f32_e32 v18, v16
	v_div_fmas_f32 v3, v3, v11, v15
	v_div_fixup_f32 v2, v3, v2, v10
	v_lshlrev_b32_e32 v12, 16, v8
	v_fma_f32 v3, -v16, v18, 1.0
	v_fmac_f32_e32 v18, v3, v18
	v_div_scale_f32 v3, vcc, v13, v14, v13
	v_mul_f32_e32 v10, v3, v18
	v_fma_f32 v11, -v16, v10, v3
	v_fmac_f32_e32 v10, v11, v18
	v_fma_f32 v3, -v16, v10, v3
	v_div_fmas_f32 v3, v3, v18, v10
	v_lshlrev_b32_e32 v10, 16, v17
	v_mul_f32_e32 v11, 0xbfb8aa3b, v10
	v_exp_f32_e32 v11, v11
	v_and_b32_e32 v8, 0xffff0000, v8
	v_mul_f32_e32 v2, v2, v12
	v_div_fixup_f32 v3, v3, v14, v13
	v_mul_f32_e32 v3, v3, v8
	v_cvt_pk_bf16_f32 v8, v2, v3
	v_add_f32_e32 v2, 1.0, v11
	v_div_scale_f32 v3, s[0:1], v2, v2, v10
	v_rcp_f32_e32 v11, v3
	v_and_b32_e32 v13, 0xffff0000, v17
	v_mul_f32_e32 v16, 0xbfb8aa3b, v13
	v_exp_f32_e32 v16, v16
	v_fma_f32 v14, -v3, v11, 1.0
	v_fmac_f32_e32 v11, v14, v11
	v_div_scale_f32 v14, vcc, v10, v2, v10
	v_mul_f32_e32 v15, v14, v11
	v_fma_f32 v17, -v3, v15, v14
	v_fmac_f32_e32 v15, v17, v11
	v_fma_f32 v3, -v3, v15, v14
	v_add_f32_e32 v14, 1.0, v16
	v_div_scale_f32 v16, s[0:1], v14, v14, v13
	v_rcp_f32_e32 v17, v16
	v_div_fmas_f32 v3, v3, v11, v15
	v_div_fixup_f32 v2, v3, v2, v10
	v_lshlrev_b32_e32 v12, 16, v9
	v_fma_f32 v3, -v16, v17, 1.0
	v_fmac_f32_e32 v17, v3, v17
	v_div_scale_f32 v3, vcc, v13, v14, v13
	v_mul_f32_e32 v10, v3, v17
	v_fma_f32 v11, -v16, v10, v3
	v_fmac_f32_e32 v10, v11, v17
	v_fma_f32 v3, -v16, v10, v3
	v_div_fmas_f32 v3, v3, v17, v10
	v_and_b32_e32 v9, 0xffff0000, v9
	v_div_fixup_f32 v3, v3, v14, v13
	v_mul_f32_e32 v2, v2, v12
	v_mul_f32_e32 v3, v3, v9
	v_cvt_pk_bf16_f32 v9, v2, v3
	global_store_dwordx4 v[0:1], v[6:9], off
	s_barrier

; #define LAS __attribute__((address_space(3)))
; __device__ __forceinline__ void xcd_barrier(const XcdBarrier& b) {
;     ...
;             asm volatile("s_waitcnt vmcnt(0)" ::: "memory");
;         }
;     }
;     __syncthreads();
; template <int PH>
; __device__ __forceinline__ void run_phase(Ctx& c, LAS unsigned char* lds, char* lds_generic) {
;     ...
;             constexpr int n_meta = 2 * (NFULL / 32), n_lr = (k == 1 && !attn) ? NREAL / 32 : 0;
;             const int r32 = c.lane & 31, hi = c.lane >> 5;
;             LAS float* RED = (LAS float*)lds;
;             for (int t = blockIdx.x; t < n_meta + n_lr; t += c.G) {
;                 const int row0 = t < n_meta ? NREAL + 32 * (t & 1) : 32 * (t - n_meta), col0 = t < n_meta ? 32 * (t >> 1) : ATT_N;
;                 const bf16_t* ap = Ap + (size_t)(row0 + r32) * DM + c.wave * 256 + hi * 64; const bf16_t* bp = Bp + (size_t)(col0 + r32) * DM + c.wave * 256 + hi * 64;
.LBB0_376:
	s_or_b64 exec, exec, s[2:3]
	s_waitcnt lgkmcnt(0)
	s_barrier
	s_nop 0
	s_nop 0
	s_nop 0
	s_nop 0
	s_nop 0
	s_nop 0
	s_nop 0
	s_nop 0
	s_nop 0
	s_nop 0
	s_nop 0
	s_nop 0
	s_nop 0
	s_nop 0
.LBB0_377:
	s_cmp_lt_i32 s74, 6
	s_cselect_b64 s[0:1], -1, 0
	s_cmp_gt_i32 s75, 5
	s_cselect_b64 s[2:3], -1, 0
	s_and_b64 s[0:1], s[0:1], s[2:3]
	s_andn2_b64 vcc, exec, s[0:1]
	s_cbranch_vccnz .LBB0_459
	s_add_u32 s38, s72, 0x2200000
	s_addc_u32 s39, s73, 0
	s_add_u32 s40, s72, 0x1a00000
	s_addc_u32 s41, s73, 0
	s_add_u32 s4, s72, 0x12500000
	v_mov_b32_e32 v0, v200
	s_addc_u32 s5, s73, 0
	s_cmpk_gt_i32 s76, 0x7f
	v_readfirstlane_b32 s0, v0
	s_cbranch_scc1 .LBB0_381
	s_ashr_i32 s6, s0, 6
	s_lshl_b32 s0, s6, 8
	s_ashr_i32 s1, s0, 31
	s_lshl_b64 s[0:1], s[0:1], 1
	s_add_u32 s2, s38, s0
	v_and_b32_e32 v24, 31, v0
	v_bfe_u32 v1, v0, 5, 1
	s_addc_u32 s3, s39, s1
	v_lshlrev_b32_e32 v2, 9, v1
	v_lshlrev_b32_e32 v3, 2, v24
	v_lshlrev_b32_e32 v16, 7, v1
	v_mov_b32_e32 v17, 0
	s_add_u32 s0, s40, s0
	v_add3_u32 v2, 0, v2, v3
	v_lshl_add_u64 v[18:19], s[2:3], 0, v[16:17]
	s_addc_u32 s1, s41, s1
	s_lshl_b32 s2, s6, 12
	v_lshlrev_b32_e32 v1, 1, v0
	v_lshl_add_u32 v25, v0, 3, 0
	v_ashrrev_i32_e32 v26, 4, v0
	v_and_b32_e32 v0, 30, v1
	v_add_u32_e32 v27, s2, v2
	v_lshl_add_u64 v[20:21], s[0:1], 0, v[16:17]
	s_lshl_b32 s0, s76, 4
	s_lshl_b32 s1, s63, 4
	s_lshl_b32 s6, s76, 5
	s_lshl_b32 s7, s63, 5
	v_lshlrev_b32_e32 v22, 1, v0
	v_mov_b32_e32 v23, v17
	v_add_u32_e32 v28, 0x400, v27
	v_add_u32_e32 v29, 0x800, v27
	v_add_u32_e32 v30, 0xc00, v27
	s_mov_b32 s8, s76

; __device__ __forceinline__ int crow(int r, int hi) { return (r & 3) + 8 * (r >> 2) + 4 * hi; }
; __device__ __forceinline__ unsigned short f2bf(float f) { unsigned u = __float_as_uint(f); return (unsigned short)((u + 0x7fffu + ((u >> 16) & 1u)) >> 16); }
; __device__ __forceinline__ unsigned f2bf(float f) { return pk2(f, 0.f) & 0xffffu; }
; __device__ __forceinline__ void attn_unit(const bf16* __restrict__ P, unsigned short* __restrict__ Ob, int b, int h, int kvh, int qb, bool meta, int jt0, int ntl, float* part, unsigned* cnt, const float* __restrict__ qnw, const float2* __restrict__ rtab, char* lds) {
;     ...
;     if (hi == 0) li_l[r32] = l_reg; asm volatile("s_waitcnt lgkmcnt(0)" ::: "memory");
;     float rli[16];
; #pragma unroll
;     for (int r = 0; r < 16; ++r) rli[r] = __builtin_amdgcn_rcpf(li_l[crow(r, hi)]);
;     char* stg = lds + 2 * SHM_V + 2 * SHM_K + NW * 64 * 4 + wid * (32 * 272);
; #pragma unroll
;     for (int r = 0; r < 16; ++r) { const int orow = crow(r, hi);
; #pragma unroll
;       for (int d0 = 0; d0 < 4; ++d0) *(unsigned short*)(stg + orow * 272 + (d0 * 32 + r32) * 2) = f2bf(o[d0][r] * rli[r]); }
.LBB0_1234:
	s_or_b64 exec, exec, s[0:1]
	s_waitcnt lgkmcnt(0)
	v_add_u32_e32 v72, v195, v180
	ds_read_b128 v[64:67], v72
	ds_read_b128 v[68:71], v72 offset:32
	v_lshlrev_b32_e32 v81, 1, v193
	v_mul_u32_u24_e32 v82, 0x440, v194
	s_lshl_b32 s64, s38, 1
	s_waitcnt lgkmcnt(1)
	v_rcp_f32_e32 v73, v64
	v_rcp_f32_e32 v74, v65
	v_rcp_f32_e32 v75, v66
	v_rcp_f32_e32 v76, v67
	s_waitcnt lgkmcnt(0)
	v_rcp_f32_e32 v77, v68
	ds_read_b128 v[64:67], v72 offset:64
	v_rcp_f32_e32 v78, v69
	v_rcp_f32_e32 v79, v70
	v_rcp_f32_e32 v80, v71
	ds_read_b128 v[68:71], v72 offset:96
	v_mul_lo_u32 v72, v192, s96
	v_add_u32_e32 v72, s97, v72
	v_mul_f32_e32 v0, v0, v73
	v_add3_u32 v81, v72, v81, v82
	v_bfe_u32 v82, v0, 16, 1
	v_add3_u32 v0, v0, v82, s61
	ds_write_b16_d16_hi v81, v0
	v_mul_f32_e32 v0, v48, v73
	v_bfe_u32 v48, v0, 16, 1
	v_add3_u32 v0, v0, v48, s61
	ds_write_b16_d16_hi v81, v0 offset:64
	v_mul_f32_e32 v0, v32, v73
	v_bfe_u32 v32, v0, 16, 1
	v_add3_u32 v0, v0, v32, s61
	ds_write_b16_d16_hi v81, v0 offset:128
	v_mul_f32_e32 v0, v16, v73
	v_bfe_u32 v16, v0, 16, 1
	v_add3_u32 v0, v0, v16, s61
	ds_write_b16_d16_hi v81, v0 offset:192
	v_mul_f32_e32 v0, v1, v74
	v_bfe_u32 v1, v0, 16, 1
	v_add3_u32 v0, v0, v1, s61
	ds_write_b16_d16_hi v81, v0 offset:272
	v_mul_f32_e32 v0, v49, v74
	v_bfe_u32 v1, v0, 16, 1
	v_add3_u32 v0, v0, v1, s61
	ds_write_b16_d16_hi v81, v0 offset:336
	v_mul_f32_e32 v0, v33, v74
	v_bfe_u32 v1, v0, 16, 1
	v_add3_u32 v0, v0, v1, s61
	ds_write_b16_d16_hi v81, v0 offset:400
	v_mul_f32_e32 v0, v17, v74
	v_bfe_u32 v1, v0, 16, 1
	v_add3_u32 v0, v0, v1, s61
	ds_write_b16_d16_hi v81, v0 offset:464
	v_mul_f32_e32 v0, v2, v75
	v_bfe_u32 v1, v0, 16, 1
	v_add3_u32 v0, v0, v1, s61
	ds_write_b16_d16_hi v81, v0 offset:544
	v_mul_f32_e32 v0, v50, v75
	v_bfe_u32 v1, v0, 16, 1
	v_add3_u32 v0, v0, v1, s61
	ds_write_b16_d16_hi v81, v0 offset:608
	v_mul_f32_e32 v0, v34, v75
	v_bfe_u32 v1, v0, 16, 1
	v_add3_u32 v0, v0, v1, s61
	ds_write_b16_d16_hi v81, v0 offset:672
	v_mul_f32_e32 v0, v18, v75
	v_bfe_u32 v1, v0, 16, 1
	v_add3_u32 v0, v0, v1, s61
	ds_write_b16_d16_hi v81, v0 offset:736
	v_mul_f32_e32 v0, v3, v76
	v_bfe_u32 v1, v0, 16, 1
	v_add3_u32 v0, v0, v1, s61
	ds_write_b16_d16_hi v81, v0 offset:816
	v_mul_f32_e32 v0, v51, v76
	v_bfe_u32 v1, v0, 16, 1
	v_add3_u32 v0, v0, v1, s61
	ds_write_b16_d16_hi v81, v0 offset:880
	v_mul_f32_e32 v0, v35, v76
	v_bfe_u32 v1, v0, 16, 1
	v_add3_u32 v0, v0, v1, s61
	ds_write_b16_d16_hi v81, v0 offset:944
	v_mul_f32_e32 v0, v19, v76
	v_bfe_u32 v1, v0, 16, 1
	v_add3_u32 v0, v0, v1, s61
	ds_write_b16_d16_hi v81, v0 offset:1008
	v_mul_f32_e32 v0, v4, v77
	v_bfe_u32 v1, v0, 16, 1
	v_add3_u32 v0, v0, v1, s61
	ds_write_b16_d16_hi v81, v0 offset:2176
	v_mul_f32_e32 v0, v52, v77
	v_bfe_u32 v1, v0, 16, 1
	v_add3_u32 v0, v0, v1, s61
	ds_write_b16_d16_hi v81, v0 offset:2240
	v_mul_f32_e32 v0, v36, v77
	v_bfe_u32 v1, v0, 16, 1
	v_add3_u32 v0, v0, v1, s61
	ds_write_b16_d16_hi v81, v0 offset:2304
	v_mul_f32_e32 v0, v20, v77
	v_bfe_u32 v1, v0, 16, 1
	v_add3_u32 v0, v0, v1, s61
	ds_write_b16_d16_hi v81, v0 offset:2368
	v_mul_f32_e32 v0, v5, v78
	v_bfe_u32 v1, v0, 16, 1
	v_add3_u32 v0, v0, v1, s61
	ds_write_b16_d16_hi v81, v0 offset:2448
	v_mul_f32_e32 v0, v53, v78
	v_bfe_u32 v1, v0, 16, 1
	v_add3_u32 v0, v0, v1, s61
	ds_write_b16_d16_hi v81, v0 offset:2512
	v_mul_f32_e32 v0, v37, v78
	v_bfe_u32 v1, v0, 16, 1
	v_add3_u32 v0, v0, v1, s61
	ds_write_b16_d16_hi v81, v0 offset:2576
	v_mul_f32_e32 v0, v21, v78
	v_bfe_u32 v1, v0, 16, 1
	v_add3_u32 v0, v0, v1, s61
	ds_write_b16_d16_hi v81, v0 offset:2640
	v_mul_f32_e32 v0, v6, v79
	v_bfe_u32 v1, v0, 16, 1
	v_add3_u32 v0, v0, v1, s61
	ds_write_b16_d16_hi v81, v0 offset:2720
	v_mul_f32_e32 v0, v54, v79
	v_bfe_u32 v1, v0, 16, 1
	v_add3_u32 v0, v0, v1, s61
	ds_write_b16_d16_hi v81, v0 offset:2784
	v_mul_f32_e32 v0, v38, v79
	v_bfe_u32 v1, v0, 16, 1
	v_add3_u32 v0, v0, v1, s61
	ds_write_b16_d16_hi v81, v0 offset:2848
	v_mul_f32_e32 v0, v22, v79
	v_bfe_u32 v1, v0, 16, 1
	v_add3_u32 v0, v0, v1, s61
	ds_write_b16_d16_hi v81, v0 offset:2912
	v_mul_f32_e32 v0, v7, v80
	v_bfe_u32 v1, v0, 16, 1
	v_add3_u32 v0, v0, v1, s61
	ds_write_b16_d16_hi v81, v0 offset:2992
	v_mul_f32_e32 v0, v55, v80
	v_bfe_u32 v1, v0, 16, 1
	v_add3_u32 v0, v0, v1, s61
	ds_write_b16_d16_hi v81, v0 offset:3056
	v_mul_f32_e32 v0, v39, v80
	v_bfe_u32 v1, v0, 16, 1
	s_waitcnt lgkmcnt(14)
; __device__ __forceinline__ int crow(int r, int hi) { return (r & 3) + 8 * (r >> 2) + 4 * hi; }
; __device__ __forceinline__ unsigned short f2bf(float f) { unsigned u = __float_as_uint(f); return (unsigned short)((u + 0x7fffu + ((u >> 16) & 1u)) >> 16); }
; __device__ __forceinline__ unsigned f2bf(float f) { return pk2(f, 0.f) & 0xffffu; }
; __device__ __forceinline__ void attn_unit(const bf16* __restrict__ P, unsigned short* __restrict__ Ob, int b, int h, int kvh, int qb, bool meta, int jt0, int ntl, float* part, unsigned* cnt, const float* __restrict__ qnw, const float2* __restrict__ rtab, char* lds) {
;     ...
;     for (int r = 0; r < 16; ++r) { const int orow = crow(r, hi);
; #pragma unroll
;       for (int d0 = 0; d0 < 4; ++d0) *(unsigned short*)(stg + orow * 272 + (d0 * 32 + r32) * 2) = f2bf(o[d0][r] * rli[r]); }
;     asm volatile("s_waitcnt lgkmcnt(0)" ::: "memory");
;     const long grow0 = (long)b * 4096 + qb * 256 + wid * QBLK;
; #pragma unroll
;     for (int i = 0; i < 8; ++i) { const int cidx = lane + 64 * i, orow = cidx >> 4, c8 = (cidx & 15) * 8;
;       const u32x4 ov = *(const u32x4*)(stg + orow * 272 + c8 * 2);
;       const u32x4 gv = *(const u32x4*)(Pg + (grow0 + orow) * LD + 4096 + h * D + c8);
	v_rcp_f32_e32 v64, v64
	v_add3_u32 v0, v0, v1, s61
	ds_write_b16_d16_hi v81, v0 offset:3120
	v_mul_f32_e32 v0, v23, v80
	v_bfe_u32 v1, v0, 16, 1
	v_add3_u32 v0, v0, v1, s61
	ds_write_b16_d16_hi v81, v0 offset:3184
	v_mul_f32_e32 v0, v8, v64
	v_bfe_u32 v1, v0, 16, 1
	v_add3_u32 v0, v0, v1, s61
	ds_write_b16_d16_hi v81, v0 offset:4352
	v_mul_f32_e32 v0, v56, v64
	v_bfe_u32 v1, v0, 16, 1
	v_add3_u32 v0, v0, v1, s61
	ds_write_b16_d16_hi v81, v0 offset:4416
	v_mul_f32_e32 v0, v40, v64
	v_bfe_u32 v1, v0, 16, 1
	v_rcp_f32_e32 v65, v65
	v_add3_u32 v0, v0, v1, s61
	ds_write_b16_d16_hi v81, v0 offset:4480
	v_mul_f32_e32 v0, v24, v64
	v_bfe_u32 v1, v0, 16, 1
	v_add3_u32 v0, v0, v1, s61
	ds_write_b16_d16_hi v81, v0 offset:4544
	v_mul_f32_e32 v0, v9, v65
	v_bfe_u32 v1, v0, 16, 1
	v_add3_u32 v0, v0, v1, s61
	ds_write_b16_d16_hi v81, v0 offset:4624
	v_mul_f32_e32 v0, v57, v65
	v_bfe_u32 v1, v0, 16, 1
	v_add3_u32 v0, v0, v1, s61
	ds_write_b16_d16_hi v81, v0 offset:4688
	v_mul_f32_e32 v0, v41, v65
	v_bfe_u32 v1, v0, 16, 1
	v_rcp_f32_e32 v66, v66
	v_add3_u32 v0, v0, v1, s61
	ds_write_b16_d16_hi v81, v0 offset:4752
	v_mul_f32_e32 v0, v25, v65
	v_bfe_u32 v1, v0, 16, 1
	v_add3_u32 v0, v0, v1, s61
	ds_write_b16_d16_hi v81, v0 offset:4816
	v_mul_f32_e32 v0, v10, v66
	v_bfe_u32 v1, v0, 16, 1
	v_add3_u32 v0, v0, v1, s61
	ds_write_b16_d16_hi v81, v0 offset:4896
	v_mul_f32_e32 v0, v58, v66
	v_bfe_u32 v1, v0, 16, 1
	v_add3_u32 v0, v0, v1, s61
	ds_write_b16_d16_hi v81, v0 offset:4960
	v_mul_f32_e32 v0, v42, v66
	v_bfe_u32 v1, v0, 16, 1
	v_rcp_f32_e32 v67, v67
	v_add3_u32 v0, v0, v1, s61
	ds_write_b16_d16_hi v81, v0 offset:5024
	v_mul_f32_e32 v0, v26, v66
	v_bfe_u32 v1, v0, 16, 1
	v_add3_u32 v0, v0, v1, s61
	ds_write_b16_d16_hi v81, v0 offset:5088
	v_mul_f32_e32 v0, v11, v67
	v_bfe_u32 v1, v0, 16, 1
	v_add3_u32 v0, v0, v1, s61
	ds_write_b16_d16_hi v81, v0 offset:5168
	v_mul_f32_e32 v0, v59, v67
	v_bfe_u32 v1, v0, 16, 1
	v_add3_u32 v0, v0, v1, s61
	ds_write_b16_d16_hi v81, v0 offset:5232
	v_mul_f32_e32 v0, v43, v67
	v_bfe_u32 v1, v0, 16, 1
	v_rcp_f32_e32 v68, v68
	v_add3_u32 v0, v0, v1, s61
	ds_write_b16_d16_hi v81, v0 offset:5296
	v_mul_f32_e32 v0, v27, v67
	v_bfe_u32 v1, v0, 16, 1
	v_add3_u32 v0, v0, v1, s61
	ds_write_b16_d16_hi v81, v0 offset:5360
	v_mul_f32_e32 v0, v12, v68
	v_bfe_u32 v1, v0, 16, 1
	v_add3_u32 v0, v0, v1, s61
	ds_write_b16_d16_hi v81, v0 offset:6528
	v_mul_f32_e32 v0, v60, v68
	v_bfe_u32 v1, v0, 16, 1
	v_add3_u32 v0, v0, v1, s61
	ds_write_b16_d16_hi v81, v0 offset:6592
	v_mul_f32_e32 v0, v44, v68
	v_bfe_u32 v1, v0, 16, 1
	v_rcp_f32_e32 v69, v69
	v_add3_u32 v0, v0, v1, s61
	ds_write_b16_d16_hi v81, v0 offset:6656
	v_mul_f32_e32 v0, v28, v68
	v_bfe_u32 v1, v0, 16, 1
	v_add3_u32 v0, v0, v1, s61
	ds_write_b16_d16_hi v81, v0 offset:6720
	v_mul_f32_e32 v0, v13, v69
	v_bfe_u32 v1, v0, 16, 1
	v_add3_u32 v0, v0, v1, s61
	ds_write_b16_d16_hi v81, v0 offset:6800
	v_mul_f32_e32 v0, v61, v69
	v_bfe_u32 v1, v0, 16, 1
	v_add3_u32 v0, v0, v1, s61
	ds_write_b16_d16_hi v81, v0 offset:6864
	v_mul_f32_e32 v0, v45, v69
	v_bfe_u32 v1, v0, 16, 1
	v_rcp_f32_e32 v70, v70
	v_add3_u32 v0, v0, v1, s61
	ds_write_b16_d16_hi v81, v0 offset:6928
	v_mul_f32_e32 v0, v29, v69
	v_bfe_u32 v1, v0, 16, 1
	v_add3_u32 v0, v0, v1, s61
	ds_write_b16_d16_hi v81, v0 offset:6992
	v_mul_f32_e32 v0, v14, v70
	v_bfe_u32 v1, v0, 16, 1
	v_add3_u32 v0, v0, v1, s61
	ds_write_b16_d16_hi v81, v0 offset:7072
	v_mul_f32_e32 v0, v62, v70
	v_bfe_u32 v1, v0, 16, 1
	v_add3_u32 v0, v0, v1, s61
	ds_write_b16_d16_hi v81, v0 offset:7136
	v_mul_f32_e32 v0, v46, v70
	v_bfe_u32 v1, v0, 16, 1
	v_rcp_f32_e32 v71, v71
	v_add3_u32 v0, v0, v1, s61
	ds_write_b16_d16_hi v81, v0 offset:7200
	v_mul_f32_e32 v0, v30, v70
	v_bfe_u32 v1, v0, 16, 1
	v_add3_u32 v0, v0, v1, s61
	ds_write_b16_d16_hi v81, v0 offset:7264
	v_mul_f32_e32 v0, v15, v71
	v_bfe_u32 v1, v0, 16, 1
	v_add3_u32 v0, v0, v1, s61
	ds_write_b16_d16_hi v81, v0 offset:7344
	v_mul_f32_e32 v0, v63, v71
	v_bfe_u32 v1, v0, 16, 1
	v_add3_u32 v0, v0, v1, s61
	ds_write_b16_d16_hi v81, v0 offset:7408
	v_mul_f32_e32 v0, v47, v71
	v_bfe_u32 v1, v0, 16, 1
	v_add3_u32 v0, v0, v1, s61
	ds_write_b16_d16_hi v81, v0 offset:7472
	v_mul_f32_e32 v0, v31, v71
	v_bfe_u32 v1, v0, 16, 1
	v_add3_u32 v0, v0, v1, s61
	ds_write_b16_d16_hi v81, v0 offset:7536
	v_lshl_add_u64 v[0:1], s[36:37], 0, v[178:179]
	v_lshrrev_b32_e32 v8, 4, v181
	v_or_b32_e32 v0, v8, v0
	v_mov_b64_e32 v[2:3], s[6:7]
	v_mad_u64_u32 v[4:5], s[0:1], v0, s46, v[2:3]
	v_mul_lo_u32 v13, v1, s46
	v_add_u32_e32 v5, v13, v5
	v_lshl_add_u64 v[4:5], v[4:5], 0, s[64:65]
	v_lshl_add_u64 v[4:5], v[4:5], 0, v[176:177]
	v_add_co_u32_e32 v4, vcc, s52, v4
	s_waitcnt lgkmcnt(0)
	v_mul_u32_u24_e32 v8, 0x110, v8
	s_nop 0
	v_addc_co_u32_e32 v5, vcc, 0, v5, vcc
	s_mov_b32 s99, 0
	s_mov_b32 s98, 0xc000
	v_lshl_add_u64 v[128:129], v[4:5], 0, s[98:99]
	global_load_dwordx4 v[100:103], v[128:129], off
	s_mov_b32 s98, 0x18000
	v_lshl_add_u64 v[128:129], v[4:5], 0, s[98:99]
	global_load_dwordx4 v[104:107], v[128:129], off
	s_mov_b32 s98, 0x24000
	v_lshl_add_u64 v[128:129], v[4:5], 0, s[98:99]
	global_load_dwordx4 v[108:111], v[128:129], off
	s_mov_b32 s98, 0x30000
	v_lshl_add_u64 v[128:129], v[4:5], 0, s[98:99]
	global_load_dwordx4 v[112:115], v[128:129], off
	s_mov_b32 s98, 0x3c000
	v_lshl_add_u64 v[128:129], v[4:5], 0, s[98:99]
	global_load_dwordx4 v[116:119], v[128:129], off
	s_mov_b32 s98, 0x48000
	v_lshl_add_u64 v[128:129], v[4:5], 0, s[98:99]
	global_load_dwordx4 v[120:123], v[128:129], off
	s_mov_b32 s98, 0x54000
	v_lshl_add_u64 v[128:129], v[4:5], 0, s[98:99]
	global_load_dwordx4 v[124:127], v[128:129], off
	global_load_dwordx4 v[4:7], v[4:5], off
	v_add3_u32 v12, v72, v176, v8
	s_waitcnt vmcnt(0)
; __device__ __forceinline__ void attn_unit(const bf16* __restrict__ P, unsigned short* __restrict__ Ob, int b, int h, int kvh, int qb, bool meta, int jt0, int ntl, float* part, unsigned* cnt, const float* __restrict__ qnw, const float2* __restrict__ rtab, char* lds) {
;     ...
;     for (int i = 0; i < 8; ++i) { const int cidx = lane + 64 * i, orow = cidx >> 4, c8 = (cidx & 15) * 8;
;       const u32x4 ov = *(const u32x4*)(stg + orow * 272 + c8 * 2);
;       const u32x4 gv = *(const u32x4*)(Pg + (grow0 + orow) * LD + 4096 + h * D + c8);
;       const unsigned ow[4] = {ov.x, ov.y, ov.z, ov.w}, gw[4] = {gv.x, gv.y, gv.z, gv.w}; unsigned res[4];
; #pragma unroll
;       for (int e = 0; e < 4; ++e) { const float o0 = __uint_as_float(ow[e] << 16), o1 = __uint_as_float(ow[e] & 0xffff0000u), g0 = __uint_as_float(gw[e] << 16), g1 = __uint_as_float(gw[e] & 0xffff0000u);
;         res[e] = cvtpk(o0 * (g0 / (1.f + __expf(-g0))), o1 * (g1 / (1.f + __expf(-g1)))); }
;       *(u32x4*)(Ob + (grow0 + orow) * 2048 + h * D + c8) = (u32x4){res[0], res[1], res[2], res[3]}; }
	v_lshlrev_b32_e32 v14, 16, v4
	v_mul_f32_e32 v9, 0xbfb8aa3b, v14
	v_exp_f32_e32 v15, v9
	v_and_b32_e32 v4, 0xffff0000, v4
	v_mul_f32_e32 v21, 0xbfb8aa3b, v4
	v_exp_f32_e32 v21, v21
	v_add_f32_e32 v15, 1.0, v15
	v_div_scale_f32 v16, s[0:1], v15, v15, v14
	v_rcp_f32_e32 v17, v16
	ds_read_b128 v[8:11], v12
	v_fma_f32 v19, -v16, v17, 1.0
	v_fmac_f32_e32 v17, v19, v17
	v_div_scale_f32 v19, vcc, v14, v15, v14
	v_mul_f32_e32 v20, v19, v17
	v_fma_f32 v22, -v16, v20, v19
	v_fmac_f32_e32 v20, v22, v17
	v_fma_f32 v16, -v16, v20, v19
	v_add_f32_e32 v19, 1.0, v21
	v_div_scale_f32 v21, s[0:1], v19, v19, v4
	v_rcp_f32_e32 v22, v21
	v_div_fmas_f32 v16, v16, v17, v20
	v_div_fixup_f32 v14, v16, v15, v14
	s_waitcnt lgkmcnt(0)
	v_lshlrev_b32_e32 v18, 16, v8
	v_fma_f32 v15, -v21, v22, 1.0
	v_fmac_f32_e32 v22, v15, v22
	v_div_scale_f32 v15, vcc, v4, v19, v4
	v_mul_f32_e32 v16, v15, v22
	v_fma_f32 v17, -v21, v16, v15
	v_fmac_f32_e32 v16, v17, v22
	v_fma_f32 v15, -v21, v16, v15
	v_div_fmas_f32 v15, v15, v22, v16
	v_lshlrev_b32_e32 v16, 16, v5
	v_mul_f32_e32 v17, 0xbfb8aa3b, v16
	v_exp_f32_e32 v17, v17
	v_and_b32_e32 v8, 0xffff0000, v8
	v_div_fixup_f32 v4, v15, v19, v4
	v_mul_f32_e32 v4, v4, v8
	v_mul_f32_e32 v14, v14, v18
	v_cvt_pk_bf16_f32 v8, v14, v4
	v_add_f32_e32 v4, 1.0, v17
	v_div_scale_f32 v14, s[0:1], v4, v4, v16
	v_rcp_f32_e32 v15, v14
	v_and_b32_e32 v5, 0xffff0000, v5
	v_mul_f32_e32 v20, 0xbfb8aa3b, v5
	v_exp_f32_e32 v20, v20
	v_fma_f32 v18, -v14, v15, 1.0
	v_fmac_f32_e32 v15, v18, v15
	v_div_scale_f32 v18, vcc, v16, v4, v16
	v_mul_f32_e32 v19, v18, v15
	v_fma_f32 v21, -v14, v19, v18
	v_fmac_f32_e32 v19, v21, v15
	v_fma_f32 v14, -v14, v19, v18
	v_add_f32_e32 v18, 1.0, v20
	v_div_scale_f32 v20, s[0:1], v18, v18, v5
	v_rcp_f32_e32 v21, v20
	v_div_fmas_f32 v14, v14, v15, v19
	v_div_fixup_f32 v4, v14, v4, v16
	v_lshlrev_b32_e32 v17, 16, v9
	v_fma_f32 v14, -v20, v21, 1.0
	v_fmac_f32_e32 v21, v14, v21
	v_div_scale_f32 v14, vcc, v5, v18, v5
	v_mul_f32_e32 v15, v14, v21
	v_fma_f32 v16, -v20, v15, v14
	v_fmac_f32_e32 v15, v16, v21
	v_fma_f32 v14, -v20, v15, v14
	v_div_fmas_f32 v14, v14, v21, v15
	v_lshlrev_b32_e32 v15, 16, v6
	v_mul_f32_e32 v16, 0xbfb8aa3b, v15
	v_exp_f32_e32 v16, v16
	v_and_b32_e32 v9, 0xffff0000, v9
	v_mul_f32_e32 v4, v4, v17
	v_div_fixup_f32 v5, v14, v18, v5
	v_mul_f32_e32 v5, v5, v9
	v_cvt_pk_bf16_f32 v9, v4, v5
	v_add_f32_e32 v4, 1.0, v16
	v_div_scale_f32 v5, s[0:1], v4, v4, v15
	v_rcp_f32_e32 v14, v5
	v_and_b32_e32 v6, 0xffff0000, v6
	v_mul_f32_e32 v19, 0xbfb8aa3b, v6
	v_exp_f32_e32 v19, v19
	v_fma_f32 v17, -v5, v14, 1.0
	v_fmac_f32_e32 v14, v17, v14
	v_div_scale_f32 v17, vcc, v15, v4, v15
	v_mul_f32_e32 v18, v17, v14
	v_fma_f32 v20, -v5, v18, v17
	v_fmac_f32_e32 v18, v20, v14
	v_fma_f32 v5, -v5, v18, v17
	v_add_f32_e32 v17, 1.0, v19
	v_div_scale_f32 v19, s[0:1], v17, v17, v6
	v_rcp_f32_e32 v20, v19
	v_div_fmas_f32 v5, v5, v14, v18
	v_div_fixup_f32 v4, v5, v4, v15
	v_lshlrev_b32_e32 v16, 16, v10
	v_fma_f32 v5, -v19, v20, 1.0
	v_fmac_f32_e32 v20, v5, v20
	v_div_scale_f32 v5, vcc, v6, v17, v6
	v_mul_f32_e32 v14, v5, v20
	v_fma_f32 v15, -v19, v14, v5
	v_fmac_f32_e32 v14, v15, v20
	v_fma_f32 v5, -v19, v14, v5
	v_div_fmas_f32 v5, v5, v20, v14
	v_lshlrev_b32_e32 v14, 16, v7
	v_mul_f32_e32 v15, 0xbfb8aa3b, v14
	v_exp_f32_e32 v15, v15
	v_and_b32_e32 v10, 0xffff0000, v10
	v_mul_f32_e32 v4, v4, v16
	v_div_fixup_f32 v5, v5, v17, v6
	v_mul_f32_e32 v5, v5, v10
	v_cvt_pk_bf16_f32 v10, v4, v5
	v_add_f32_e32 v4, 1.0, v15
	v_div_scale_f32 v5, s[0:1], v4, v4, v14
	v_rcp_f32_e32 v6, v5
	v_and_b32_e32 v7, 0xffff0000, v7
	v_mul_f32_e32 v18, 0xbfb8aa3b, v7
	v_exp_f32_e32 v18, v18
	v_fma_f32 v16, -v5, v6, 1.0
	v_fmac_f32_e32 v6, v16, v6
	v_div_scale_f32 v16, vcc, v14, v4, v14
	v_mul_f32_e32 v17, v16, v6
	v_fma_f32 v19, -v5, v17, v16
	v_fmac_f32_e32 v17, v19, v6
	v_fma_f32 v5, -v5, v17, v16
	v_add_f32_e32 v16, 1.0, v18
	v_div_scale_f32 v18, s[0:1], v16, v16, v7
	v_rcp_f32_e32 v19, v18
	v_div_fmas_f32 v5, v5, v6, v17
	v_div_fixup_f32 v4, v5, v4, v14
	v_lshlrev_b32_e32 v15, 16, v11
	v_fma_f32 v5, -v18, v19, 1.0
	v_fmac_f32_e32 v19, v5, v19
	v_div_scale_f32 v5, vcc, v7, v16, v7
	v_mul_f32_e32 v6, v5, v19
	v_fma_f32 v14, -v18, v6, v5
	v_fmac_f32_e32 v6, v14, v19
	v_fma_f32 v5, -v18, v6, v5
	v_div_fmas_f32 v5, v5, v19, v6
	v_and_b32_e32 v11, 0xffff0000, v11
	v_div_fixup_f32 v5, v5, v16, v7
	v_mul_f32_e32 v4, v4, v15
	v_mul_f32_e32 v5, v5, v11
	v_or_b32_e32 v6, 4, v0
	v_cvt_pk_bf16_f32 v11, v4, v5
	v_mad_u64_u32 v[4:5], s[0:1], v6, s46, v[2:3]
	v_add_u32_e32 v5, v13, v5
	v_lshl_add_u64 v[4:5], v[4:5], 0, s[64:65]
	v_lshl_add_u64 v[4:5], v[4:5], 0, v[176:177]
	v_add_co_u32_e32 v4, vcc, s52, v4
	s_add_u32 s0, s24, s64
	s_nop 0
	v_addc_co_u32_e32 v5, vcc, 0, v5, vcc
	s_nop 1
	v_mov_b64_e32 v[14:15], v[100:101]
	v_mov_b64_e32 v[16:17], v[102:103]
	s_addc_u32 s1, s25, 0
	v_lshl_add_u64 v[4:5], s[0:1], 0, v[176:177]
	v_lshlrev_b64 v[18:19], 12, v[0:1]
	v_lshl_add_u64 v[18:19], v[4:5], 0, v[18:19]
	global_store_dwordx4 v[18:19], v[8:11], off
	ds_read_b128 v[8:11], v12 offset:1088
	s_waitcnt lgkmcnt(0)
	v_lshlrev_b32_e32 v21, 16, v8
	v_and_b32_e32 v8, 0xffff0000, v8
	s_waitcnt vmcnt(1)
; __device__ __forceinline__ void attn_unit(const bf16* __restrict__ P, unsigned short* __restrict__ Ob, int b, int h, int kvh, int qb, bool meta, int jt0, int ntl, float* part, unsigned* cnt, const float* __restrict__ qnw, const float2* __restrict__ rtab, char* lds) {
;     ...
;     for (int i = 0; i < 8; ++i) { const int cidx = lane + 64 * i, orow = cidx >> 4, c8 = (cidx & 15) * 8;
;       const u32x4 ov = *(const u32x4*)(stg + orow * 272 + c8 * 2);
;       const u32x4 gv = *(const u32x4*)(Pg + (grow0 + orow) * LD + 4096 + h * D + c8);
;       const unsigned ow[4] = {ov.x, ov.y, ov.z, ov.w}, gw[4] = {gv.x, gv.y, gv.z, gv.w}; unsigned res[4];
; #pragma unroll
;       for (int e = 0; e < 4; ++e) { const float o0 = __uint_as_float(ow[e] << 16), o1 = __uint_as_float(ow[e] & 0xffff0000u), g0 = __uint_as_float(gw[e] << 16), g1 = __uint_as_float(gw[e] & 0xffff0000u);
;         res[e] = cvtpk(o0 * (g0 / (1.f + __expf(-g0))), o1 * (g1 / (1.f + __expf(-g1)))); }
;       *(u32x4*)(Ob + (grow0 + orow) * 2048 + h * D + c8) = (u32x4){res[0], res[1], res[2], res[3]}; }
	v_lshlrev_b32_e32 v7, 16, v14
	v_mul_f32_e32 v20, 0xbfb8aa3b, v7
	v_exp_f32_e32 v20, v20
	v_and_b32_e32 v14, 0xffff0000, v14
	v_mul_f32_e32 v24, 0xbfb8aa3b, v14
	v_exp_f32_e32 v24, v24
	v_add_f32_e32 v18, 1.0, v20
	v_div_scale_f32 v19, s[0:1], v18, v18, v7
	v_rcp_f32_e32 v20, v19
	s_nop 0
	v_fma_f32 v22, -v19, v20, 1.0
	v_fmac_f32_e32 v20, v22, v20
	v_div_scale_f32 v22, vcc, v7, v18, v7
	v_mul_f32_e32 v23, v22, v20
	v_fma_f32 v25, -v19, v23, v22
	v_fmac_f32_e32 v23, v25, v20
	v_fma_f32 v19, -v19, v23, v22
	v_add_f32_e32 v22, 1.0, v24
	v_div_scale_f32 v24, s[0:1], v22, v22, v14
	v_rcp_f32_e32 v25, v24
	v_div_fmas_f32 v19, v19, v20, v23
	v_div_fixup_f32 v7, v19, v18, v7
	v_mul_f32_e32 v7, v7, v21
	v_fma_f32 v18, -v24, v25, 1.0
	v_fmac_f32_e32 v25, v18, v25
	v_div_scale_f32 v18, vcc, v14, v22, v14
	v_mul_f32_e32 v19, v18, v25
	v_fma_f32 v20, -v24, v19, v18
	v_fmac_f32_e32 v19, v20, v25
	v_fma_f32 v18, -v24, v19, v18
	v_div_fmas_f32 v18, v18, v25, v19
	v_lshlrev_b32_e32 v19, 16, v15
	v_mul_f32_e32 v20, 0xbfb8aa3b, v19
	v_exp_f32_e32 v20, v20
	v_div_fixup_f32 v14, v18, v22, v14
	v_mul_f32_e32 v8, v14, v8
	v_cvt_pk_bf16_f32 v14, v7, v8
	v_add_f32_e32 v7, 1.0, v20
	v_div_scale_f32 v8, s[0:1], v7, v7, v19
	v_rcp_f32_e32 v18, v8
	v_and_b32_e32 v15, 0xffff0000, v15
	v_mul_f32_e32 v23, 0xbfb8aa3b, v15
	v_exp_f32_e32 v23, v23
	v_fma_f32 v21, -v8, v18, 1.0
	v_fmac_f32_e32 v18, v21, v18
	v_div_scale_f32 v21, vcc, v19, v7, v19
	v_mul_f32_e32 v22, v21, v18
	v_fma_f32 v24, -v8, v22, v21
	v_fmac_f32_e32 v22, v24, v18
	v_fma_f32 v8, -v8, v22, v21
	v_add_f32_e32 v21, 1.0, v23
	v_div_scale_f32 v23, s[0:1], v21, v21, v15
	v_rcp_f32_e32 v24, v23
	v_div_fmas_f32 v8, v8, v18, v22
	v_div_fixup_f32 v7, v8, v7, v19
	v_lshlrev_b32_e32 v20, 16, v9
	v_fma_f32 v8, -v23, v24, 1.0
	v_fmac_f32_e32 v24, v8, v24
	v_div_scale_f32 v8, vcc, v15, v21, v15
	v_mul_f32_e32 v18, v8, v24
	v_fma_f32 v19, -v23, v18, v8
	v_fmac_f32_e32 v18, v19, v24
	v_fma_f32 v8, -v23, v18, v8
	v_div_fmas_f32 v8, v8, v24, v18
	v_lshlrev_b32_e32 v18, 16, v16
	v_mul_f32_e32 v19, 0xbfb8aa3b, v18
	v_exp_f32_e32 v19, v19
	v_and_b32_e32 v9, 0xffff0000, v9
	v_mul_f32_e32 v7, v7, v20
	v_div_fixup_f32 v8, v8, v21, v15
	v_mul_f32_e32 v8, v8, v9
	v_cvt_pk_bf16_f32 v15, v7, v8
	v_add_f32_e32 v7, 1.0, v19
	v_div_scale_f32 v8, s[0:1], v7, v7, v18
	v_rcp_f32_e32 v9, v8
	v_and_b32_e32 v16, 0xffff0000, v16
	v_mul_f32_e32 v22, 0xbfb8aa3b, v16
	v_exp_f32_e32 v22, v22
	v_fma_f32 v20, -v8, v9, 1.0
	v_fmac_f32_e32 v9, v20, v9
	v_div_scale_f32 v20, vcc, v18, v7, v18
	v_mul_f32_e32 v21, v20, v9
	v_fma_f32 v23, -v8, v21, v20
	v_fmac_f32_e32 v21, v23, v9
	v_fma_f32 v8, -v8, v21, v20
	v_add_f32_e32 v20, 1.0, v22
	v_div_scale_f32 v22, s[0:1], v20, v20, v16
	v_rcp_f32_e32 v23, v22
	v_div_fmas_f32 v8, v8, v9, v21
	v_div_fixup_f32 v7, v8, v7, v18
	v_lshlrev_b32_e32 v19, 16, v10
	v_fma_f32 v8, -v22, v23, 1.0
	v_fmac_f32_e32 v23, v8, v23
	v_div_scale_f32 v8, vcc, v16, v20, v16
	v_mul_f32_e32 v9, v8, v23
	v_fma_f32 v18, -v22, v9, v8
	v_fmac_f32_e32 v9, v18, v23
	v_fma_f32 v8, -v22, v9, v8
	v_div_fmas_f32 v8, v8, v23, v9
	v_lshlrev_b32_e32 v9, 16, v17
	v_mul_f32_e32 v18, 0xbfb8aa3b, v9
	v_exp_f32_e32 v18, v18
	v_and_b32_e32 v10, 0xffff0000, v10
	v_mul_f32_e32 v7, v7, v19
	v_div_fixup_f32 v8, v8, v20, v16
	v_mul_f32_e32 v8, v8, v10
	v_cvt_pk_bf16_f32 v16, v7, v8
	v_add_f32_e32 v7, 1.0, v18
	v_div_scale_f32 v8, s[0:1], v7, v7, v9
	v_rcp_f32_e32 v10, v8
	v_and_b32_e32 v17, 0xffff0000, v17
	v_mul_f32_e32 v21, 0xbfb8aa3b, v17
	v_exp_f32_e32 v21, v21
	v_fma_f32 v19, -v8, v10, 1.0
	v_fmac_f32_e32 v10, v19, v10
	v_div_scale_f32 v19, vcc, v9, v7, v9
	v_mul_f32_e32 v20, v19, v10
	v_fma_f32 v22, -v8, v20, v19
	v_fmac_f32_e32 v20, v22, v10
	v_fma_f32 v8, -v8, v20, v19
	v_add_f32_e32 v19, 1.0, v21
	v_div_scale_f32 v21, s[0:1], v19, v19, v17
	v_rcp_f32_e32 v22, v21
	v_div_fmas_f32 v8, v8, v10, v20
	v_div_fixup_f32 v7, v8, v7, v9
	v_lshlrev_b32_e32 v18, 16, v11
	v_fma_f32 v8, -v21, v22, 1.0
	v_fmac_f32_e32 v22, v8, v22
	v_div_scale_f32 v8, vcc, v17, v19, v17
	v_mul_f32_e32 v9, v8, v22
	v_fma_f32 v10, -v21, v9, v8
	v_fmac_f32_e32 v9, v10, v22
	v_fma_f32 v8, -v21, v9, v8
	v_div_fmas_f32 v8, v8, v22, v9
	v_and_b32_e32 v11, 0xffff0000, v11
	v_div_fixup_f32 v8, v8, v19, v17
	v_mul_f32_e32 v8, v8, v11
	v_or_b32_e32 v10, 8, v0
	v_mul_f32_e32 v7, v7, v18
	v_cvt_pk_bf16_f32 v17, v7, v8
	v_mad_u64_u32 v[8:9], s[0:1], v10, s46, v[2:3]
	v_add_u32_e32 v9, v13, v9
	v_lshl_add_u64 v[8:9], v[8:9], 0, s[64:65]
	v_lshl_add_u64 v[8:9], v[8:9], 0, v[176:177]
	v_add_co_u32_e32 v8, vcc, s52, v8
	v_mov_b32_e32 v7, v1
	s_nop 0
	v_addc_co_u32_e32 v9, vcc, 0, v9, vcc
	s_nop 1
	v_mov_b64_e32 v[18:19], v[104:105]
	v_mov_b64_e32 v[20:21], v[106:107]
	v_lshlrev_b64 v[6:7], 12, v[6:7]
	v_lshl_add_u64 v[6:7], v[4:5], 0, v[6:7]
	global_store_dwordx4 v[6:7], v[14:17], off
	s_waitcnt vmcnt(1)
	v_lshlrev_b32_e32 v11, 16, v18
	v_mul_f32_e32 v8, 0xbfb8aa3b, v11
	v_exp_f32_e32 v22, v8
	v_and_b32_e32 v18, 0xffff0000, v18
	v_mul_f32_e32 v24, 0xbfb8aa3b, v18
	v_exp_f32_e32 v24, v24
	v_add_f32_e32 v14, 1.0, v22
	v_div_scale_f32 v15, s[0:1], v14, v14, v11
	v_rcp_f32_e32 v16, v15
	ds_read_b128 v[6:9], v12 offset:2176
	v_fma_f32 v22, -v15, v16, 1.0
	v_fmac_f32_e32 v16, v22, v16
	v_div_scale_f32 v22, vcc, v11, v14, v11
	v_mul_f32_e32 v23, v22, v16
	v_fma_f32 v25, -v15, v23, v22
	v_fmac_f32_e32 v23, v25, v16
	v_fma_f32 v15, -v15, v23, v22
	v_add_f32_e32 v22, 1.0, v24
	v_div_scale_f32 v24, s[0:1], v22, v22, v18
	v_rcp_f32_e32 v25, v24
	v_div_fmas_f32 v15, v15, v16, v23
	v_div_fixup_f32 v11, v15, v14, v11
	s_waitcnt lgkmcnt(0)
; __device__ __forceinline__ void attn_unit(const bf16* __restrict__ P, unsigned short* __restrict__ Ob, int b, int h, int kvh, int qb, bool meta, int jt0, int ntl, float* part, unsigned* cnt, const float* __restrict__ qnw, const float2* __restrict__ rtab, char* lds) {
;     ...
;     for (int i = 0; i < 8; ++i) { const int cidx = lane + 64 * i, orow = cidx >> 4, c8 = (cidx & 15) * 8;
;       const u32x4 ov = *(const u32x4*)(stg + orow * 272 + c8 * 2);
;       const u32x4 gv = *(const u32x4*)(Pg + (grow0 + orow) * LD + 4096 + h * D + c8);
;       const unsigned ow[4] = {ov.x, ov.y, ov.z, ov.w}, gw[4] = {gv.x, gv.y, gv.z, gv.w}; unsigned res[4];
; #pragma unroll
;       for (int e = 0; e < 4; ++e) { const float o0 = __uint_as_float(ow[e] << 16), o1 = __uint_as_float(ow[e] & 0xffff0000u), g0 = __uint_as_float(gw[e] << 16), g1 = __uint_as_float(gw[e] & 0xffff0000u);
;         res[e] = cvtpk(o0 * (g0 / (1.f + __expf(-g0))), o1 * (g1 / (1.f + __expf(-g1)))); }
;       *(u32x4*)(Ob + (grow0 + orow) * 2048 + h * D + c8) = (u32x4){res[0], res[1], res[2], res[3]}; }
	v_lshlrev_b32_e32 v17, 16, v6
	v_fma_f32 v14, -v24, v25, 1.0
	v_fmac_f32_e32 v25, v14, v25
	v_div_scale_f32 v14, vcc, v18, v22, v18
	v_mul_f32_e32 v15, v14, v25
	v_fma_f32 v16, -v24, v15, v14
	v_fmac_f32_e32 v15, v16, v25
	v_fma_f32 v14, -v24, v15, v14
	v_div_fmas_f32 v14, v14, v25, v15
	v_lshlrev_b32_e32 v15, 16, v19
	v_mul_f32_e32 v16, 0xbfb8aa3b, v15
	v_exp_f32_e32 v16, v16
	v_and_b32_e32 v6, 0xffff0000, v6
	v_div_fixup_f32 v14, v14, v22, v18
	v_mul_f32_e32 v6, v14, v6
	v_mul_f32_e32 v11, v11, v17
	v_cvt_pk_bf16_f32 v14, v11, v6
	v_add_f32_e32 v6, 1.0, v16
	v_div_scale_f32 v11, s[0:1], v6, v6, v15
	v_rcp_f32_e32 v16, v11
	v_and_b32_e32 v18, 0xffff0000, v19
	v_mul_f32_e32 v23, 0xbfb8aa3b, v18
	v_exp_f32_e32 v23, v23
	v_fma_f32 v19, -v11, v16, 1.0
	v_fmac_f32_e32 v16, v19, v16
	v_div_scale_f32 v19, vcc, v15, v6, v15
	v_mul_f32_e32 v22, v19, v16
	v_fma_f32 v24, -v11, v22, v19
	v_fmac_f32_e32 v22, v24, v16
	v_fma_f32 v11, -v11, v22, v19
	v_add_f32_e32 v19, 1.0, v23
	v_div_scale_f32 v23, s[0:1], v19, v19, v18
	v_rcp_f32_e32 v24, v23
	v_div_fmas_f32 v11, v11, v16, v22
	v_div_fixup_f32 v6, v11, v6, v15
	v_lshlrev_b32_e32 v17, 16, v7
	v_fma_f32 v11, -v23, v24, 1.0
	v_fmac_f32_e32 v24, v11, v24
	v_div_scale_f32 v11, vcc, v18, v19, v18
	v_mul_f32_e32 v15, v11, v24
	v_fma_f32 v16, -v23, v15, v11
	v_fmac_f32_e32 v15, v16, v24
	v_fma_f32 v11, -v23, v15, v11
	v_lshlrev_b32_e32 v16, 16, v20
	v_div_fmas_f32 v11, v11, v24, v15
	v_mul_f32_e32 v15, 0xbfb8aa3b, v16
	v_mul_f32_e32 v6, v6, v17
	v_exp_f32_e32 v17, v15
	v_and_b32_e32 v7, 0xffff0000, v7
	v_div_fixup_f32 v11, v11, v19, v18
	v_mul_f32_e32 v7, v11, v7
	v_cvt_pk_bf16_f32 v15, v6, v7
	v_add_f32_e32 v6, 1.0, v17
	v_div_scale_f32 v7, s[0:1], v6, v6, v16
	v_rcp_f32_e32 v11, v7
	v_and_b32_e32 v18, 0xffff0000, v20
	v_mul_f32_e32 v22, 0xbfb8aa3b, v18
	v_exp_f32_e32 v22, v22
	v_fma_f32 v19, -v7, v11, 1.0
	v_fmac_f32_e32 v11, v19, v11
	v_div_scale_f32 v19, vcc, v16, v6, v16
	v_mul_f32_e32 v20, v19, v11
	v_fma_f32 v23, -v7, v20, v19
	v_fmac_f32_e32 v20, v23, v11
	v_fma_f32 v7, -v7, v20, v19
	v_add_f32_e32 v19, 1.0, v22
	v_div_scale_f32 v22, s[0:1], v19, v19, v18
	v_rcp_f32_e32 v23, v22
	v_div_fmas_f32 v7, v7, v11, v20
	v_div_fixup_f32 v6, v7, v6, v16
	v_lshlrev_b32_e32 v17, 16, v8
	v_fma_f32 v7, -v22, v23, 1.0
	v_fmac_f32_e32 v23, v7, v23
	v_div_scale_f32 v7, vcc, v18, v19, v18
	v_mul_f32_e32 v11, v7, v23
	v_fma_f32 v16, -v22, v11, v7
	v_fmac_f32_e32 v11, v16, v23
	v_fma_f32 v7, -v22, v11, v7
	v_div_fmas_f32 v7, v7, v23, v11
	v_lshlrev_b32_e32 v11, 16, v21
	v_mul_f32_e32 v16, 0xbfb8aa3b, v11
	v_mul_f32_e32 v6, v6, v17
	v_exp_f32_e32 v17, v16
	v_and_b32_e32 v8, 0xffff0000, v8
	v_div_fixup_f32 v7, v7, v19, v18
	v_mul_f32_e32 v7, v7, v8
	v_cvt_pk_bf16_f32 v16, v6, v7
	v_add_f32_e32 v6, 1.0, v17
	v_div_scale_f32 v7, s[0:1], v6, v6, v11
	v_rcp_f32_e32 v8, v7
	v_and_b32_e32 v18, 0xffff0000, v21
	v_mul_f32_e32 v21, 0xbfb8aa3b, v18
	v_exp_f32_e32 v21, v21
	v_fma_f32 v19, -v7, v8, 1.0
	v_fmac_f32_e32 v8, v19, v8
	v_div_scale_f32 v19, vcc, v11, v6, v11
	v_mul_f32_e32 v20, v19, v8
	v_fma_f32 v22, -v7, v20, v19
	v_fmac_f32_e32 v20, v22, v8
	v_fma_f32 v7, -v7, v20, v19
	v_add_f32_e32 v19, 1.0, v21
	v_div_scale_f32 v21, s[0:1], v19, v19, v18
	v_rcp_f32_e32 v22, v21
	v_div_fmas_f32 v7, v7, v8, v20
	v_div_fixup_f32 v6, v7, v6, v11
	v_lshlrev_b32_e32 v17, 16, v9
	v_fma_f32 v7, -v21, v22, 1.0
	v_fmac_f32_e32 v22, v7, v22
	v_div_scale_f32 v7, vcc, v18, v19, v18
	v_mul_f32_e32 v8, v7, v22
	v_fma_f32 v11, -v21, v8, v7
	v_fmac_f32_e32 v8, v11, v22
	v_fma_f32 v7, -v21, v8, v7
	v_div_fmas_f32 v7, v7, v22, v8
	v_and_b32_e32 v9, 0xffff0000, v9
	v_div_fixup_f32 v7, v7, v19, v18
	v_mul_f32_e32 v6, v6, v17
	v_mul_f32_e32 v7, v7, v9
	v_or_b32_e32 v8, 12, v0
	v_cvt_pk_bf16_f32 v17, v6, v7
	v_mad_u64_u32 v[6:7], s[0:1], v8, s46, v[2:3]
	v_add_u32_e32 v7, v13, v7
	v_lshl_add_u64 v[6:7], v[6:7], 0, s[64:65]
	v_lshl_add_u64 v[6:7], v[6:7], 0, v[176:177]
	v_add_co_u32_e32 v6, vcc, s52, v6
	v_mov_b32_e32 v11, v1
	s_nop 0
	v_addc_co_u32_e32 v7, vcc, 0, v7, vcc
	s_nop 1
	v_mov_b64_e32 v[18:19], v[108:109]
	v_mov_b64_e32 v[20:21], v[110:111]
	v_lshlrev_b64 v[6:7], 12, v[10:11]
	v_lshl_add_u64 v[6:7], v[4:5], 0, v[6:7]
	global_store_dwordx4 v[6:7], v[14:17], off
	ds_read_b128 v[14:17], v12 offset:3264
	s_waitcnt lgkmcnt(0)
	v_lshlrev_b32_e32 v11, 16, v14
	v_and_b32_e32 v14, 0xffff0000, v14
	s_waitcnt vmcnt(1)
; __device__ __forceinline__ void attn_unit(const bf16* __restrict__ P, unsigned short* __restrict__ Ob, int b, int h, int kvh, int qb, bool meta, int jt0, int ntl, float* part, unsigned* cnt, const float* __restrict__ qnw, const float2* __restrict__ rtab, char* lds) {
;     ...
;     for (int i = 0; i < 8; ++i) { const int cidx = lane + 64 * i, orow = cidx >> 4, c8 = (cidx & 15) * 8;
;       const u32x4 ov = *(const u32x4*)(stg + orow * 272 + c8 * 2);
;       const u32x4 gv = *(const u32x4*)(Pg + (grow0 + orow) * LD + 4096 + h * D + c8);
;       const unsigned ow[4] = {ov.x, ov.y, ov.z, ov.w}, gw[4] = {gv.x, gv.y, gv.z, gv.w}; unsigned res[4];
; #pragma unroll
;       for (int e = 0; e < 4; ++e) { const float o0 = __uint_as_float(ow[e] << 16), o1 = __uint_as_float(ow[e] & 0xffff0000u), g0 = __uint_as_float(gw[e] << 16), g1 = __uint_as_float(gw[e] & 0xffff0000u);
;         res[e] = cvtpk(o0 * (g0 / (1.f + __expf(-g0))), o1 * (g1 / (1.f + __expf(-g1)))); }
;       *(u32x4*)(Ob + (grow0 + orow) * 2048 + h * D + c8) = (u32x4){res[0], res[1], res[2], res[3]}; }
	v_lshlrev_b32_e32 v9, 16, v18
	v_mul_f32_e32 v10, 0xbfb8aa3b, v9
	v_exp_f32_e32 v10, v10
	v_and_b32_e32 v18, 0xffff0000, v18
	v_mul_f32_e32 v24, 0xbfb8aa3b, v18
	v_exp_f32_e32 v24, v24
	v_add_f32_e32 v6, 1.0, v10
	v_div_scale_f32 v7, s[0:1], v6, v6, v9
	v_rcp_f32_e32 v10, v7
	s_nop 0
	v_fma_f32 v22, -v7, v10, 1.0
	v_fmac_f32_e32 v10, v22, v10
	v_div_scale_f32 v22, vcc, v9, v6, v9
	v_mul_f32_e32 v23, v22, v10
	v_fma_f32 v25, -v7, v23, v22
	v_fmac_f32_e32 v23, v25, v10
	v_fma_f32 v7, -v7, v23, v22
	v_add_f32_e32 v22, 1.0, v24
	v_div_scale_f32 v24, s[0:1], v22, v22, v18
	v_rcp_f32_e32 v25, v24
	v_div_fmas_f32 v7, v7, v10, v23
	v_div_fixup_f32 v6, v7, v6, v9
	v_mul_f32_e32 v6, v6, v11
	v_fma_f32 v7, -v24, v25, 1.0
	v_fmac_f32_e32 v25, v7, v25
	v_div_scale_f32 v7, vcc, v18, v22, v18
	v_mul_f32_e32 v9, v7, v25
	v_fma_f32 v10, -v24, v9, v7
	v_fmac_f32_e32 v9, v10, v25
	v_fma_f32 v7, -v24, v9, v7
	v_div_fmas_f32 v7, v7, v25, v9
	v_lshlrev_b32_e32 v9, 16, v19
	v_mul_f32_e32 v10, 0xbfb8aa3b, v9
	v_exp_f32_e32 v10, v10
	v_div_fixup_f32 v7, v7, v22, v18
	v_mul_f32_e32 v7, v7, v14
	v_cvt_pk_bf16_f32 v14, v6, v7
	v_add_f32_e32 v6, 1.0, v10
	v_div_scale_f32 v7, s[0:1], v6, v6, v9
	v_rcp_f32_e32 v10, v7
	v_and_b32_e32 v18, 0xffff0000, v19
	v_mul_f32_e32 v23, 0xbfb8aa3b, v18
	v_exp_f32_e32 v23, v23
	v_fma_f32 v19, -v7, v10, 1.0
	v_fmac_f32_e32 v10, v19, v10
	v_div_scale_f32 v19, vcc, v9, v6, v9
	v_mul_f32_e32 v22, v19, v10
	v_fma_f32 v24, -v7, v22, v19
	v_fmac_f32_e32 v22, v24, v10
	v_fma_f32 v7, -v7, v22, v19
	v_add_f32_e32 v19, 1.0, v23
	v_div_scale_f32 v23, s[0:1], v19, v19, v18
	v_rcp_f32_e32 v24, v23
	v_div_fmas_f32 v7, v7, v10, v22
	v_div_fixup_f32 v6, v7, v6, v9
	v_lshlrev_b32_e32 v11, 16, v15
	v_fma_f32 v7, -v23, v24, 1.0
	v_fmac_f32_e32 v24, v7, v24
	v_div_scale_f32 v7, vcc, v18, v19, v18
	v_mul_f32_e32 v9, v7, v24
	v_fma_f32 v10, -v23, v9, v7
	v_fmac_f32_e32 v9, v10, v24
	v_fma_f32 v7, -v23, v9, v7
	v_div_fmas_f32 v7, v7, v24, v9
	v_lshlrev_b32_e32 v9, 16, v20
	v_mul_f32_e32 v10, 0xbfb8aa3b, v9
	v_exp_f32_e32 v10, v10
	v_and_b32_e32 v15, 0xffff0000, v15
	v_mul_f32_e32 v6, v6, v11
	v_div_fixup_f32 v7, v7, v19, v18
	v_mul_f32_e32 v7, v7, v15
	v_cvt_pk_bf16_f32 v15, v6, v7
	v_add_f32_e32 v6, 1.0, v10
	v_div_scale_f32 v7, s[0:1], v6, v6, v9
	v_rcp_f32_e32 v10, v7
	v_and_b32_e32 v18, 0xffff0000, v20
	v_mul_f32_e32 v22, 0xbfb8aa3b, v18
	v_exp_f32_e32 v22, v22
	v_fma_f32 v19, -v7, v10, 1.0
	v_fmac_f32_e32 v10, v19, v10
	v_div_scale_f32 v19, vcc, v9, v6, v9
	v_mul_f32_e32 v20, v19, v10
	v_fma_f32 v23, -v7, v20, v19
	v_fmac_f32_e32 v20, v23, v10
	v_fma_f32 v7, -v7, v20, v19
	v_add_f32_e32 v19, 1.0, v22
	v_div_scale_f32 v22, s[0:1], v19, v19, v18
	v_rcp_f32_e32 v23, v22
	v_div_fmas_f32 v7, v7, v10, v20
	v_div_fixup_f32 v6, v7, v6, v9
	v_lshlrev_b32_e32 v11, 16, v16
	v_fma_f32 v7, -v22, v23, 1.0
	v_fmac_f32_e32 v23, v7, v23
	v_div_scale_f32 v7, vcc, v18, v19, v18
	v_mul_f32_e32 v9, v7, v23
	v_fma_f32 v10, -v22, v9, v7
	v_fmac_f32_e32 v9, v10, v23
	v_fma_f32 v7, -v22, v9, v7
	v_div_fmas_f32 v7, v7, v23, v9
	v_lshlrev_b32_e32 v9, 16, v21
	v_mul_f32_e32 v10, 0xbfb8aa3b, v9
	v_exp_f32_e32 v10, v10
	v_and_b32_e32 v16, 0xffff0000, v16
	v_mul_f32_e32 v6, v6, v11
	v_div_fixup_f32 v7, v7, v19, v18
	v_mul_f32_e32 v7, v7, v16
	v_cvt_pk_bf16_f32 v16, v6, v7
	v_add_f32_e32 v6, 1.0, v10
	v_div_scale_f32 v7, s[0:1], v6, v6, v9
	v_rcp_f32_e32 v10, v7
	v_and_b32_e32 v18, 0xffff0000, v21
	v_mul_f32_e32 v21, 0xbfb8aa3b, v18
	v_exp_f32_e32 v21, v21
	v_fma_f32 v19, -v7, v10, 1.0
	v_fmac_f32_e32 v10, v19, v10
	v_div_scale_f32 v19, vcc, v9, v6, v9
	v_mul_f32_e32 v20, v19, v10
	v_fma_f32 v22, -v7, v20, v19
	v_fmac_f32_e32 v20, v22, v10
	v_fma_f32 v7, -v7, v20, v19
	v_add_f32_e32 v19, 1.0, v21
	v_div_scale_f32 v21, s[0:1], v19, v19, v18
	v_rcp_f32_e32 v22, v21
	v_div_fmas_f32 v7, v7, v10, v20
	v_div_fixup_f32 v6, v7, v6, v9
	v_lshlrev_b32_e32 v11, 16, v17
	v_fma_f32 v7, -v21, v22, 1.0
	v_fmac_f32_e32 v22, v7, v22
	v_div_scale_f32 v7, vcc, v18, v19, v18
	v_mul_f32_e32 v9, v7, v22
	v_fma_f32 v10, -v21, v9, v7
	v_fmac_f32_e32 v9, v10, v22
	v_fma_f32 v7, -v21, v9, v7
	v_div_fmas_f32 v7, v7, v22, v9
	v_and_b32_e32 v17, 0xffff0000, v17
	v_mul_f32_e32 v6, v6, v11
	v_div_fixup_f32 v7, v7, v19, v18
	v_mul_f32_e32 v7, v7, v17
	v_cvt_pk_bf16_f32 v17, v6, v7
	v_or_b32_e32 v6, 16, v0
	v_mad_u64_u32 v[10:11], s[0:1], v6, s46, v[2:3]
	v_add_u32_e32 v11, v13, v11
	v_lshl_add_u64 v[10:11], v[10:11], 0, s[64:65]
	v_lshl_add_u64 v[10:11], v[10:11], 0, v[176:177]
	v_add_co_u32_e32 v10, vcc, s52, v10
	v_mov_b32_e32 v9, v1
	s_nop 0
	v_addc_co_u32_e32 v11, vcc, 0, v11, vcc
	s_nop 1
	v_mov_b64_e32 v[18:19], v[112:113]
	v_mov_b64_e32 v[20:21], v[114:115]
	v_lshlrev_b64 v[8:9], 12, v[8:9]
	v_lshl_add_u64 v[8:9], v[4:5], 0, v[8:9]
	global_store_dwordx4 v[8:9], v[14:17], off
	s_waitcnt vmcnt(1)
	v_lshlrev_b32_e32 v7, 16, v18
	v_mul_f32_e32 v10, 0xbfb8aa3b, v7
	v_exp_f32_e32 v22, v10
	v_and_b32_e32 v18, 0xffff0000, v18
	v_mul_f32_e32 v24, 0xbfb8aa3b, v18
	v_exp_f32_e32 v24, v24
	v_add_f32_e32 v14, 1.0, v22
	v_div_scale_f32 v15, s[0:1], v14, v14, v7
	v_rcp_f32_e32 v16, v15
	ds_read_b128 v[8:11], v12 offset:4352
	v_fma_f32 v22, -v15, v16, 1.0
	v_fmac_f32_e32 v16, v22, v16
	v_div_scale_f32 v22, vcc, v7, v14, v7
	v_mul_f32_e32 v23, v22, v16
	v_fma_f32 v25, -v15, v23, v22
	v_fmac_f32_e32 v23, v25, v16
	v_fma_f32 v15, -v15, v23, v22
	v_add_f32_e32 v22, 1.0, v24
	v_div_scale_f32 v24, s[0:1], v22, v22, v18
	v_rcp_f32_e32 v25, v24
	v_div_fmas_f32 v15, v15, v16, v23
	v_div_fixup_f32 v7, v15, v14, v7
	s_waitcnt lgkmcnt(0)
; __device__ __forceinline__ void attn_unit(const bf16* __restrict__ P, unsigned short* __restrict__ Ob, int b, int h, int kvh, int qb, bool meta, int jt0, int ntl, float* part, unsigned* cnt, const float* __restrict__ qnw, const float2* __restrict__ rtab, char* lds) {
;     ...
;     for (int i = 0; i < 8; ++i) { const int cidx = lane + 64 * i, orow = cidx >> 4, c8 = (cidx & 15) * 8;
;       const u32x4 ov = *(const u32x4*)(stg + orow * 272 + c8 * 2);
;       const u32x4 gv = *(const u32x4*)(Pg + (grow0 + orow) * LD + 4096 + h * D + c8);
;       const unsigned ow[4] = {ov.x, ov.y, ov.z, ov.w}, gw[4] = {gv.x, gv.y, gv.z, gv.w}; unsigned res[4];
; #pragma unroll
;       for (int e = 0; e < 4; ++e) { const float o0 = __uint_as_float(ow[e] << 16), o1 = __uint_as_float(ow[e] & 0xffff0000u), g0 = __uint_as_float(gw[e] << 16), g1 = __uint_as_float(gw[e] & 0xffff0000u);
;         res[e] = cvtpk(o0 * (g0 / (1.f + __expf(-g0))), o1 * (g1 / (1.f + __expf(-g1)))); }
;       *(u32x4*)(Ob + (grow0 + orow) * 2048 + h * D + c8) = (u32x4){res[0], res[1], res[2], res[3]}; }
	v_lshlrev_b32_e32 v17, 16, v8
	v_fma_f32 v14, -v24, v25, 1.0
	v_fmac_f32_e32 v25, v14, v25
	v_div_scale_f32 v14, vcc, v18, v22, v18
	v_mul_f32_e32 v15, v14, v25
	v_fma_f32 v16, -v24, v15, v14
	v_fmac_f32_e32 v15, v16, v25
	v_fma_f32 v14, -v24, v15, v14
	v_div_fmas_f32 v14, v14, v25, v15
	v_lshlrev_b32_e32 v15, 16, v19
	v_mul_f32_e32 v16, 0xbfb8aa3b, v15
	v_exp_f32_e32 v16, v16
	v_and_b32_e32 v8, 0xffff0000, v8
	v_mul_f32_e32 v7, v7, v17
	v_div_fixup_f32 v14, v14, v22, v18
	v_mul_f32_e32 v8, v14, v8
	v_cvt_pk_bf16_f32 v14, v7, v8
	v_add_f32_e32 v7, 1.0, v16
	v_div_scale_f32 v8, s[0:1], v7, v7, v15
	v_rcp_f32_e32 v16, v8
	v_and_b32_e32 v18, 0xffff0000, v19
	v_mul_f32_e32 v23, 0xbfb8aa3b, v18
	v_exp_f32_e32 v23, v23
	v_fma_f32 v19, -v8, v16, 1.0
	v_fmac_f32_e32 v16, v19, v16
	v_div_scale_f32 v19, vcc, v15, v7, v15
	v_mul_f32_e32 v22, v19, v16
	v_fma_f32 v24, -v8, v22, v19
	v_fmac_f32_e32 v22, v24, v16
	v_fma_f32 v8, -v8, v22, v19
	v_add_f32_e32 v19, 1.0, v23
	v_div_scale_f32 v23, s[0:1], v19, v19, v18
	v_rcp_f32_e32 v24, v23
	v_div_fmas_f32 v8, v8, v16, v22
	v_div_fixup_f32 v7, v8, v7, v15
	v_lshlrev_b32_e32 v17, 16, v9
	v_fma_f32 v8, -v23, v24, 1.0
	v_fmac_f32_e32 v24, v8, v24
	v_div_scale_f32 v8, vcc, v18, v19, v18
	v_mul_f32_e32 v15, v8, v24
	v_fma_f32 v16, -v23, v15, v8
	v_fmac_f32_e32 v15, v16, v24
	v_fma_f32 v8, -v23, v15, v8
	v_lshlrev_b32_e32 v16, 16, v20
	v_div_fmas_f32 v8, v8, v24, v15
	v_mul_f32_e32 v15, 0xbfb8aa3b, v16
	v_mul_f32_e32 v7, v7, v17
	v_exp_f32_e32 v17, v15
	v_and_b32_e32 v9, 0xffff0000, v9
	v_div_fixup_f32 v8, v8, v19, v18
	v_mul_f32_e32 v8, v8, v9
	v_cvt_pk_bf16_f32 v15, v7, v8
	v_add_f32_e32 v7, 1.0, v17
	v_div_scale_f32 v8, s[0:1], v7, v7, v16
	v_rcp_f32_e32 v9, v8
	v_and_b32_e32 v18, 0xffff0000, v20
	v_mul_f32_e32 v22, 0xbfb8aa3b, v18
	v_exp_f32_e32 v22, v22
	v_fma_f32 v19, -v8, v9, 1.0
	v_fmac_f32_e32 v9, v19, v9
	v_div_scale_f32 v19, vcc, v16, v7, v16
	v_mul_f32_e32 v20, v19, v9
	v_fma_f32 v23, -v8, v20, v19
	v_fmac_f32_e32 v20, v23, v9
	v_fma_f32 v8, -v8, v20, v19
	v_add_f32_e32 v19, 1.0, v22
	v_div_scale_f32 v22, s[0:1], v19, v19, v18
	v_rcp_f32_e32 v23, v22
	v_div_fmas_f32 v8, v8, v9, v20
	v_div_fixup_f32 v7, v8, v7, v16
	v_lshlrev_b32_e32 v17, 16, v10
	v_fma_f32 v8, -v22, v23, 1.0
	v_fmac_f32_e32 v23, v8, v23
	v_div_scale_f32 v8, vcc, v18, v19, v18
	v_mul_f32_e32 v9, v8, v23
	v_fma_f32 v16, -v22, v9, v8
	v_fmac_f32_e32 v9, v16, v23
	v_fma_f32 v8, -v22, v9, v8
	v_div_fmas_f32 v8, v8, v23, v9
	v_lshlrev_b32_e32 v9, 16, v21
	v_mul_f32_e32 v16, 0xbfb8aa3b, v9
	v_mul_f32_e32 v7, v7, v17
	v_exp_f32_e32 v17, v16
	v_and_b32_e32 v10, 0xffff0000, v10
	v_div_fixup_f32 v8, v8, v19, v18
	v_mul_f32_e32 v8, v8, v10
	v_cvt_pk_bf16_f32 v16, v7, v8
	v_add_f32_e32 v7, 1.0, v17
	v_div_scale_f32 v8, s[0:1], v7, v7, v9
	v_rcp_f32_e32 v10, v8
	v_and_b32_e32 v18, 0xffff0000, v21
	v_mul_f32_e32 v21, 0xbfb8aa3b, v18
	v_exp_f32_e32 v21, v21
	v_fma_f32 v19, -v8, v10, 1.0
	v_fmac_f32_e32 v10, v19, v10
	v_div_scale_f32 v19, vcc, v9, v7, v9
	v_mul_f32_e32 v20, v19, v10
	v_fma_f32 v22, -v8, v20, v19
	v_fmac_f32_e32 v20, v22, v10
	v_fma_f32 v8, -v8, v20, v19
	v_add_f32_e32 v19, 1.0, v21
	v_div_scale_f32 v21, s[0:1], v19, v19, v18
	v_rcp_f32_e32 v22, v21
	v_div_fmas_f32 v8, v8, v10, v20
	v_div_fixup_f32 v7, v8, v7, v9
	v_lshlrev_b32_e32 v17, 16, v11
	v_fma_f32 v8, -v21, v22, 1.0
	v_fmac_f32_e32 v22, v8, v22
	v_div_scale_f32 v8, vcc, v18, v19, v18
	v_mul_f32_e32 v9, v8, v22
	v_fma_f32 v10, -v21, v9, v8
	v_fmac_f32_e32 v9, v10, v22
	v_fma_f32 v8, -v21, v9, v8
	v_div_fmas_f32 v8, v8, v22, v9
	v_and_b32_e32 v11, 0xffff0000, v11
	v_div_fixup_f32 v8, v8, v19, v18
	v_mul_f32_e32 v8, v8, v11
	v_mul_f32_e32 v7, v7, v17
	v_cvt_pk_bf16_f32 v17, v7, v8
	v_or_b32_e32 v8, 20, v0
	v_mad_u64_u32 v[10:11], s[0:1], v8, s46, v[2:3]
	v_add_u32_e32 v11, v13, v11
	v_lshl_add_u64 v[10:11], v[10:11], 0, s[64:65]
	v_lshl_add_u64 v[10:11], v[10:11], 0, v[176:177]
	v_add_co_u32_e32 v10, vcc, s52, v10
	v_mov_b32_e32 v7, v1
	s_nop 0
	v_addc_co_u32_e32 v11, vcc, 0, v11, vcc
	s_nop 1
	v_mov_b64_e32 v[18:19], v[116:117]
	v_mov_b64_e32 v[20:21], v[118:119]
	v_lshlrev_b64 v[6:7], 12, v[6:7]
	v_lshl_add_u64 v[6:7], v[4:5], 0, v[6:7]
	global_store_dwordx4 v[6:7], v[14:17], off
	ds_read_b128 v[14:17], v12 offset:5440
	s_waitcnt lgkmcnt(0)
	v_lshlrev_b32_e32 v11, 16, v14
	v_and_b32_e32 v14, 0xffff0000, v14
	s_waitcnt vmcnt(1)
; __device__ __forceinline__ void attn_unit(const bf16* __restrict__ P, unsigned short* __restrict__ Ob, int b, int h, int kvh, int qb, bool meta, int jt0, int ntl, float* part, unsigned* cnt, const float* __restrict__ qnw, const float2* __restrict__ rtab, char* lds) {
;     ...
;     for (int i = 0; i < 8; ++i) { const int cidx = lane + 64 * i, orow = cidx >> 4, c8 = (cidx & 15) * 8;
;       const u32x4 ov = *(const u32x4*)(stg + orow * 272 + c8 * 2);
;       const u32x4 gv = *(const u32x4*)(Pg + (grow0 + orow) * LD + 4096 + h * D + c8);
;       const unsigned ow[4] = {ov.x, ov.y, ov.z, ov.w}, gw[4] = {gv.x, gv.y, gv.z, gv.w}; unsigned res[4];
; #pragma unroll
;       for (int e = 0; e < 4; ++e) { const float o0 = __uint_as_float(ow[e] << 16), o1 = __uint_as_float(ow[e] & 0xffff0000u), g0 = __uint_as_float(gw[e] << 16), g1 = __uint_as_float(gw[e] & 0xffff0000u);
;         res[e] = cvtpk(o0 * (g0 / (1.f + __expf(-g0))), o1 * (g1 / (1.f + __expf(-g1)))); }
;       *(u32x4*)(Ob + (grow0 + orow) * 2048 + h * D + c8) = (u32x4){res[0], res[1], res[2], res[3]}; }
	v_lshlrev_b32_e32 v9, 16, v18
	v_mul_f32_e32 v10, 0xbfb8aa3b, v9
	v_exp_f32_e32 v10, v10
	v_and_b32_e32 v18, 0xffff0000, v18
	v_mul_f32_e32 v24, 0xbfb8aa3b, v18
	v_exp_f32_e32 v24, v24
	v_add_f32_e32 v6, 1.0, v10
	v_div_scale_f32 v7, s[0:1], v6, v6, v9
	v_rcp_f32_e32 v10, v7
	s_nop 0
	v_fma_f32 v22, -v7, v10, 1.0
	v_fmac_f32_e32 v10, v22, v10
	v_div_scale_f32 v22, vcc, v9, v6, v9
	v_mul_f32_e32 v23, v22, v10
	v_fma_f32 v25, -v7, v23, v22
	v_fmac_f32_e32 v23, v25, v10
	v_fma_f32 v7, -v7, v23, v22
	v_add_f32_e32 v22, 1.0, v24
	v_div_scale_f32 v24, s[0:1], v22, v22, v18
	v_rcp_f32_e32 v25, v24
	v_div_fmas_f32 v7, v7, v10, v23
	v_div_fixup_f32 v6, v7, v6, v9
	v_mul_f32_e32 v6, v6, v11
	v_fma_f32 v7, -v24, v25, 1.0
	v_fmac_f32_e32 v25, v7, v25
	v_div_scale_f32 v7, vcc, v18, v22, v18
	v_mul_f32_e32 v9, v7, v25
	v_fma_f32 v10, -v24, v9, v7
	v_fmac_f32_e32 v9, v10, v25
	v_fma_f32 v7, -v24, v9, v7
	v_div_fmas_f32 v7, v7, v25, v9
	v_lshlrev_b32_e32 v9, 16, v19
	v_mul_f32_e32 v10, 0xbfb8aa3b, v9
	v_exp_f32_e32 v10, v10
	v_div_fixup_f32 v7, v7, v22, v18
	v_mul_f32_e32 v7, v7, v14
	v_cvt_pk_bf16_f32 v14, v6, v7
	v_add_f32_e32 v6, 1.0, v10
	v_div_scale_f32 v7, s[0:1], v6, v6, v9
	v_rcp_f32_e32 v10, v7
	v_and_b32_e32 v18, 0xffff0000, v19
	v_mul_f32_e32 v23, 0xbfb8aa3b, v18
	v_exp_f32_e32 v23, v23
	v_fma_f32 v19, -v7, v10, 1.0
	v_fmac_f32_e32 v10, v19, v10
	v_div_scale_f32 v19, vcc, v9, v6, v9
	v_mul_f32_e32 v22, v19, v10
	v_fma_f32 v24, -v7, v22, v19
	v_fmac_f32_e32 v22, v24, v10
	v_fma_f32 v7, -v7, v22, v19
	v_add_f32_e32 v19, 1.0, v23
	v_div_scale_f32 v23, s[0:1], v19, v19, v18
	v_rcp_f32_e32 v24, v23
	v_div_fmas_f32 v7, v7, v10, v22
	v_div_fixup_f32 v6, v7, v6, v9
	v_lshlrev_b32_e32 v11, 16, v15
	v_fma_f32 v7, -v23, v24, 1.0
	v_fmac_f32_e32 v24, v7, v24
	v_div_scale_f32 v7, vcc, v18, v19, v18
	v_mul_f32_e32 v9, v7, v24
	v_fma_f32 v10, -v23, v9, v7
	v_fmac_f32_e32 v9, v10, v24
	v_fma_f32 v7, -v23, v9, v7
	v_div_fmas_f32 v7, v7, v24, v9
	v_lshlrev_b32_e32 v9, 16, v20
	v_mul_f32_e32 v10, 0xbfb8aa3b, v9
	v_exp_f32_e32 v10, v10
	v_and_b32_e32 v15, 0xffff0000, v15
	v_mul_f32_e32 v6, v6, v11
	v_div_fixup_f32 v7, v7, v19, v18
	v_mul_f32_e32 v7, v7, v15
	v_cvt_pk_bf16_f32 v15, v6, v7
	v_add_f32_e32 v6, 1.0, v10
	v_div_scale_f32 v7, s[0:1], v6, v6, v9
	v_rcp_f32_e32 v10, v7
	v_and_b32_e32 v18, 0xffff0000, v20
	v_mul_f32_e32 v22, 0xbfb8aa3b, v18
	v_exp_f32_e32 v22, v22
	v_fma_f32 v19, -v7, v10, 1.0
	v_fmac_f32_e32 v10, v19, v10
	v_div_scale_f32 v19, vcc, v9, v6, v9
	v_mul_f32_e32 v20, v19, v10
	v_fma_f32 v23, -v7, v20, v19
	v_fmac_f32_e32 v20, v23, v10
	v_fma_f32 v7, -v7, v20, v19
	v_add_f32_e32 v19, 1.0, v22
	v_div_scale_f32 v22, s[0:1], v19, v19, v18
	v_rcp_f32_e32 v23, v22
	v_div_fmas_f32 v7, v7, v10, v20
	v_div_fixup_f32 v6, v7, v6, v9
	v_lshlrev_b32_e32 v11, 16, v16
	v_fma_f32 v7, -v22, v23, 1.0
	v_fmac_f32_e32 v23, v7, v23
	v_div_scale_f32 v7, vcc, v18, v19, v18
	v_mul_f32_e32 v9, v7, v23
	v_fma_f32 v10, -v22, v9, v7
	v_fmac_f32_e32 v9, v10, v23
	v_fma_f32 v7, -v22, v9, v7
	v_div_fmas_f32 v7, v7, v23, v9
	v_lshlrev_b32_e32 v9, 16, v21
	v_mul_f32_e32 v10, 0xbfb8aa3b, v9
	v_exp_f32_e32 v10, v10
	v_and_b32_e32 v16, 0xffff0000, v16
	v_mul_f32_e32 v6, v6, v11
	v_div_fixup_f32 v7, v7, v19, v18
	v_mul_f32_e32 v7, v7, v16
	v_cvt_pk_bf16_f32 v16, v6, v7
	v_add_f32_e32 v6, 1.0, v10
	v_div_scale_f32 v7, s[0:1], v6, v6, v9
	v_rcp_f32_e32 v10, v7
	v_and_b32_e32 v18, 0xffff0000, v21
	v_mul_f32_e32 v21, 0xbfb8aa3b, v18
	v_exp_f32_e32 v21, v21
	v_fma_f32 v19, -v7, v10, 1.0
	v_fmac_f32_e32 v10, v19, v10
	v_div_scale_f32 v19, vcc, v9, v6, v9
	v_mul_f32_e32 v20, v19, v10
	v_fma_f32 v22, -v7, v20, v19
	v_fmac_f32_e32 v20, v22, v10
	v_fma_f32 v7, -v7, v20, v19
	v_add_f32_e32 v19, 1.0, v21
	v_div_scale_f32 v21, s[0:1], v19, v19, v18
	v_rcp_f32_e32 v22, v21
	v_div_fmas_f32 v7, v7, v10, v20
	v_div_fixup_f32 v6, v7, v6, v9
	v_lshlrev_b32_e32 v11, 16, v17
	v_fma_f32 v7, -v21, v22, 1.0
	v_fmac_f32_e32 v22, v7, v22
	v_div_scale_f32 v7, vcc, v18, v19, v18
	v_mul_f32_e32 v9, v7, v22
	v_fma_f32 v10, -v21, v9, v7
	v_fmac_f32_e32 v9, v10, v22
	v_fma_f32 v7, -v21, v9, v7
	v_div_fmas_f32 v7, v7, v22, v9
	v_and_b32_e32 v17, 0xffff0000, v17
	v_mul_f32_e32 v6, v6, v11
	v_div_fixup_f32 v7, v7, v19, v18
	v_mul_f32_e32 v7, v7, v17
	v_cvt_pk_bf16_f32 v17, v6, v7
	v_or_b32_e32 v6, 24, v0
	v_mad_u64_u32 v[10:11], s[0:1], v6, s46, v[2:3]
	v_add_u32_e32 v11, v13, v11
	v_lshl_add_u64 v[10:11], v[10:11], 0, s[64:65]
	v_lshl_add_u64 v[10:11], v[10:11], 0, v[176:177]
	v_add_co_u32_e32 v10, vcc, s52, v10
	v_mov_b32_e32 v9, v1
	s_nop 0
	v_addc_co_u32_e32 v11, vcc, 0, v11, vcc
	s_nop 1
	v_mov_b64_e32 v[18:19], v[120:121]
	v_mov_b64_e32 v[20:21], v[122:123]
	v_lshlrev_b64 v[8:9], 12, v[8:9]
	v_lshl_add_u64 v[8:9], v[4:5], 0, v[8:9]
	global_store_dwordx4 v[8:9], v[14:17], off
	v_or_b32_e32 v0, 28, v0
	v_mad_u64_u32 v[2:3], s[0:1], v0, s46, v[2:3]
	v_add_u32_e32 v3, v13, v3
	v_lshl_add_u64 v[2:3], v[2:3], 0, s[64:65]
	v_lshl_add_u64 v[2:3], v[2:3], 0, v[176:177]
	s_waitcnt vmcnt(1)
	v_lshlrev_b32_e32 v7, 16, v18
	v_mul_f32_e32 v10, 0xbfb8aa3b, v7
	v_exp_f32_e32 v22, v10
	v_and_b32_e32 v18, 0xffff0000, v18
	v_mul_f32_e32 v24, 0xbfb8aa3b, v18
	v_exp_f32_e32 v24, v24
	v_add_f32_e32 v14, 1.0, v22
	v_div_scale_f32 v15, s[0:1], v14, v14, v7
	v_rcp_f32_e32 v16, v15
	ds_read_b128 v[8:11], v12 offset:6528
	v_fma_f32 v22, -v15, v16, 1.0
	v_fmac_f32_e32 v16, v22, v16
	v_div_scale_f32 v22, vcc, v7, v14, v7
	v_mul_f32_e32 v23, v22, v16
	v_fma_f32 v25, -v15, v23, v22
	v_fmac_f32_e32 v23, v25, v16
	v_fma_f32 v15, -v15, v23, v22
	v_add_f32_e32 v22, 1.0, v24
	v_div_scale_f32 v24, s[0:1], v22, v22, v18
	v_rcp_f32_e32 v25, v24
	v_div_fmas_f32 v15, v15, v16, v23
	v_div_fixup_f32 v7, v15, v14, v7
	s_waitcnt lgkmcnt(0)
; __device__ __forceinline__ void attn_unit(const bf16* __restrict__ P, unsigned short* __restrict__ Ob, int b, int h, int kvh, int qb, bool meta, int jt0, int ntl, float* part, unsigned* cnt, const float* __restrict__ qnw, const float2* __restrict__ rtab, char* lds) {
;     ...
;     for (int i = 0; i < 8; ++i) { const int cidx = lane + 64 * i, orow = cidx >> 4, c8 = (cidx & 15) * 8;
;       const u32x4 ov = *(const u32x4*)(stg + orow * 272 + c8 * 2);
;       const u32x4 gv = *(const u32x4*)(Pg + (grow0 + orow) * LD + 4096 + h * D + c8);
;       const unsigned ow[4] = {ov.x, ov.y, ov.z, ov.w}, gw[4] = {gv.x, gv.y, gv.z, gv.w}; unsigned res[4];
; #pragma unroll
;       for (int e = 0; e < 4; ++e) { const float o0 = __uint_as_float(ow[e] << 16), o1 = __uint_as_float(ow[e] & 0xffff0000u), g0 = __uint_as_float(gw[e] << 16), g1 = __uint_as_float(gw[e] & 0xffff0000u);
;         res[e] = cvtpk(o0 * (g0 / (1.f + __expf(-g0))), o1 * (g1 / (1.f + __expf(-g1)))); }
;       *(u32x4*)(Ob + (grow0 + orow) * 2048 + h * D + c8) = (u32x4){res[0], res[1], res[2], res[3]}; }
	v_lshlrev_b32_e32 v17, 16, v8
	v_fma_f32 v14, -v24, v25, 1.0
	v_fmac_f32_e32 v25, v14, v25
	v_div_scale_f32 v14, vcc, v18, v22, v18
	v_mul_f32_e32 v15, v14, v25
	v_fma_f32 v16, -v24, v15, v14
	v_fmac_f32_e32 v15, v16, v25
	v_fma_f32 v14, -v24, v15, v14
	v_div_fmas_f32 v14, v14, v25, v15
	v_lshlrev_b32_e32 v15, 16, v19
	v_mul_f32_e32 v16, 0xbfb8aa3b, v15
	v_exp_f32_e32 v16, v16
	v_and_b32_e32 v8, 0xffff0000, v8
	v_div_fixup_f32 v14, v14, v22, v18
	v_mul_f32_e32 v7, v7, v17
	v_mul_f32_e32 v8, v14, v8
	v_cvt_pk_bf16_f32 v8, v7, v8
	v_add_f32_e32 v7, 1.0, v16
	v_div_scale_f32 v14, s[0:1], v7, v7, v15
	v_rcp_f32_e32 v16, v14
	v_and_b32_e32 v18, 0xffff0000, v19
	v_mul_f32_e32 v23, 0xbfb8aa3b, v18
	v_exp_f32_e32 v23, v23
	v_fma_f32 v19, -v14, v16, 1.0
	v_fmac_f32_e32 v16, v19, v16
	v_div_scale_f32 v19, vcc, v15, v7, v15
	v_mul_f32_e32 v22, v19, v16
	v_fma_f32 v24, -v14, v22, v19
	v_fmac_f32_e32 v22, v24, v16
	v_fma_f32 v14, -v14, v22, v19
	v_add_f32_e32 v19, 1.0, v23
	v_div_scale_f32 v23, s[0:1], v19, v19, v18
	v_rcp_f32_e32 v24, v23
	v_div_fmas_f32 v14, v14, v16, v22
	v_div_fixup_f32 v7, v14, v7, v15
	v_lshlrev_b32_e32 v17, 16, v9
	v_fma_f32 v14, -v23, v24, 1.0
	v_fmac_f32_e32 v24, v14, v24
	v_div_scale_f32 v14, vcc, v18, v19, v18
	v_mul_f32_e32 v15, v14, v24
	v_fma_f32 v16, -v23, v15, v14
	v_fmac_f32_e32 v15, v16, v24
	v_fma_f32 v14, -v23, v15, v14
	v_div_fmas_f32 v14, v14, v24, v15
	v_lshlrev_b32_e32 v15, 16, v20
	v_mul_f32_e32 v16, 0xbfb8aa3b, v15
	v_exp_f32_e32 v16, v16
	v_and_b32_e32 v9, 0xffff0000, v9
	v_div_fixup_f32 v14, v14, v19, v18
	v_mul_f32_e32 v7, v7, v17
	v_mul_f32_e32 v9, v14, v9
	v_cvt_pk_bf16_f32 v9, v7, v9
	v_add_f32_e32 v7, 1.0, v16
	v_div_scale_f32 v14, s[0:1], v7, v7, v15
	v_rcp_f32_e32 v16, v14
	v_and_b32_e32 v18, 0xffff0000, v20
	v_mul_f32_e32 v22, 0xbfb8aa3b, v18
	v_exp_f32_e32 v22, v22
	v_fma_f32 v19, -v14, v16, 1.0
	v_fmac_f32_e32 v16, v19, v16
	v_div_scale_f32 v19, vcc, v15, v7, v15
	v_mul_f32_e32 v20, v19, v16
	v_fma_f32 v23, -v14, v20, v19
	v_fmac_f32_e32 v20, v23, v16
	v_fma_f32 v14, -v14, v20, v19
	v_add_f32_e32 v19, 1.0, v22
	v_div_scale_f32 v22, s[0:1], v19, v19, v18
	v_rcp_f32_e32 v23, v22
	v_div_fmas_f32 v14, v14, v16, v20
	v_div_fixup_f32 v7, v14, v7, v15
	v_lshlrev_b32_e32 v17, 16, v10
	v_fma_f32 v14, -v22, v23, 1.0
	v_fmac_f32_e32 v23, v14, v23
	v_div_scale_f32 v14, vcc, v18, v19, v18
	v_mul_f32_e32 v15, v14, v23
	v_fma_f32 v16, -v22, v15, v14
	v_fmac_f32_e32 v15, v16, v23
	v_fma_f32 v14, -v22, v15, v14
	v_div_fmas_f32 v14, v14, v23, v15
	v_lshlrev_b32_e32 v15, 16, v21
	v_mul_f32_e32 v16, 0xbfb8aa3b, v15
	v_exp_f32_e32 v16, v16
	v_and_b32_e32 v10, 0xffff0000, v10
	v_div_fixup_f32 v14, v14, v19, v18
	v_mul_f32_e32 v7, v7, v17
	v_mul_f32_e32 v10, v14, v10
	v_cvt_pk_bf16_f32 v10, v7, v10
	v_add_f32_e32 v7, 1.0, v16
	v_div_scale_f32 v14, s[0:1], v7, v7, v15
	v_rcp_f32_e32 v16, v14
	v_and_b32_e32 v18, 0xffff0000, v21
	v_mul_f32_e32 v21, 0xbfb8aa3b, v18
	v_exp_f32_e32 v21, v21
	v_fma_f32 v19, -v14, v16, 1.0
	v_fmac_f32_e32 v16, v19, v16
	v_div_scale_f32 v19, vcc, v15, v7, v15
	v_mul_f32_e32 v20, v19, v16
	v_fma_f32 v22, -v14, v20, v19
	v_fmac_f32_e32 v20, v22, v16
	v_fma_f32 v14, -v14, v20, v19
	v_add_f32_e32 v19, 1.0, v21
	v_div_scale_f32 v21, s[0:1], v19, v19, v18
	v_rcp_f32_e32 v22, v21
	v_div_fmas_f32 v14, v14, v16, v20
	v_div_fixup_f32 v7, v14, v7, v15
	v_lshlrev_b32_e32 v17, 16, v11
	v_fma_f32 v14, -v21, v22, 1.0
	v_fmac_f32_e32 v22, v14, v22
	v_div_scale_f32 v14, vcc, v18, v19, v18
	v_mul_f32_e32 v15, v14, v22
	v_fma_f32 v16, -v21, v15, v14
	v_fmac_f32_e32 v15, v16, v22
	v_fma_f32 v14, -v21, v15, v14
	v_div_fmas_f32 v14, v14, v22, v15
	v_and_b32_e32 v11, 0xffff0000, v11
	v_div_fixup_f32 v14, v14, v19, v18
	v_add_co_u32_e32 v2, vcc, s52, v2
	v_mul_f32_e32 v11, v14, v11
	s_nop 0
	v_addc_co_u32_e32 v3, vcc, 0, v3, vcc
	v_mul_f32_e32 v7, v7, v17
	v_cvt_pk_bf16_f32 v11, v7, v11
	s_nop 1
	v_mov_b64_e32 v[14:15], v[124:125]
	v_mov_b64_e32 v[16:17], v[126:127]
	v_mov_b32_e32 v7, v1
	v_lshlrev_b64 v[2:3], 12, v[6:7]
	v_lshl_add_u64 v[2:3], v[4:5], 0, v[2:3]
	global_store_dwordx4 v[2:3], v[8:11], off
	v_lshlrev_b64 v[0:1], 12, v[0:1]
	v_lshl_add_u64 v[0:1], v[4:5], 0, v[0:1]
	s_waitcnt vmcnt(1)
; __device__ __forceinline__ void attn_unit(const bf16* __restrict__ P, unsigned short* __restrict__ Ob, int b, int h, int kvh, int qb, bool meta, int jt0, int ntl, float* part, unsigned* cnt, const float* __restrict__ qnw, const float2* __restrict__ rtab, char* lds) {
;     ...
;     for (int i = 0; i < 8; ++i) { const int cidx = lane + 64 * i, orow = cidx >> 4, c8 = (cidx & 15) * 8;
;       const u32x4 ov = *(const u32x4*)(stg + orow * 272 + c8 * 2);
;       const u32x4 gv = *(const u32x4*)(Pg + (grow0 + orow) * LD + 4096 + h * D + c8);
;       const unsigned ow[4] = {ov.x, ov.y, ov.z, ov.w}, gw[4] = {gv.x, gv.y, gv.z, gv.w}; unsigned res[4];
; #pragma unroll
;       for (int e = 0; e < 4; ++e) { const float o0 = __uint_as_float(ow[e] << 16), o1 = __uint_as_float(ow[e] & 0xffff0000u), g0 = __uint_as_float(gw[e] << 16), g1 = __uint_as_float(gw[e] & 0xffff0000u);
;         res[e] = cvtpk(o0 * (g0 / (1.f + __expf(-g0))), o1 * (g1 / (1.f + __expf(-g1)))); }
;       *(u32x4*)(Ob + (grow0 + orow) * 2048 + h * D + c8) = (u32x4){res[0], res[1], res[2], res[3]}; }
;     ...
;   __syncthreads();
	v_lshlrev_b32_e32 v13, 16, v14
	v_mul_f32_e32 v6, 0xbfb8aa3b, v13
	v_exp_f32_e32 v18, v6
	ds_read_b128 v[6:9], v12 offset:7616
	v_and_b32_e32 v12, 0xffff0000, v14
	v_mul_f32_e32 v19, 0xbfb8aa3b, v12
	v_add_f32_e32 v2, 1.0, v18
	v_div_scale_f32 v3, s[0:1], v2, v2, v13
	v_rcp_f32_e32 v10, v3
	v_exp_f32_e32 v19, v19
	s_waitcnt lgkmcnt(0)
	v_lshlrev_b32_e32 v11, 16, v6
	v_and_b32_e32 v6, 0xffff0000, v6
	v_fma_f32 v14, -v3, v10, 1.0
	v_fmac_f32_e32 v10, v14, v10
	v_div_scale_f32 v14, vcc, v13, v2, v13
	v_mul_f32_e32 v18, v14, v10
	v_fma_f32 v20, -v3, v18, v14
	v_fmac_f32_e32 v18, v20, v10
	v_fma_f32 v3, -v3, v18, v14
	v_add_f32_e32 v14, 1.0, v19
	v_div_scale_f32 v19, s[0:1], v14, v14, v12
	v_rcp_f32_e32 v20, v19
	v_div_fmas_f32 v3, v3, v10, v18
	v_div_fixup_f32 v2, v3, v2, v13
	v_mul_f32_e32 v2, v2, v11
	v_fma_f32 v3, -v19, v20, 1.0
	v_fmac_f32_e32 v20, v3, v20
	v_div_scale_f32 v3, vcc, v12, v14, v12
	v_mul_f32_e32 v10, v3, v20
	v_fma_f32 v11, -v19, v10, v3
	v_fmac_f32_e32 v10, v11, v20
	v_fma_f32 v3, -v19, v10, v3
	v_div_fmas_f32 v3, v3, v20, v10
	v_lshlrev_b32_e32 v10, 16, v15
	v_mul_f32_e32 v11, 0xbfb8aa3b, v10
	v_exp_f32_e32 v11, v11
	v_div_fixup_f32 v3, v3, v14, v12
	v_mul_f32_e32 v3, v3, v6
	v_cvt_pk_bf16_f32 v6, v2, v3
	v_add_f32_e32 v2, 1.0, v11
	v_div_scale_f32 v3, s[0:1], v2, v2, v10
	v_rcp_f32_e32 v11, v3
	v_and_b32_e32 v13, 0xffff0000, v15
	v_mul_f32_e32 v18, 0xbfb8aa3b, v13
	v_exp_f32_e32 v18, v18
	v_fma_f32 v14, -v3, v11, 1.0
	v_fmac_f32_e32 v11, v14, v11
	v_div_scale_f32 v14, vcc, v10, v2, v10
	v_mul_f32_e32 v15, v14, v11
	v_fma_f32 v19, -v3, v15, v14
	v_fmac_f32_e32 v15, v19, v11
	v_fma_f32 v3, -v3, v15, v14
	v_add_f32_e32 v14, 1.0, v18
	v_div_scale_f32 v18, s[0:1], v14, v14, v13
	v_rcp_f32_e32 v19, v18
	v_div_fmas_f32 v3, v3, v11, v15
	v_div_fixup_f32 v2, v3, v2, v10
	v_lshlrev_b32_e32 v12, 16, v7
	v_fma_f32 v3, -v18, v19, 1.0
	v_fmac_f32_e32 v19, v3, v19
	v_div_scale_f32 v3, vcc, v13, v14, v13
	v_mul_f32_e32 v10, v3, v19
	v_fma_f32 v11, -v18, v10, v3
	v_fmac_f32_e32 v10, v11, v19
	v_fma_f32 v3, -v18, v10, v3
	v_div_fmas_f32 v3, v3, v19, v10
	v_lshlrev_b32_e32 v10, 16, v16
	v_mul_f32_e32 v11, 0xbfb8aa3b, v10
	v_exp_f32_e32 v11, v11
	v_and_b32_e32 v7, 0xffff0000, v7
	v_mul_f32_e32 v2, v2, v12
	v_div_fixup_f32 v3, v3, v14, v13
	v_mul_f32_e32 v3, v3, v7
	v_cvt_pk_bf16_f32 v7, v2, v3
	v_add_f32_e32 v2, 1.0, v11
	v_div_scale_f32 v3, s[0:1], v2, v2, v10
	v_rcp_f32_e32 v11, v3
	v_and_b32_e32 v13, 0xffff0000, v16
	v_mul_f32_e32 v16, 0xbfb8aa3b, v13
	v_exp_f32_e32 v16, v16
	v_fma_f32 v14, -v3, v11, 1.0
	v_fmac_f32_e32 v11, v14, v11
	v_div_scale_f32 v14, vcc, v10, v2, v10
	v_mul_f32_e32 v15, v14, v11
	v_fma_f32 v18, -v3, v15, v14
	v_fmac_f32_e32 v15, v18, v11
	v_fma_f32 v3, -v3, v15, v14
	v_add_f32_e32 v14, 1.0, v16
	v_div_scale_f32 v16, s[0:1], v14, v14, v13
	v_rcp_f32_e32 v18, v16
	v_div_fmas_f32 v3, v3, v11, v15
	v_div_fixup_f32 v2, v3, v2, v10
	v_lshlrev_b32_e32 v12, 16, v8
	v_fma_f32 v3, -v16, v18, 1.0
	v_fmac_f32_e32 v18, v3, v18
	v_div_scale_f32 v3, vcc, v13, v14, v13
	v_mul_f32_e32 v10, v3, v18
	v_fma_f32 v11, -v16, v10, v3
	v_fmac_f32_e32 v10, v11, v18
	v_fma_f32 v3, -v16, v10, v3
	v_div_fmas_f32 v3, v3, v18, v10
	v_lshlrev_b32_e32 v10, 16, v17
	v_mul_f32_e32 v11, 0xbfb8aa3b, v10
	v_exp_f32_e32 v11, v11
	v_and_b32_e32 v8, 0xffff0000, v8
	v_mul_f32_e32 v2, v2, v12
	v_div_fixup_f32 v3, v3, v14, v13
	v_mul_f32_e32 v3, v3, v8
	v_cvt_pk_bf16_f32 v8, v2, v3
	v_add_f32_e32 v2, 1.0, v11
	v_div_scale_f32 v3, s[0:1], v2, v2, v10
	v_rcp_f32_e32 v11, v3
	v_and_b32_e32 v13, 0xffff0000, v17
	v_mul_f32_e32 v16, 0xbfb8aa3b, v13
	v_exp_f32_e32 v16, v16
	v_fma_f32 v14, -v3, v11, 1.0
	v_fmac_f32_e32 v11, v14, v11
	v_div_scale_f32 v14, vcc, v10, v2, v10
	v_mul_f32_e32 v15, v14, v11
	v_fma_f32 v17, -v3, v15, v14
	v_fmac_f32_e32 v15, v17, v11
	v_fma_f32 v3, -v3, v15, v14
	v_add_f32_e32 v14, 1.0, v16
	v_div_scale_f32 v16, s[0:1], v14, v14, v13
	v_rcp_f32_e32 v17, v16
	v_div_fmas_f32 v3, v3, v11, v15
	v_div_fixup_f32 v2, v3, v2, v10
	v_lshlrev_b32_e32 v12, 16, v9
	v_fma_f32 v3, -v16, v17, 1.0
	v_fmac_f32_e32 v17, v3, v17
	v_div_scale_f32 v3, vcc, v13, v14, v13
	v_mul_f32_e32 v10, v3, v17
	v_fma_f32 v11, -v16, v10, v3
	v_fmac_f32_e32 v10, v11, v17
	v_fma_f32 v3, -v16, v10, v3
	v_div_fmas_f32 v3, v3, v17, v10
	v_and_b32_e32 v9, 0xffff0000, v9
	v_div_fixup_f32 v3, v3, v14, v13
	v_mul_f32_e32 v2, v2, v12
	v_mul_f32_e32 v3, v3, v9
	v_cvt_pk_bf16_f32 v9, v2, v3
	global_store_dwordx4 v[0:1], v[6:9], off
	s_barrier

; #define LAS __attribute__((address_space(3)))
; __device__ __forceinline__ void xcd_barrier(const XcdBarrier& b) {
;     ...
;             asm volatile("s_waitcnt vmcnt(0)" ::: "memory");
;         }
;     }
;     __syncthreads();
; template <int PH>
; __device__ __forceinline__ void run_phase(Ctx& c, LAS unsigned char* lds, char* lds_generic) {
;     ...
;             constexpr int n_meta = 2 * (NFULL / 32), n_lr = (k == 1 && !attn) ? NREAL / 32 : 0;
;             const int r32 = c.lane & 31, hi = c.lane >> 5;
;             LAS float* RED = (LAS float*)lds;
;             for (int t = blockIdx.x; t < n_meta + n_lr; t += c.G) {
;                 const int row0 = t < n_meta ? NREAL + 32 * (t & 1) : 32 * (t - n_meta), col0 = t < n_meta ? 32 * (t >> 1) : ATT_N;
;                 const bf16_t* ap = Ap + (size_t)(row0 + r32) * DM + c.wave * 256 + hi * 64; const bf16_t* bp = Bp + (size_t)(col0 + r32) * DM + c.wave * 256 + hi * 64;
.LBB0_1340:
	s_or_b64 exec, exec, s[2:3]
	s_waitcnt lgkmcnt(0)
	s_barrier
	s_nop 0
	s_nop 0
	s_nop 0
	s_nop 0
	s_nop 0
	s_nop 0
	s_nop 0
	s_nop 0
	s_nop 0
	s_nop 0
	s_nop 0
	s_nop 0
	s_nop 0
	s_nop 0
.LBB0_1341:
	s_cmp_lt_i32 s74, 22
	s_cselect_b64 s[0:1], -1, 0
	s_cmp_gt_i32 s75, 21
	s_cselect_b64 s[2:3], -1, 0
	s_and_b64 s[0:1], s[0:1], s[2:3]
	s_andn2_b64 vcc, exec, s[0:1]
	s_cbranch_vccnz .LBB0_1423
	s_add_u32 s38, s72, 0x2200000
	s_addc_u32 s39, s73, 0
	s_add_u32 s40, s72, 0x1a00000
	s_addc_u32 s41, s73, 0
	s_add_u32 s4, s72, 0x12500000
	v_mov_b32_e32 v0, v200
	s_addc_u32 s5, s73, 0
	s_cmpk_gt_i32 s76, 0x7f
	v_readfirstlane_b32 s0, v0
	s_cbranch_scc1 .LBB0_1345
	s_ashr_i32 s6, s0, 6
	s_lshl_b32 s0, s6, 8
	s_ashr_i32 s1, s0, 31
	s_lshl_b64 s[0:1], s[0:1], 1
	s_add_u32 s2, s38, s0
	s_waitcnt vmcnt(0)
	v_and_b32_e32 v24, 31, v0
	v_bfe_u32 v1, v0, 5, 1
	s_addc_u32 s3, s39, s1
	v_lshlrev_b32_e32 v2, 9, v1
	v_lshlrev_b32_e32 v3, 2, v24
	v_lshlrev_b32_e32 v16, 7, v1
	v_mov_b32_e32 v17, 0
	s_add_u32 s0, s40, s0
	v_add3_u32 v2, 0, v2, v3
	v_lshl_add_u64 v[18:19], s[2:3], 0, v[16:17]
	s_addc_u32 s1, s41, s1
	s_lshl_b32 s2, s6, 12
	v_lshlrev_b32_e32 v1, 1, v0
	v_lshl_add_u32 v25, v0, 3, 0
	v_ashrrev_i32_e32 v26, 4, v0
	v_and_b32_e32 v0, 30, v1
	v_add_u32_e32 v27, s2, v2
	v_lshl_add_u64 v[20:21], s[0:1], 0, v[16:17]
	s_lshl_b32 s0, s76, 4
	s_lshl_b32 s1, s63, 4
	s_lshl_b32 s6, s76, 5
	s_lshl_b32 s7, s63, 5
	v_lshlrev_b32_e32 v22, 1, v0
	v_mov_b32_e32 v23, v17
	v_add_u32_e32 v28, 0x400, v27
	v_add_u32_e32 v29, 0x800, v27
	v_add_u32_e32 v30, 0xc00, v27
	s_mov_b32 s8, s76

; #define LAS __attribute__((address_space(3)))
; __global__ void __launch_bounds__(512, 2) fwd_kernel(Args args) {
;     extern __shared__ __attribute__((aligned(16))) unsigned char lds_raw[];
;     LAS unsigned char* lds = (LAS unsigned char*)lds_raw;
;     Ctx c;
;     c.x = args.in[0]; c.meta_tokens = args.in[1]; c.pre_norm = args.in[2]; c.post_norm = args.in[3]; c.attn_w_in = args.in[4]; c.attn_q_norm = args.in[5]; c.attn_k_norm = args.in[6];
;     c.attn_w_out = args.in[7]; c.gla_w_in = args.in[8]; c.gla_gk_up = args.in[9]; c.gla_gk_bias = args.in[10]; c.gla_o_norm = args.in[11]; c.gla_w_out = args.in[12];
;     c.out = args.out; c.ws = args.ws;
;     c.tid = threadIdx.x; c.lane = c.tid & 63; c.wave = __builtin_amdgcn_readfirstlane(c.tid >> 6); c.G = gridDim.x;
	.amdhsa_kernel _Z10fwd_kernel4Args
		.amdhsa_group_segment_fixed_size 0
		.amdhsa_private_segment_fixed_size 0
		.amdhsa_kernarg_size 384
		.amdhsa_user_sgpr_count 2
		.amdhsa_user_sgpr_dispatch_ptr 0
		.amdhsa_user_sgpr_queue_ptr 0
		.amdhsa_user_sgpr_kernarg_segment_ptr 1
		.amdhsa_user_sgpr_dispatch_id 0
		.amdhsa_user_sgpr_kernarg_preload_length 0
		.amdhsa_user_sgpr_kernarg_preload_offset 0
		.amdhsa_user_sgpr_private_segment_size 0
		.amdhsa_uses_dynamic_stack 0
		.amdhsa_enable_private_segment 0
		.amdhsa_system_sgpr_workgroup_id_x 1
		.amdhsa_system_sgpr_workgroup_id_y 0
		.amdhsa_system_sgpr_workgroup_id_z 0
		.amdhsa_system_sgpr_workgroup_info 0
		.amdhsa_system_vgpr_workitem_id 2
		.amdhsa_next_free_vgpr 255
		.amdhsa_next_free_sgpr 102
		.amdhsa_accum_offset 256
		.amdhsa_reserve_vcc 1
		.amdhsa_float_round_mode_32 0
		.amdhsa_float_round_mode_16_64 0
		.amdhsa_float_denorm_mode_32 3
		.amdhsa_float_denorm_mode_16_64 3
		.amdhsa_dx10_clamp 1
		.amdhsa_ieee_mode 1
		.amdhsa_fp16_overflow 0
		.amdhsa_tg_split 0
		.amdhsa_exception_fp_ieee_invalid_op 0
		.amdhsa_exception_fp_denorm_src 0
		.amdhsa_exception_fp_ieee_div_zero 0
		.amdhsa_exception_fp_ieee_overflow 0
		.amdhsa_exception_fp_ieee_underflow 0
		.amdhsa_exception_fp_ieee_inexact 0
		.amdhsa_exception_int_div_zero 0
	.end_amdhsa_kernel

; #define LAS __attribute__((address_space(3)))
; __global__ void __launch_bounds__(512, 2) fwd_kernel(Args args) {
;     extern __shared__ __attribute__((aligned(16))) unsigned char lds_raw[];
;     LAS unsigned char* lds = (LAS unsigned char*)lds_raw;
;     Ctx c;
;     c.x = args.in[0]; c.meta_tokens = args.in[1]; c.pre_norm = args.in[2]; c.post_norm = args.in[3]; c.attn_w_in = args.in[4]; c.attn_q_norm = args.in[5]; c.attn_k_norm = args.in[6];
;     c.attn_w_out = args.in[7]; c.gla_w_in = args.in[8]; c.gla_gk_up = args.in[9]; c.gla_gk_bias = args.in[10]; c.gla_o_norm = args.in[11]; c.gla_w_out = args.in[12];
;     c.out = args.out; c.ws = args.ws;
;     c.tid = threadIdx.x; c.lane = c.tid & 63; c.wave = __builtin_amdgcn_readfirstlane(c.tid >> 6); c.G = gridDim.x;
amdhsa.kernels:
  - .agpr_count:     0
    .args:
      - .offset:         0
        .size:           128
        .value_kind:     by_value
      - .offset:         128
        .size:           4
        .value_kind:     hidden_block_count_x
      - .offset:         132
        .size:           4
        .value_kind:     hidden_block_count_y
      - .offset:         136
        .size:           4
        .value_kind:     hidden_block_count_z
      - .offset:         140
        .size:           2
        .value_kind:     hidden_group_size_x
      - .offset:         142
        .size:           2
        .value_kind:     hidden_group_size_y
      - .offset:         144
        .size:           2
        .value_kind:     hidden_group_size_z
      - .offset:         146
        .size:           2
        .value_kind:     hidden_remainder_x
      - .offset:         148
        .size:           2
        .value_kind:     hidden_remainder_y
      - .offset:         150
        .size:           2
        .value_kind:     hidden_remainder_z
      - .offset:         168
        .size:           8
        .value_kind:     hidden_global_offset_x
      - .offset:         176
        .size:           8
        .value_kind:     hidden_global_offset_y
      - .offset:         184
        .size:           8
        .value_kind:     hidden_global_offset_z
      - .offset:         192
        .size:           2
        .value_kind:     hidden_grid_dims
      - .offset:         216
        .size:           8
        .value_kind:     hidden_multigrid_sync_arg
      - .offset:         248
        .size:           4
        .value_kind:     hidden_dynamic_lds_size
    .group_segment_fixed_size: 0
    .kernarg_segment_align: 8
    .kernarg_segment_size: 384
    .language:       OpenCL C
    .language_version:
      - 2
      - 0
    .max_flat_workgroup_size: 512
    .name:           _Z10fwd_kernel4Args
    .private_segment_fixed_size: 0
    .sgpr_count:     108
    .sgpr_spill_count: 56
    .symbol:         _Z10fwd_kernel4Args.kd
    .uniform_work_group_size: 1
    .uses_dynamic_stack: false
    .vgpr_count:     255
    .vgpr_spill_count: 0
    .wavefront_size: 64
